# P5 scan: the 32 steps of a half run as two 16-step streams packed in v_pk_fma_f32 (U rows permuted so a register pair holds steps t and t+16), joined by one complex FMA with Abar^16; swaps interleaved
# baseline (speedup 1.0000x reference)
; __device__ __forceinline__ unsigned cvt_pk_bf16(float lo, float hi) { unsigned r; asm volatile("v_cvt_pk_bf16_f32 %0, %1, %2" : "=v"(r) : "v"(lo), "v"(hi)); return r; }
; __device__ __forceinline__ float bflo(unsigned w) { return __uint_as_float(w << 16); }
; __device__ __forceinline__ float bfhi(unsigned w) { return __uint_as_float(w & 0xffff0000u); }
; #define LAS __attribute__((address_space(3)))
; __device__ __forceinline__ void ssm_load_bfrag(Frame& F, int g, int lane, bf16x8 (&bf)[8]) {
;     const int q = lane >> 4, hs = (q & 1) * 8; const bool lo = q >= 2;
; #pragma unroll
;     for (int cb = 0; cb < 8; ++cb) { const int col = 16 * cb + (lane & 15), p = col & 63, im = col >> 6;
;         const float* src = (const float*)(F.ws + WS_BB) + (size_t)(g * NST + p) * 32 + im * 16 + hs;
;         const f32x4 x0 = *(const f32x4*)src, x1 = *(const f32x4*)(src + 4);
;         float v[8] = {x0.x, x0.y, x0.z, x0.w, x1.x, x1.y, x1.z, x1.w};
;         unsigned w[4];
; #pragma unroll
;         for (int j = 0; j < 4; ++j) { const unsigned hi = cvt_pk_bf16(v[2 * j], v[2 * j + 1]);
;             const unsigned l2 = cvt_pk_bf16(v[2 * j] - bflo(hi), v[2 * j + 1] - bfhi(hi)); w[j] = lo ? l2 : hi; }
;         v4u ww = (v4u){w[0], w[1], w[2], w[3]}; bf[cb] = __builtin_bit_cast(bf16x8, ww); }
; }
; __device__ __forceinline__ void p5_phase(Frame& F) {
;     LAS float* bubuf = (LAS float*)(F.lds + RING_OFF + F.wave * SSM_LDS_W);
;     const bf16* U = (const bf16*)(F.ws + WS_U);
;     const int g = F.gw & (NGRP - 1);
;     bf16x8 bf[8]; ssm_load_bfrag(F, g, F.lane, bf);
;     const f32x2 ab = ((const f32x2*)(F.ws + WS_ABAR))[g * NST + F.lane];
;     bf16x8 nfr[4];
;     { const int bc = F.gw >> 7, r0 = (bc / NCH) * SEQ + (bc % NCH) * TCH;
; #pragma unroll
;       for (int sub = 0; sub < 4; ++sub) nfr[sub] = ssm_load_afrag(U, r0 + 16 * sub, g, F.lane); }
.LBB0_684:
	s_cmp_lt_i32 s8, 6
	s_cselect_b64 s[0:1], -1, 0
	s_cmp_gt_i32 s9, 5
	s_cselect_b64 s[2:3], -1, 0
	s_and_b64 s[0:1], s[0:1], s[2:3]
	s_andn2_b64 vcc, exec, s[0:1]
	v_lshlrev_b32_e32 v1, 7, v0
	s_cbranch_vccnz .LBB0_783
	s_waitcnt vmcnt(0)
	s_and_b32 s56, s88, 0x7f
	v_and_b32_e32 v177, 31, v198
	v_lshrrev_b32_e32 v2, 5, v198
	v_lshlrev_b32_e32 v3, 7, v177
	v_lshl_or_b32 v3, v2, 5, v3
	s_lshl_b32 s57, s56, 13
	s_add_u32 s50, s96, 0x120000
	s_addc_u32 s51, s97, 0
	s_add_u32 s50, s50, s57
	s_addc_u32 s51, s51, 0
	s_add_u32 s52, s50, 0x1000
	s_addc_u32 s53, s51, 0
	global_load_dwordx4 v[16:19], v3, s[50:51]
	global_load_dwordx4 v[20:23], v3, s[50:51] offset:16
	global_load_dwordx4 v[24:27], v3, s[52:53]
	global_load_dwordx4 v[28:31], v3, s[52:53] offset:16
	global_load_dwordx4 v[32:35], v3, s[50:51] offset:64
	global_load_dwordx4 v[36:39], v3, s[50:51] offset:80
	global_load_dwordx4 v[40:43], v3, s[52:53] offset:64
	global_load_dwordx4 v[44:47], v3, s[52:53] offset:80
	v_lshlrev_b32_e32 v7, 3, v198
	v_lshl_or_b32 v4, s56, 9, v7
	s_add_u32 s58, s96, 0x100000
	s_addc_u32 s59, s97, 0
	global_load_dwordx2 v[8:9], v4, s[58:59]
	v_lshrrev_b32_e32 v5, 1, v177
	v_and_b32_e32 v6, 1, v177
	v_lshl_or_b32 v5, v6, 4, v5
	v_lshlrev_b32_e32 v5, 12, v5
	v_lshl_or_b32 v5, v2, 4, v5
	v_add_u32_e32 v6, 0x20000, v5
	s_lshr_b32 s54, s88, 7
	s_lshl_b32 s54, s54, 18
	s_lshl_b32 s60, s56, 5
	s_add_u32 s54, s54, s60
	s_add_u32 s54, s54, 0x39600000
	s_add_u32 s54, s96, s54
	s_addc_u32 s55, s97, 0
	s_lshl_b32 s48, s88, 9
	s_add_u32 s48, s48, 0x400000
	s_add_u32 s48, s96, s48
	s_addc_u32 s49, s97, 0
	global_load_dwordx4 v[80:83], v5, s[54:55]
	global_load_dwordx4 v[84:87], v6, s[54:55]
	s_add_u32 s54, s54, 0x400000
	s_addc_u32 s55, s55, 0
	global_load_dwordx4 v[88:91], v5, s[54:55]
	global_load_dwordx4 v[92:95], v6, s[54:55]
	s_add_u32 s54, s54, 0x400000
	s_addc_u32 s55, s55, 0
	global_load_dwordx4 v[96:99], v5, s[54:55]
	global_load_dwordx4 v[100:103], v6, s[54:55]
	s_add_u32 s54, s54, 0x400000
	s_addc_u32 s55, s55, 0
	global_load_dwordx4 v[104:107], v5, s[54:55]
	global_load_dwordx4 v[108:111], v6, s[54:55]
	s_add_u32 s54, s54, 0x400000
	s_addc_u32 s55, s55, 0
	s_waitcnt vmcnt(15)
	v_cvt_pk_bf16_f32 v48, v16, v17
	s_nop 0
	v_lshlrev_b32_e32 v14, 16, v48
	v_and_b32_e32 v15, 0xffff0000, v48
	v_sub_f32_e32 v14, v16, v14
	v_sub_f32_e32 v15, v17, v15
	v_cvt_pk_bf16_f32 v64, v14, v15
	v_cvt_pk_bf16_f32 v49, v18, v19
	s_nop 0
	v_lshlrev_b32_e32 v14, 16, v49
	v_and_b32_e32 v15, 0xffff0000, v49
	v_sub_f32_e32 v14, v18, v14
	v_sub_f32_e32 v15, v19, v15
	v_cvt_pk_bf16_f32 v65, v14, v15
	v_cvt_pk_bf16_f32 v50, v20, v21
	s_nop 0
	v_lshlrev_b32_e32 v14, 16, v50
	v_and_b32_e32 v15, 0xffff0000, v50
	v_sub_f32_e32 v14, v20, v14
	v_sub_f32_e32 v15, v21, v15
	v_cvt_pk_bf16_f32 v66, v14, v15
	v_cvt_pk_bf16_f32 v51, v22, v23
	s_nop 0
	v_lshlrev_b32_e32 v14, 16, v51
	v_and_b32_e32 v15, 0xffff0000, v51
	v_sub_f32_e32 v14, v22, v14
	v_sub_f32_e32 v15, v23, v15
	v_cvt_pk_bf16_f32 v67, v14, v15
	s_waitcnt vmcnt(13)
	v_cvt_pk_bf16_f32 v52, v24, v25
	s_nop 0
	v_lshlrev_b32_e32 v14, 16, v52
	v_and_b32_e32 v15, 0xffff0000, v52
	v_sub_f32_e32 v14, v24, v14
	v_sub_f32_e32 v15, v25, v15
	v_cvt_pk_bf16_f32 v68, v14, v15
	v_cvt_pk_bf16_f32 v53, v26, v27
	s_nop 0
	v_lshlrev_b32_e32 v14, 16, v53
	v_and_b32_e32 v15, 0xffff0000, v53
	v_sub_f32_e32 v14, v26, v14
	v_sub_f32_e32 v15, v27, v15
	v_cvt_pk_bf16_f32 v69, v14, v15
	v_cvt_pk_bf16_f32 v54, v28, v29
	s_nop 0
	v_lshlrev_b32_e32 v14, 16, v54
	v_and_b32_e32 v15, 0xffff0000, v54
	v_sub_f32_e32 v14, v28, v14
	v_sub_f32_e32 v15, v29, v15
	v_cvt_pk_bf16_f32 v70, v14, v15
	v_cvt_pk_bf16_f32 v55, v30, v31
	s_nop 0
	v_lshlrev_b32_e32 v14, 16, v55
	v_and_b32_e32 v15, 0xffff0000, v55
	v_sub_f32_e32 v14, v30, v14
	v_sub_f32_e32 v15, v31, v15
	v_cvt_pk_bf16_f32 v71, v14, v15
	s_waitcnt vmcnt(11)
	v_cvt_pk_bf16_f32 v56, v32, v33
	s_nop 0
	v_lshlrev_b32_e32 v14, 16, v56
	v_and_b32_e32 v15, 0xffff0000, v56
	v_sub_f32_e32 v14, v32, v14
	v_sub_f32_e32 v15, v33, v15
	v_cvt_pk_bf16_f32 v72, v14, v15
	v_cvt_pk_bf16_f32 v57, v34, v35
	s_nop 0
	v_lshlrev_b32_e32 v14, 16, v57
	v_and_b32_e32 v15, 0xffff0000, v57
	v_sub_f32_e32 v14, v34, v14
	v_sub_f32_e32 v15, v35, v15
	v_cvt_pk_bf16_f32 v73, v14, v15
	v_cvt_pk_bf16_f32 v58, v36, v37
	s_nop 0
	v_lshlrev_b32_e32 v14, 16, v58
	v_and_b32_e32 v15, 0xffff0000, v58
	v_sub_f32_e32 v14, v36, v14
	v_sub_f32_e32 v15, v37, v15
	v_cvt_pk_bf16_f32 v74, v14, v15
	v_cvt_pk_bf16_f32 v59, v38, v39
	s_nop 0
	v_lshlrev_b32_e32 v14, 16, v59
	v_and_b32_e32 v15, 0xffff0000, v59
	v_sub_f32_e32 v14, v38, v14
	v_sub_f32_e32 v15, v39, v15
	v_cvt_pk_bf16_f32 v75, v14, v15
	s_waitcnt vmcnt(9)
	v_cvt_pk_bf16_f32 v60, v40, v41
	s_nop 0
	v_lshlrev_b32_e32 v14, 16, v60
	v_and_b32_e32 v15, 0xffff0000, v60
	v_sub_f32_e32 v14, v40, v14
	v_sub_f32_e32 v15, v41, v15
	v_cvt_pk_bf16_f32 v76, v14, v15
	v_cvt_pk_bf16_f32 v61, v42, v43
	s_nop 0
	v_lshlrev_b32_e32 v14, 16, v61
	v_and_b32_e32 v15, 0xffff0000, v61
	v_sub_f32_e32 v14, v42, v14
	v_sub_f32_e32 v15, v43, v15
	v_cvt_pk_bf16_f32 v77, v14, v15
	v_cvt_pk_bf16_f32 v62, v44, v45
	s_nop 0
	v_lshlrev_b32_e32 v14, 16, v62
	v_and_b32_e32 v15, 0xffff0000, v62
	v_sub_f32_e32 v14, v44, v14
	v_sub_f32_e32 v15, v45, v15
	v_cvt_pk_bf16_f32 v78, v14, v15
	v_cvt_pk_bf16_f32 v63, v46, v47
	s_nop 0
	v_lshlrev_b32_e32 v14, 16, v63
	v_and_b32_e32 v15, 0xffff0000, v63
	v_sub_f32_e32 v14, v46, v14
	v_sub_f32_e32 v15, v47, v15
	v_cvt_pk_bf16_f32 v79, v14, v15
	s_waitcnt vmcnt(8)
; #define LAS __attribute__((address_space(3)))
; #define LDS_WAIT() asm volatile("s_waitcnt lgkmcnt(0)" ::: "memory")
; #define MFMA_PIN(a, b) do { __builtin_amdgcn_sched_barrier(0); asm volatile("" :: "v"(a), "v"(b)); } while (0)
; #define MFMA_SETTLE() do { __builtin_amdgcn_sched_barrier(0); asm volatile("s_nop 15"); __builtin_amdgcn_sched_barrier(0); } while (0)
; __device__ __forceinline__ void ssm_bu16(const bf16x8 afr, const bf16x8 (&bf)[8], LAS float* bubuf, int lane) {
;     LAS float* wp = bubuf + (4 * (lane >> 4)) * BUP + (lane & 15);
;     f32x4 d[8];
; #pragma unroll
;     for (int cb = 0; cb < 8; ++cb) { d[cb] = __builtin_amdgcn_mfma_f32_16x16x32_bf16(afr, bf[cb], (f32x4){0.f, 0.f, 0.f, 0.f}, 0, 0, 0); MFMA_PIN(afr, bf[cb]); }
;     MFMA_SETTLE();
; __device__ __forceinline__ void p5_phase(Frame& F) {
;     ...
;     for (int it = F.gw; it < NB * NCH * NGRP; it += F.ngw) {
;         bf16x8 afr[4];
; #pragma unroll
;         for (int sub = 0; sub < 4; ++sub) afr[sub] = nfr[sub];
;         if (it + F.ngw < NB * NCH * NGRP) { const int bc = (it + F.ngw) >> 7, r0 = (bc / NCH) * SEQ + (bc % NCH) * TCH;
; #pragma unroll
;             for (int sub = 0; sub < 4; ++sub) nfr[sub] = ssm_load_afrag(U, r0 + 16 * sub, g, F.lane); }
;         float sr = 0.f, si = 0.f;
; #pragma unroll
;         for (int sub = 0; sub < 4; ++sub) {
;             ssm_bu16(afr[sub], bf, bubuf, F.lane);
; #pragma unroll
;             for (int tt = 0; tt < 16; ++tt) { const float bur = bubuf[tt * BUP + F.lane], bui = bubuf[tt * BUP + 64 + F.lane];
;                 const float nr = fmaf(ab.x, sr, fmaf(-ab.y, si, bur)), ni = fmaf(ab.x, si, fmaf(ab.y, sr, bui)); sr = nr; si = ni; }
;             LDS_WAIT(); asm volatile("" ::: "memory");
;         }
;         ((f32x2*)(F.ws + WS_E))[(size_t)it * NST + F.lane] = (f32x2){sr, si};
	v_xor_b32_e32 v10, 0x80000000, v9
	v_mov_b32_e32 v178, v8
	v_mov_b32_e32 v179, v9
	v_mul_f32_e32 v181, v179, v179
	v_mul_f32_e32 v179, v178, v179
	v_fma_f32 v178, v178, v178, -v181
	v_add_f32_e32 v179, v179, v179
	v_mul_f32_e32 v181, v179, v179
	v_mul_f32_e32 v179, v178, v179
	v_fma_f32 v178, v178, v178, -v181
	v_add_f32_e32 v179, v179, v179
	v_mul_f32_e32 v181, v179, v179
	v_mul_f32_e32 v179, v178, v179
	v_fma_f32 v178, v178, v178, -v181
	v_add_f32_e32 v179, v179, v179
	v_mul_f32_e32 v181, v179, v179
	v_mul_f32_e32 v179, v178, v179
	v_fma_f32 v178, v178, v178, -v181
	v_add_f32_e32 v179, v179, v179
	v_xor_b32_e32 v180, 0x80000000, v179
	s_nop 1
	s_waitcnt vmcnt(7)
	v_mfma_f32_32x32x16_bf16 v[112:127], v[80:83], v[48:51], 0
	v_mfma_f32_32x32x16_bf16 v[128:143], v[80:83], v[52:55], 0
	v_mfma_f32_32x32x16_bf16 v[144:159], v[80:83], v[56:59], 0
	v_mfma_f32_32x32x16_bf16 v[160:175], v[80:83], v[60:63], 0
	v_mfma_f32_32x32x16_bf16 v[112:127], v[80:83], v[64:67], v[112:127]
	v_mfma_f32_32x32x16_bf16 v[128:143], v[80:83], v[68:71], v[128:143]
	v_mfma_f32_32x32x16_bf16 v[144:159], v[80:83], v[72:75], v[144:159]
	v_mfma_f32_32x32x16_bf16 v[160:175], v[80:83], v[76:79], v[160:175]
	v_mov_b32_e32 v12, 0
	v_mov_b32_e32 v13, 0
	v_mov_b32_e32 v14, 0
	v_mov_b32_e32 v15, 0
	s_waitcnt vmcnt(6)
	v_mfma_f32_32x32x16_bf16 v[16:31], v[84:87], v[48:51], 0
	v_mfma_f32_32x32x16_bf16 v[32:47], v[84:87], v[52:55], 0
	v_mfma_f32_32x32x16_bf16 v[200:215], v[84:87], v[56:59], 0
	v_mfma_f32_32x32x16_bf16 v[216:231], v[84:87], v[60:63], 0
	v_mfma_f32_32x32x16_bf16 v[16:31], v[84:87], v[64:67], v[16:31]
	v_mfma_f32_32x32x16_bf16 v[32:47], v[84:87], v[68:71], v[32:47]
	v_mfma_f32_32x32x16_bf16 v[200:215], v[84:87], v[72:75], v[200:215]
	v_mfma_f32_32x32x16_bf16 v[216:231], v[84:87], v[76:79], v[216:231]
	s_nop 15
	s_nop 3
	v_permlane32_swap_b32_e32 v112, v128
	v_permlane32_swap_b32_e32 v144, v160
	v_permlane32_swap_b32_e32 v113, v129
	v_permlane32_swap_b32_e32 v145, v161
	v_permlane32_swap_b32_e32 v114, v130
	v_permlane32_swap_b32_e32 v146, v162
	v_permlane32_swap_b32_e32 v115, v131
	v_permlane32_swap_b32_e32 v147, v163
	v_pk_fma_f32 v[112:113], v[10:11], v[14:15], v[112:113] op_sel_hi:[0,1,1]
	v_pk_fma_f32 v[144:145], v[8:9], v[12:13], v[144:145] op_sel:[1,0,0]
	v_permlane32_swap_b32_e32 v116, v132
	v_pk_fma_f32 v[12:13], v[8:9], v[12:13], v[112:113] op_sel_hi:[0,1,1]
	v_pk_fma_f32 v[14:15], v[8:9], v[14:15], v[144:145] op_sel_hi:[0,1,1]
	v_permlane32_swap_b32_e32 v148, v164
	v_pk_fma_f32 v[114:115], v[10:11], v[14:15], v[114:115] op_sel_hi:[0,1,1]
	v_pk_fma_f32 v[146:147], v[8:9], v[12:13], v[146:147] op_sel:[1,0,0]
	v_permlane32_swap_b32_e32 v117, v133
	v_pk_fma_f32 v[12:13], v[8:9], v[12:13], v[114:115] op_sel_hi:[0,1,1]
	v_pk_fma_f32 v[14:15], v[8:9], v[14:15], v[146:147] op_sel_hi:[0,1,1]
	v_permlane32_swap_b32_e32 v149, v165
	v_pk_fma_f32 v[128:129], v[10:11], v[14:15], v[128:129] op_sel_hi:[0,1,1]
	v_pk_fma_f32 v[160:161], v[8:9], v[12:13], v[160:161] op_sel:[1,0,0]
	v_permlane32_swap_b32_e32 v118, v134
	v_pk_fma_f32 v[12:13], v[8:9], v[12:13], v[128:129] op_sel_hi:[0,1,1]
	v_pk_fma_f32 v[14:15], v[8:9], v[14:15], v[160:161] op_sel_hi:[0,1,1]
	v_permlane32_swap_b32_e32 v150, v166
	v_pk_fma_f32 v[130:131], v[10:11], v[14:15], v[130:131] op_sel_hi:[0,1,1]
	v_pk_fma_f32 v[162:163], v[8:9], v[12:13], v[162:163] op_sel:[1,0,0]
	v_permlane32_swap_b32_e32 v119, v135
	v_pk_fma_f32 v[12:13], v[8:9], v[12:13], v[130:131] op_sel_hi:[0,1,1]
	v_pk_fma_f32 v[14:15], v[8:9], v[14:15], v[162:163] op_sel_hi:[0,1,1]
	v_permlane32_swap_b32_e32 v151, v167
	v_pk_fma_f32 v[116:117], v[10:11], v[14:15], v[116:117] op_sel_hi:[0,1,1]
	v_pk_fma_f32 v[148:149], v[8:9], v[12:13], v[148:149] op_sel:[1,0,0]
	v_permlane32_swap_b32_e32 v120, v136
	v_pk_fma_f32 v[12:13], v[8:9], v[12:13], v[116:117] op_sel_hi:[0,1,1]
	v_pk_fma_f32 v[14:15], v[8:9], v[14:15], v[148:149] op_sel_hi:[0,1,1]
	v_permlane32_swap_b32_e32 v152, v168
	v_pk_fma_f32 v[118:119], v[10:11], v[14:15], v[118:119] op_sel_hi:[0,1,1]
	v_pk_fma_f32 v[150:151], v[8:9], v[12:13], v[150:151] op_sel:[1,0,0]
	v_permlane32_swap_b32_e32 v121, v137
	v_pk_fma_f32 v[12:13], v[8:9], v[12:13], v[118:119] op_sel_hi:[0,1,1]
	v_pk_fma_f32 v[14:15], v[8:9], v[14:15], v[150:151] op_sel_hi:[0,1,1]
	v_permlane32_swap_b32_e32 v153, v169
	v_pk_fma_f32 v[132:133], v[10:11], v[14:15], v[132:133] op_sel_hi:[0,1,1]
	v_pk_fma_f32 v[164:165], v[8:9], v[12:13], v[164:165] op_sel:[1,0,0]
	v_permlane32_swap_b32_e32 v122, v138
	v_pk_fma_f32 v[12:13], v[8:9], v[12:13], v[132:133] op_sel_hi:[0,1,1]
	v_pk_fma_f32 v[14:15], v[8:9], v[14:15], v[164:165] op_sel_hi:[0,1,1]
	v_permlane32_swap_b32_e32 v154, v170
	v_pk_fma_f32 v[134:135], v[10:11], v[14:15], v[134:135] op_sel_hi:[0,1,1]
	v_pk_fma_f32 v[166:167], v[8:9], v[12:13], v[166:167] op_sel:[1,0,0]
	v_permlane32_swap_b32_e32 v123, v139
	v_pk_fma_f32 v[12:13], v[8:9], v[12:13], v[134:135] op_sel_hi:[0,1,1]
	v_pk_fma_f32 v[14:15], v[8:9], v[14:15], v[166:167] op_sel_hi:[0,1,1]
	v_permlane32_swap_b32_e32 v155, v171
	v_pk_fma_f32 v[120:121], v[10:11], v[14:15], v[120:121] op_sel_hi:[0,1,1]
	v_pk_fma_f32 v[152:153], v[8:9], v[12:13], v[152:153] op_sel:[1,0,0]
	v_permlane32_swap_b32_e32 v124, v140
	v_pk_fma_f32 v[12:13], v[8:9], v[12:13], v[120:121] op_sel_hi:[0,1,1]
	v_pk_fma_f32 v[14:15], v[8:9], v[14:15], v[152:153] op_sel_hi:[0,1,1]
	v_permlane32_swap_b32_e32 v156, v172
	v_pk_fma_f32 v[122:123], v[10:11], v[14:15], v[122:123] op_sel_hi:[0,1,1]
	v_pk_fma_f32 v[154:155], v[8:9], v[12:13], v[154:155] op_sel:[1,0,0]
	v_permlane32_swap_b32_e32 v125, v141
	v_pk_fma_f32 v[12:13], v[8:9], v[12:13], v[122:123] op_sel_hi:[0,1,1]
; #define LAS __attribute__((address_space(3)))
; #define LDS_WAIT() asm volatile("s_waitcnt lgkmcnt(0)" ::: "memory")
; #define MFMA_PIN(a, b) do { __builtin_amdgcn_sched_barrier(0); asm volatile("" :: "v"(a), "v"(b)); } while (0)
; #define MFMA_SETTLE() do { __builtin_amdgcn_sched_barrier(0); asm volatile("s_nop 15"); __builtin_amdgcn_sched_barrier(0); } while (0)
; __device__ __forceinline__ void ssm_bu16(const bf16x8 afr, const bf16x8 (&bf)[8], LAS float* bubuf, int lane) {
;     LAS float* wp = bubuf + (4 * (lane >> 4)) * BUP + (lane & 15);
;     f32x4 d[8];
; #pragma unroll
;     for (int cb = 0; cb < 8; ++cb) { d[cb] = __builtin_amdgcn_mfma_f32_16x16x32_bf16(afr, bf[cb], (f32x4){0.f, 0.f, 0.f, 0.f}, 0, 0, 0); MFMA_PIN(afr, bf[cb]); }
;     MFMA_SETTLE();
; __device__ __forceinline__ void p5_phase(Frame& F) {
;     ...
;     for (int it = F.gw; it < NB * NCH * NGRP; it += F.ngw) {
;         bf16x8 afr[4];
; #pragma unroll
;         for (int sub = 0; sub < 4; ++sub) afr[sub] = nfr[sub];
;         if (it + F.ngw < NB * NCH * NGRP) { const int bc = (it + F.ngw) >> 7, r0 = (bc / NCH) * SEQ + (bc % NCH) * TCH;
; #pragma unroll
;             for (int sub = 0; sub < 4; ++sub) nfr[sub] = ssm_load_afrag(U, r0 + 16 * sub, g, F.lane); }
;         float sr = 0.f, si = 0.f;
; #pragma unroll
;         for (int sub = 0; sub < 4; ++sub) {
;             ssm_bu16(afr[sub], bf, bubuf, F.lane);
; #pragma unroll
;             for (int tt = 0; tt < 16; ++tt) { const float bur = bubuf[tt * BUP + F.lane], bui = bubuf[tt * BUP + 64 + F.lane];
;                 const float nr = fmaf(ab.x, sr, fmaf(-ab.y, si, bur)), ni = fmaf(ab.x, si, fmaf(ab.y, sr, bui)); sr = nr; si = ni; }
;             LDS_WAIT(); asm volatile("" ::: "memory");
;         }
;         ((f32x2*)(F.ws + WS_E))[(size_t)it * NST + F.lane] = (f32x2){sr, si};
	v_pk_fma_f32 v[14:15], v[8:9], v[14:15], v[154:155] op_sel_hi:[0,1,1]
	v_permlane32_swap_b32_e32 v157, v173
	v_pk_fma_f32 v[136:137], v[10:11], v[14:15], v[136:137] op_sel_hi:[0,1,1]
	v_pk_fma_f32 v[168:169], v[8:9], v[12:13], v[168:169] op_sel:[1,0,0]
	v_permlane32_swap_b32_e32 v126, v142
	v_pk_fma_f32 v[12:13], v[8:9], v[12:13], v[136:137] op_sel_hi:[0,1,1]
	v_pk_fma_f32 v[14:15], v[8:9], v[14:15], v[168:169] op_sel_hi:[0,1,1]
	v_permlane32_swap_b32_e32 v158, v174
	v_pk_fma_f32 v[138:139], v[10:11], v[14:15], v[138:139] op_sel_hi:[0,1,1]
	v_pk_fma_f32 v[170:171], v[8:9], v[12:13], v[170:171] op_sel:[1,0,0]
	v_permlane32_swap_b32_e32 v127, v143
	v_pk_fma_f32 v[12:13], v[8:9], v[12:13], v[138:139] op_sel_hi:[0,1,1]
	v_pk_fma_f32 v[14:15], v[8:9], v[14:15], v[170:171] op_sel_hi:[0,1,1]
	v_permlane32_swap_b32_e32 v159, v175
	v_pk_fma_f32 v[124:125], v[10:11], v[14:15], v[124:125] op_sel_hi:[0,1,1]
	v_pk_fma_f32 v[156:157], v[8:9], v[12:13], v[156:157] op_sel:[1,0,0]
	s_nop 0
	v_pk_fma_f32 v[12:13], v[8:9], v[12:13], v[124:125] op_sel_hi:[0,1,1]
	v_pk_fma_f32 v[14:15], v[8:9], v[14:15], v[156:157] op_sel_hi:[0,1,1]
	s_nop 0
	v_pk_fma_f32 v[126:127], v[10:11], v[14:15], v[126:127] op_sel_hi:[0,1,1]
	v_pk_fma_f32 v[158:159], v[8:9], v[12:13], v[158:159] op_sel:[1,0,0]
	s_nop 0
	v_pk_fma_f32 v[12:13], v[8:9], v[12:13], v[126:127] op_sel_hi:[0,1,1]
	v_pk_fma_f32 v[14:15], v[8:9], v[14:15], v[158:159] op_sel_hi:[0,1,1]
	s_nop 0
	v_pk_fma_f32 v[140:141], v[10:11], v[14:15], v[140:141] op_sel_hi:[0,1,1]
	v_pk_fma_f32 v[172:173], v[8:9], v[12:13], v[172:173] op_sel:[1,0,0]
	s_nop 0
	v_pk_fma_f32 v[12:13], v[8:9], v[12:13], v[140:141] op_sel_hi:[0,1,1]
	v_pk_fma_f32 v[14:15], v[8:9], v[14:15], v[172:173] op_sel_hi:[0,1,1]
	s_nop 0
	v_pk_fma_f32 v[142:143], v[10:11], v[14:15], v[142:143] op_sel_hi:[0,1,1]
	v_pk_fma_f32 v[174:175], v[8:9], v[12:13], v[174:175] op_sel:[1,0,0]
	s_nop 0
	v_pk_fma_f32 v[12:13], v[8:9], v[12:13], v[142:143] op_sel_hi:[0,1,1]
	v_pk_fma_f32 v[14:15], v[8:9], v[14:15], v[174:175] op_sel_hi:[0,1,1]
	s_nop 0
	s_nop 0
	v_fma_f32 v181, v180, v14, v13
	v_fma_f32 v182, v179, v12, v15
	v_fma_f32 v12, v178, v12, v181
	v_fma_f32 v14, v178, v14, v182
	v_mov_b32_e32 v13, 0
	v_mov_b32_e32 v15, 0
	s_waitcnt vmcnt(5)
	v_mfma_f32_32x32x16_bf16 v[112:127], v[88:91], v[48:51], 0
	v_mfma_f32_32x32x16_bf16 v[128:143], v[88:91], v[52:55], 0
	v_mfma_f32_32x32x16_bf16 v[144:159], v[88:91], v[56:59], 0
	v_mfma_f32_32x32x16_bf16 v[160:175], v[88:91], v[60:63], 0
	v_mfma_f32_32x32x16_bf16 v[112:127], v[88:91], v[64:67], v[112:127]
	v_mfma_f32_32x32x16_bf16 v[128:143], v[88:91], v[68:71], v[128:143]
	v_mfma_f32_32x32x16_bf16 v[144:159], v[88:91], v[72:75], v[144:159]
	v_mfma_f32_32x32x16_bf16 v[160:175], v[88:91], v[76:79], v[160:175]
	s_nop 3
	v_permlane32_swap_b32_e32 v16, v32
	v_permlane32_swap_b32_e32 v200, v216
	v_permlane32_swap_b32_e32 v17, v33
	v_permlane32_swap_b32_e32 v201, v217
	v_permlane32_swap_b32_e32 v18, v34
	v_permlane32_swap_b32_e32 v202, v218
	v_permlane32_swap_b32_e32 v19, v35
	v_permlane32_swap_b32_e32 v203, v219
	v_pk_fma_f32 v[16:17], v[10:11], v[14:15], v[16:17] op_sel_hi:[0,1,1]
	v_pk_fma_f32 v[200:201], v[8:9], v[12:13], v[200:201] op_sel:[1,0,0]
	v_permlane32_swap_b32_e32 v20, v36
	v_pk_fma_f32 v[12:13], v[8:9], v[12:13], v[16:17] op_sel_hi:[0,1,1]
	v_pk_fma_f32 v[14:15], v[8:9], v[14:15], v[200:201] op_sel_hi:[0,1,1]
	v_permlane32_swap_b32_e32 v204, v220
	v_pk_fma_f32 v[18:19], v[10:11], v[14:15], v[18:19] op_sel_hi:[0,1,1]
	v_pk_fma_f32 v[202:203], v[8:9], v[12:13], v[202:203] op_sel:[1,0,0]
	v_permlane32_swap_b32_e32 v21, v37
	v_pk_fma_f32 v[12:13], v[8:9], v[12:13], v[18:19] op_sel_hi:[0,1,1]
	v_pk_fma_f32 v[14:15], v[8:9], v[14:15], v[202:203] op_sel_hi:[0,1,1]
	v_permlane32_swap_b32_e32 v205, v221
	v_pk_fma_f32 v[32:33], v[10:11], v[14:15], v[32:33] op_sel_hi:[0,1,1]
	v_pk_fma_f32 v[216:217], v[8:9], v[12:13], v[216:217] op_sel:[1,0,0]
	v_permlane32_swap_b32_e32 v22, v38
	v_pk_fma_f32 v[12:13], v[8:9], v[12:13], v[32:33] op_sel_hi:[0,1,1]
	v_pk_fma_f32 v[14:15], v[8:9], v[14:15], v[216:217] op_sel_hi:[0,1,1]
	v_permlane32_swap_b32_e32 v206, v222
	v_pk_fma_f32 v[34:35], v[10:11], v[14:15], v[34:35] op_sel_hi:[0,1,1]
	v_pk_fma_f32 v[218:219], v[8:9], v[12:13], v[218:219] op_sel:[1,0,0]
	v_permlane32_swap_b32_e32 v23, v39
	v_pk_fma_f32 v[12:13], v[8:9], v[12:13], v[34:35] op_sel_hi:[0,1,1]
	v_pk_fma_f32 v[14:15], v[8:9], v[14:15], v[218:219] op_sel_hi:[0,1,1]
	v_permlane32_swap_b32_e32 v207, v223
	v_pk_fma_f32 v[20:21], v[10:11], v[14:15], v[20:21] op_sel_hi:[0,1,1]
	v_pk_fma_f32 v[204:205], v[8:9], v[12:13], v[204:205] op_sel:[1,0,0]
	v_permlane32_swap_b32_e32 v24, v40
	v_pk_fma_f32 v[12:13], v[8:9], v[12:13], v[20:21] op_sel_hi:[0,1,1]
	v_pk_fma_f32 v[14:15], v[8:9], v[14:15], v[204:205] op_sel_hi:[0,1,1]
	v_permlane32_swap_b32_e32 v208, v224
	v_pk_fma_f32 v[22:23], v[10:11], v[14:15], v[22:23] op_sel_hi:[0,1,1]
	v_pk_fma_f32 v[206:207], v[8:9], v[12:13], v[206:207] op_sel:[1,0,0]
	v_permlane32_swap_b32_e32 v25, v41
	v_pk_fma_f32 v[12:13], v[8:9], v[12:13], v[22:23] op_sel_hi:[0,1,1]
	v_pk_fma_f32 v[14:15], v[8:9], v[14:15], v[206:207] op_sel_hi:[0,1,1]
	v_permlane32_swap_b32_e32 v209, v225
	v_pk_fma_f32 v[36:37], v[10:11], v[14:15], v[36:37] op_sel_hi:[0,1,1]
	v_pk_fma_f32 v[220:221], v[8:9], v[12:13], v[220:221] op_sel:[1,0,0]
	v_permlane32_swap_b32_e32 v26, v42
	v_pk_fma_f32 v[12:13], v[8:9], v[12:13], v[36:37] op_sel_hi:[0,1,1]
	v_pk_fma_f32 v[14:15], v[8:9], v[14:15], v[220:221] op_sel_hi:[0,1,1]
	v_permlane32_swap_b32_e32 v210, v226
	v_pk_fma_f32 v[38:39], v[10:11], v[14:15], v[38:39] op_sel_hi:[0,1,1]
; #define LAS __attribute__((address_space(3)))
; #define LDS_WAIT() asm volatile("s_waitcnt lgkmcnt(0)" ::: "memory")
; #define MFMA_PIN(a, b) do { __builtin_amdgcn_sched_barrier(0); asm volatile("" :: "v"(a), "v"(b)); } while (0)
; #define MFMA_SETTLE() do { __builtin_amdgcn_sched_barrier(0); asm volatile("s_nop 15"); __builtin_amdgcn_sched_barrier(0); } while (0)
; __device__ __forceinline__ void ssm_bu16(const bf16x8 afr, const bf16x8 (&bf)[8], LAS float* bubuf, int lane) {
;     LAS float* wp = bubuf + (4 * (lane >> 4)) * BUP + (lane & 15);
;     f32x4 d[8];
; #pragma unroll
;     for (int cb = 0; cb < 8; ++cb) { d[cb] = __builtin_amdgcn_mfma_f32_16x16x32_bf16(afr, bf[cb], (f32x4){0.f, 0.f, 0.f, 0.f}, 0, 0, 0); MFMA_PIN(afr, bf[cb]); }
;     MFMA_SETTLE();
; __device__ __forceinline__ void p5_phase(Frame& F) {
;     ...
;     for (int it = F.gw; it < NB * NCH * NGRP; it += F.ngw) {
;         bf16x8 afr[4];
; #pragma unroll
;         for (int sub = 0; sub < 4; ++sub) afr[sub] = nfr[sub];
;         if (it + F.ngw < NB * NCH * NGRP) { const int bc = (it + F.ngw) >> 7, r0 = (bc / NCH) * SEQ + (bc % NCH) * TCH;
; #pragma unroll
;             for (int sub = 0; sub < 4; ++sub) nfr[sub] = ssm_load_afrag(U, r0 + 16 * sub, g, F.lane); }
;         float sr = 0.f, si = 0.f;
; #pragma unroll
;         for (int sub = 0; sub < 4; ++sub) {
;             ssm_bu16(afr[sub], bf, bubuf, F.lane);
; #pragma unroll
;             for (int tt = 0; tt < 16; ++tt) { const float bur = bubuf[tt * BUP + F.lane], bui = bubuf[tt * BUP + 64 + F.lane];
;                 const float nr = fmaf(ab.x, sr, fmaf(-ab.y, si, bur)), ni = fmaf(ab.x, si, fmaf(ab.y, sr, bui)); sr = nr; si = ni; }
;             LDS_WAIT(); asm volatile("" ::: "memory");
;         }
;         ((f32x2*)(F.ws + WS_E))[(size_t)it * NST + F.lane] = (f32x2){sr, si};
	v_pk_fma_f32 v[222:223], v[8:9], v[12:13], v[222:223] op_sel:[1,0,0]
	v_permlane32_swap_b32_e32 v27, v43
	v_pk_fma_f32 v[12:13], v[8:9], v[12:13], v[38:39] op_sel_hi:[0,1,1]
	v_pk_fma_f32 v[14:15], v[8:9], v[14:15], v[222:223] op_sel_hi:[0,1,1]
	v_permlane32_swap_b32_e32 v211, v227
	v_pk_fma_f32 v[24:25], v[10:11], v[14:15], v[24:25] op_sel_hi:[0,1,1]
	v_pk_fma_f32 v[208:209], v[8:9], v[12:13], v[208:209] op_sel:[1,0,0]
	v_permlane32_swap_b32_e32 v28, v44
	v_pk_fma_f32 v[12:13], v[8:9], v[12:13], v[24:25] op_sel_hi:[0,1,1]
	v_pk_fma_f32 v[14:15], v[8:9], v[14:15], v[208:209] op_sel_hi:[0,1,1]
	v_permlane32_swap_b32_e32 v212, v228
	v_pk_fma_f32 v[26:27], v[10:11], v[14:15], v[26:27] op_sel_hi:[0,1,1]
	v_pk_fma_f32 v[210:211], v[8:9], v[12:13], v[210:211] op_sel:[1,0,0]
	v_permlane32_swap_b32_e32 v29, v45
	v_pk_fma_f32 v[12:13], v[8:9], v[12:13], v[26:27] op_sel_hi:[0,1,1]
	v_pk_fma_f32 v[14:15], v[8:9], v[14:15], v[210:211] op_sel_hi:[0,1,1]
	v_permlane32_swap_b32_e32 v213, v229
	v_pk_fma_f32 v[40:41], v[10:11], v[14:15], v[40:41] op_sel_hi:[0,1,1]
	v_pk_fma_f32 v[224:225], v[8:9], v[12:13], v[224:225] op_sel:[1,0,0]
	v_permlane32_swap_b32_e32 v30, v46
	v_pk_fma_f32 v[12:13], v[8:9], v[12:13], v[40:41] op_sel_hi:[0,1,1]
	v_pk_fma_f32 v[14:15], v[8:9], v[14:15], v[224:225] op_sel_hi:[0,1,1]
	v_permlane32_swap_b32_e32 v214, v230
	v_pk_fma_f32 v[42:43], v[10:11], v[14:15], v[42:43] op_sel_hi:[0,1,1]
	v_pk_fma_f32 v[226:227], v[8:9], v[12:13], v[226:227] op_sel:[1,0,0]
	v_permlane32_swap_b32_e32 v31, v47
	v_pk_fma_f32 v[12:13], v[8:9], v[12:13], v[42:43] op_sel_hi:[0,1,1]
	v_pk_fma_f32 v[14:15], v[8:9], v[14:15], v[226:227] op_sel_hi:[0,1,1]
	v_permlane32_swap_b32_e32 v215, v231
	v_pk_fma_f32 v[28:29], v[10:11], v[14:15], v[28:29] op_sel_hi:[0,1,1]
	v_pk_fma_f32 v[212:213], v[8:9], v[12:13], v[212:213] op_sel:[1,0,0]
	s_nop 0
	v_pk_fma_f32 v[12:13], v[8:9], v[12:13], v[28:29] op_sel_hi:[0,1,1]
	v_pk_fma_f32 v[14:15], v[8:9], v[14:15], v[212:213] op_sel_hi:[0,1,1]
	s_nop 0
	v_pk_fma_f32 v[30:31], v[10:11], v[14:15], v[30:31] op_sel_hi:[0,1,1]
	v_pk_fma_f32 v[214:215], v[8:9], v[12:13], v[214:215] op_sel:[1,0,0]
	s_nop 0
	v_pk_fma_f32 v[12:13], v[8:9], v[12:13], v[30:31] op_sel_hi:[0,1,1]
	v_pk_fma_f32 v[14:15], v[8:9], v[14:15], v[214:215] op_sel_hi:[0,1,1]
	s_nop 0
	v_pk_fma_f32 v[44:45], v[10:11], v[14:15], v[44:45] op_sel_hi:[0,1,1]
	v_pk_fma_f32 v[228:229], v[8:9], v[12:13], v[228:229] op_sel:[1,0,0]
	s_nop 0
	v_pk_fma_f32 v[12:13], v[8:9], v[12:13], v[44:45] op_sel_hi:[0,1,1]
	v_pk_fma_f32 v[14:15], v[8:9], v[14:15], v[228:229] op_sel_hi:[0,1,1]
	s_nop 0
	v_pk_fma_f32 v[46:47], v[10:11], v[14:15], v[46:47] op_sel_hi:[0,1,1]
	v_pk_fma_f32 v[230:231], v[8:9], v[12:13], v[230:231] op_sel:[1,0,0]
	s_nop 0
	v_pk_fma_f32 v[12:13], v[8:9], v[12:13], v[46:47] op_sel_hi:[0,1,1]
	v_pk_fma_f32 v[14:15], v[8:9], v[14:15], v[230:231] op_sel_hi:[0,1,1]
	s_nop 0
	s_nop 0
	v_fma_f32 v181, v180, v14, v13
	v_fma_f32 v182, v179, v12, v15
	v_fma_f32 v12, v178, v12, v181
	v_fma_f32 v14, v178, v14, v182
	v_mov_b32_e32 v13, 0
	v_mov_b32_e32 v15, 0
	v_mov_b32_e32 v182, v12
	v_mov_b32_e32 v183, v14
	global_store_dwordx2 v7, v[182:183], s[48:49]
	s_add_u32 s48, s48, 0x100000
	s_addc_u32 s49, s49, 0
	global_load_dwordx4 v[80:83], v5, s[54:55]
	global_load_dwordx4 v[84:87], v6, s[54:55]
	s_add_u32 s54, s54, 0x400000
	s_addc_u32 s55, s55, 0
	v_mov_b32_e32 v12, 0
	v_mov_b32_e32 v13, 0
	v_mov_b32_e32 v14, 0
	v_mov_b32_e32 v15, 0
	s_waitcnt vmcnt(7)
	v_mfma_f32_32x32x16_bf16 v[16:31], v[92:95], v[48:51], 0
	v_mfma_f32_32x32x16_bf16 v[32:47], v[92:95], v[52:55], 0
	v_mfma_f32_32x32x16_bf16 v[200:215], v[92:95], v[56:59], 0
	v_mfma_f32_32x32x16_bf16 v[216:231], v[92:95], v[60:63], 0
	v_mfma_f32_32x32x16_bf16 v[16:31], v[92:95], v[64:67], v[16:31]
	v_mfma_f32_32x32x16_bf16 v[32:47], v[92:95], v[68:71], v[32:47]
	v_mfma_f32_32x32x16_bf16 v[200:215], v[92:95], v[72:75], v[200:215]
	v_mfma_f32_32x32x16_bf16 v[216:231], v[92:95], v[76:79], v[216:231]
	s_nop 3
	v_permlane32_swap_b32_e32 v112, v128
	v_permlane32_swap_b32_e32 v144, v160
	v_permlane32_swap_b32_e32 v113, v129
	v_permlane32_swap_b32_e32 v145, v161
	v_permlane32_swap_b32_e32 v114, v130
	v_permlane32_swap_b32_e32 v146, v162
	v_permlane32_swap_b32_e32 v115, v131
	v_permlane32_swap_b32_e32 v147, v163
	v_pk_fma_f32 v[112:113], v[10:11], v[14:15], v[112:113] op_sel_hi:[0,1,1]
	v_pk_fma_f32 v[144:145], v[8:9], v[12:13], v[144:145] op_sel:[1,0,0]
	v_permlane32_swap_b32_e32 v116, v132
	v_pk_fma_f32 v[12:13], v[8:9], v[12:13], v[112:113] op_sel_hi:[0,1,1]
	v_pk_fma_f32 v[14:15], v[8:9], v[14:15], v[144:145] op_sel_hi:[0,1,1]
	v_permlane32_swap_b32_e32 v148, v164
	v_pk_fma_f32 v[114:115], v[10:11], v[14:15], v[114:115] op_sel_hi:[0,1,1]
	v_pk_fma_f32 v[146:147], v[8:9], v[12:13], v[146:147] op_sel:[1,0,0]
	v_permlane32_swap_b32_e32 v117, v133
	v_pk_fma_f32 v[12:13], v[8:9], v[12:13], v[114:115] op_sel_hi:[0,1,1]
	v_pk_fma_f32 v[14:15], v[8:9], v[14:15], v[146:147] op_sel_hi:[0,1,1]
	v_permlane32_swap_b32_e32 v149, v165
	v_pk_fma_f32 v[128:129], v[10:11], v[14:15], v[128:129] op_sel_hi:[0,1,1]
	v_pk_fma_f32 v[160:161], v[8:9], v[12:13], v[160:161] op_sel:[1,0,0]
	v_permlane32_swap_b32_e32 v118, v134
	v_pk_fma_f32 v[12:13], v[8:9], v[12:13], v[128:129] op_sel_hi:[0,1,1]
	v_pk_fma_f32 v[14:15], v[8:9], v[14:15], v[160:161] op_sel_hi:[0,1,1]
	v_permlane32_swap_b32_e32 v150, v166
	v_pk_fma_f32 v[130:131], v[10:11], v[14:15], v[130:131] op_sel_hi:[0,1,1]
	v_pk_fma_f32 v[162:163], v[8:9], v[12:13], v[162:163] op_sel:[1,0,0]
	v_permlane32_swap_b32_e32 v119, v135
	v_pk_fma_f32 v[12:13], v[8:9], v[12:13], v[130:131] op_sel_hi:[0,1,1]
; #define LAS __attribute__((address_space(3)))
; #define LDS_WAIT() asm volatile("s_waitcnt lgkmcnt(0)" ::: "memory")
; #define MFMA_PIN(a, b) do { __builtin_amdgcn_sched_barrier(0); asm volatile("" :: "v"(a), "v"(b)); } while (0)
; #define MFMA_SETTLE() do { __builtin_amdgcn_sched_barrier(0); asm volatile("s_nop 15"); __builtin_amdgcn_sched_barrier(0); } while (0)
; __device__ __forceinline__ void ssm_bu16(const bf16x8 afr, const bf16x8 (&bf)[8], LAS float* bubuf, int lane) {
;     LAS float* wp = bubuf + (4 * (lane >> 4)) * BUP + (lane & 15);
;     f32x4 d[8];
; #pragma unroll
;     for (int cb = 0; cb < 8; ++cb) { d[cb] = __builtin_amdgcn_mfma_f32_16x16x32_bf16(afr, bf[cb], (f32x4){0.f, 0.f, 0.f, 0.f}, 0, 0, 0); MFMA_PIN(afr, bf[cb]); }
;     MFMA_SETTLE();
; __device__ __forceinline__ void p5_phase(Frame& F) {
;     ...
;     for (int it = F.gw; it < NB * NCH * NGRP; it += F.ngw) {
;         bf16x8 afr[4];
; #pragma unroll
;         for (int sub = 0; sub < 4; ++sub) afr[sub] = nfr[sub];
;         if (it + F.ngw < NB * NCH * NGRP) { const int bc = (it + F.ngw) >> 7, r0 = (bc / NCH) * SEQ + (bc % NCH) * TCH;
; #pragma unroll
;             for (int sub = 0; sub < 4; ++sub) nfr[sub] = ssm_load_afrag(U, r0 + 16 * sub, g, F.lane); }
;         float sr = 0.f, si = 0.f;
; #pragma unroll
;         for (int sub = 0; sub < 4; ++sub) {
;             ssm_bu16(afr[sub], bf, bubuf, F.lane);
; #pragma unroll
;             for (int tt = 0; tt < 16; ++tt) { const float bur = bubuf[tt * BUP + F.lane], bui = bubuf[tt * BUP + 64 + F.lane];
;                 const float nr = fmaf(ab.x, sr, fmaf(-ab.y, si, bur)), ni = fmaf(ab.x, si, fmaf(ab.y, sr, bui)); sr = nr; si = ni; }
;             LDS_WAIT(); asm volatile("" ::: "memory");
;         }
;         ((f32x2*)(F.ws + WS_E))[(size_t)it * NST + F.lane] = (f32x2){sr, si};
	v_pk_fma_f32 v[14:15], v[8:9], v[14:15], v[162:163] op_sel_hi:[0,1,1]
	v_permlane32_swap_b32_e32 v151, v167
	v_pk_fma_f32 v[116:117], v[10:11], v[14:15], v[116:117] op_sel_hi:[0,1,1]
	v_pk_fma_f32 v[148:149], v[8:9], v[12:13], v[148:149] op_sel:[1,0,0]
	v_permlane32_swap_b32_e32 v120, v136
	v_pk_fma_f32 v[12:13], v[8:9], v[12:13], v[116:117] op_sel_hi:[0,1,1]
	v_pk_fma_f32 v[14:15], v[8:9], v[14:15], v[148:149] op_sel_hi:[0,1,1]
	v_permlane32_swap_b32_e32 v152, v168
	v_pk_fma_f32 v[118:119], v[10:11], v[14:15], v[118:119] op_sel_hi:[0,1,1]
	v_pk_fma_f32 v[150:151], v[8:9], v[12:13], v[150:151] op_sel:[1,0,0]
	v_permlane32_swap_b32_e32 v121, v137
	v_pk_fma_f32 v[12:13], v[8:9], v[12:13], v[118:119] op_sel_hi:[0,1,1]
	v_pk_fma_f32 v[14:15], v[8:9], v[14:15], v[150:151] op_sel_hi:[0,1,1]
	v_permlane32_swap_b32_e32 v153, v169
	v_pk_fma_f32 v[132:133], v[10:11], v[14:15], v[132:133] op_sel_hi:[0,1,1]
	v_pk_fma_f32 v[164:165], v[8:9], v[12:13], v[164:165] op_sel:[1,0,0]
	v_permlane32_swap_b32_e32 v122, v138
	v_pk_fma_f32 v[12:13], v[8:9], v[12:13], v[132:133] op_sel_hi:[0,1,1]
	v_pk_fma_f32 v[14:15], v[8:9], v[14:15], v[164:165] op_sel_hi:[0,1,1]
	v_permlane32_swap_b32_e32 v154, v170
	v_pk_fma_f32 v[134:135], v[10:11], v[14:15], v[134:135] op_sel_hi:[0,1,1]
	v_pk_fma_f32 v[166:167], v[8:9], v[12:13], v[166:167] op_sel:[1,0,0]
	v_permlane32_swap_b32_e32 v123, v139
	v_pk_fma_f32 v[12:13], v[8:9], v[12:13], v[134:135] op_sel_hi:[0,1,1]
	v_pk_fma_f32 v[14:15], v[8:9], v[14:15], v[166:167] op_sel_hi:[0,1,1]
	v_permlane32_swap_b32_e32 v155, v171
	v_pk_fma_f32 v[120:121], v[10:11], v[14:15], v[120:121] op_sel_hi:[0,1,1]
	v_pk_fma_f32 v[152:153], v[8:9], v[12:13], v[152:153] op_sel:[1,0,0]
	v_permlane32_swap_b32_e32 v124, v140
	v_pk_fma_f32 v[12:13], v[8:9], v[12:13], v[120:121] op_sel_hi:[0,1,1]
	v_pk_fma_f32 v[14:15], v[8:9], v[14:15], v[152:153] op_sel_hi:[0,1,1]
	v_permlane32_swap_b32_e32 v156, v172
	v_pk_fma_f32 v[122:123], v[10:11], v[14:15], v[122:123] op_sel_hi:[0,1,1]
	v_pk_fma_f32 v[154:155], v[8:9], v[12:13], v[154:155] op_sel:[1,0,0]
	v_permlane32_swap_b32_e32 v125, v141
	v_pk_fma_f32 v[12:13], v[8:9], v[12:13], v[122:123] op_sel_hi:[0,1,1]
	v_pk_fma_f32 v[14:15], v[8:9], v[14:15], v[154:155] op_sel_hi:[0,1,1]
	v_permlane32_swap_b32_e32 v157, v173
	v_pk_fma_f32 v[136:137], v[10:11], v[14:15], v[136:137] op_sel_hi:[0,1,1]
	v_pk_fma_f32 v[168:169], v[8:9], v[12:13], v[168:169] op_sel:[1,0,0]
	v_permlane32_swap_b32_e32 v126, v142
	v_pk_fma_f32 v[12:13], v[8:9], v[12:13], v[136:137] op_sel_hi:[0,1,1]
	v_pk_fma_f32 v[14:15], v[8:9], v[14:15], v[168:169] op_sel_hi:[0,1,1]
	v_permlane32_swap_b32_e32 v158, v174
	v_pk_fma_f32 v[138:139], v[10:11], v[14:15], v[138:139] op_sel_hi:[0,1,1]
	v_pk_fma_f32 v[170:171], v[8:9], v[12:13], v[170:171] op_sel:[1,0,0]
	v_permlane32_swap_b32_e32 v127, v143
	v_pk_fma_f32 v[12:13], v[8:9], v[12:13], v[138:139] op_sel_hi:[0,1,1]
	v_pk_fma_f32 v[14:15], v[8:9], v[14:15], v[170:171] op_sel_hi:[0,1,1]
	v_permlane32_swap_b32_e32 v159, v175
	v_pk_fma_f32 v[124:125], v[10:11], v[14:15], v[124:125] op_sel_hi:[0,1,1]
	v_pk_fma_f32 v[156:157], v[8:9], v[12:13], v[156:157] op_sel:[1,0,0]
	s_nop 0
	v_pk_fma_f32 v[12:13], v[8:9], v[12:13], v[124:125] op_sel_hi:[0,1,1]
	v_pk_fma_f32 v[14:15], v[8:9], v[14:15], v[156:157] op_sel_hi:[0,1,1]
	s_nop 0
	v_pk_fma_f32 v[126:127], v[10:11], v[14:15], v[126:127] op_sel_hi:[0,1,1]
	v_pk_fma_f32 v[158:159], v[8:9], v[12:13], v[158:159] op_sel:[1,0,0]
	s_nop 0
	v_pk_fma_f32 v[12:13], v[8:9], v[12:13], v[126:127] op_sel_hi:[0,1,1]
	v_pk_fma_f32 v[14:15], v[8:9], v[14:15], v[158:159] op_sel_hi:[0,1,1]
	s_nop 0
	v_pk_fma_f32 v[140:141], v[10:11], v[14:15], v[140:141] op_sel_hi:[0,1,1]
	v_pk_fma_f32 v[172:173], v[8:9], v[12:13], v[172:173] op_sel:[1,0,0]
	s_nop 0
	v_pk_fma_f32 v[12:13], v[8:9], v[12:13], v[140:141] op_sel_hi:[0,1,1]
	v_pk_fma_f32 v[14:15], v[8:9], v[14:15], v[172:173] op_sel_hi:[0,1,1]
	s_nop 0
	v_pk_fma_f32 v[142:143], v[10:11], v[14:15], v[142:143] op_sel_hi:[0,1,1]
	v_pk_fma_f32 v[174:175], v[8:9], v[12:13], v[174:175] op_sel:[1,0,0]
	s_nop 0
	v_pk_fma_f32 v[12:13], v[8:9], v[12:13], v[142:143] op_sel_hi:[0,1,1]
	v_pk_fma_f32 v[14:15], v[8:9], v[14:15], v[174:175] op_sel_hi:[0,1,1]
	s_nop 0
	s_nop 0
	v_fma_f32 v181, v180, v14, v13
	v_fma_f32 v182, v179, v12, v15
	v_fma_f32 v12, v178, v12, v181
	v_fma_f32 v14, v178, v14, v182
	v_mov_b32_e32 v13, 0
	v_mov_b32_e32 v15, 0
	s_waitcnt vmcnt(6)
; #define LAS __attribute__((address_space(3)))
; #define LDS_WAIT() asm volatile("s_waitcnt lgkmcnt(0)" ::: "memory")
; #define MFMA_PIN(a, b) do { __builtin_amdgcn_sched_barrier(0); asm volatile("" :: "v"(a), "v"(b)); } while (0)
; #define MFMA_SETTLE() do { __builtin_amdgcn_sched_barrier(0); asm volatile("s_nop 15"); __builtin_amdgcn_sched_barrier(0); } while (0)
; __device__ __forceinline__ void ssm_bu16(const bf16x8 afr, const bf16x8 (&bf)[8], LAS float* bubuf, int lane) {
;     LAS float* wp = bubuf + (4 * (lane >> 4)) * BUP + (lane & 15);
;     f32x4 d[8];
; #pragma unroll
;     for (int cb = 0; cb < 8; ++cb) { d[cb] = __builtin_amdgcn_mfma_f32_16x16x32_bf16(afr, bf[cb], (f32x4){0.f, 0.f, 0.f, 0.f}, 0, 0, 0); MFMA_PIN(afr, bf[cb]); }
;     MFMA_SETTLE();
; __device__ __forceinline__ void p5_phase(Frame& F) {
;     ...
;     for (int it = F.gw; it < NB * NCH * NGRP; it += F.ngw) {
;         bf16x8 afr[4];
; #pragma unroll
;         for (int sub = 0; sub < 4; ++sub) afr[sub] = nfr[sub];
;         if (it + F.ngw < NB * NCH * NGRP) { const int bc = (it + F.ngw) >> 7, r0 = (bc / NCH) * SEQ + (bc % NCH) * TCH;
; #pragma unroll
;             for (int sub = 0; sub < 4; ++sub) nfr[sub] = ssm_load_afrag(U, r0 + 16 * sub, g, F.lane); }
;         float sr = 0.f, si = 0.f;
; #pragma unroll
;         for (int sub = 0; sub < 4; ++sub) {
;             ssm_bu16(afr[sub], bf, bubuf, F.lane);
; #pragma unroll
;             for (int tt = 0; tt < 16; ++tt) { const float bur = bubuf[tt * BUP + F.lane], bui = bubuf[tt * BUP + 64 + F.lane];
;                 const float nr = fmaf(ab.x, sr, fmaf(-ab.y, si, bur)), ni = fmaf(ab.x, si, fmaf(ab.y, sr, bui)); sr = nr; si = ni; }
;             LDS_WAIT(); asm volatile("" ::: "memory");
;         }
;         ((f32x2*)(F.ws + WS_E))[(size_t)it * NST + F.lane] = (f32x2){sr, si};
	v_mfma_f32_32x32x16_bf16 v[112:127], v[96:99], v[48:51], 0
	v_mfma_f32_32x32x16_bf16 v[128:143], v[96:99], v[52:55], 0
	v_mfma_f32_32x32x16_bf16 v[144:159], v[96:99], v[56:59], 0
	v_mfma_f32_32x32x16_bf16 v[160:175], v[96:99], v[60:63], 0
	v_mfma_f32_32x32x16_bf16 v[112:127], v[96:99], v[64:67], v[112:127]
	v_mfma_f32_32x32x16_bf16 v[128:143], v[96:99], v[68:71], v[128:143]
	v_mfma_f32_32x32x16_bf16 v[144:159], v[96:99], v[72:75], v[144:159]
	v_mfma_f32_32x32x16_bf16 v[160:175], v[96:99], v[76:79], v[160:175]
	s_nop 3
	v_permlane32_swap_b32_e32 v16, v32
	v_permlane32_swap_b32_e32 v200, v216
	v_permlane32_swap_b32_e32 v17, v33
	v_permlane32_swap_b32_e32 v201, v217
	v_permlane32_swap_b32_e32 v18, v34
	v_permlane32_swap_b32_e32 v202, v218
	v_permlane32_swap_b32_e32 v19, v35
	v_permlane32_swap_b32_e32 v203, v219
	v_pk_fma_f32 v[16:17], v[10:11], v[14:15], v[16:17] op_sel_hi:[0,1,1]
	v_pk_fma_f32 v[200:201], v[8:9], v[12:13], v[200:201] op_sel:[1,0,0]
	v_permlane32_swap_b32_e32 v20, v36
	v_pk_fma_f32 v[12:13], v[8:9], v[12:13], v[16:17] op_sel_hi:[0,1,1]
	v_pk_fma_f32 v[14:15], v[8:9], v[14:15], v[200:201] op_sel_hi:[0,1,1]
	v_permlane32_swap_b32_e32 v204, v220
	v_pk_fma_f32 v[18:19], v[10:11], v[14:15], v[18:19] op_sel_hi:[0,1,1]
	v_pk_fma_f32 v[202:203], v[8:9], v[12:13], v[202:203] op_sel:[1,0,0]
	v_permlane32_swap_b32_e32 v21, v37
	v_pk_fma_f32 v[12:13], v[8:9], v[12:13], v[18:19] op_sel_hi:[0,1,1]
	v_pk_fma_f32 v[14:15], v[8:9], v[14:15], v[202:203] op_sel_hi:[0,1,1]
	v_permlane32_swap_b32_e32 v205, v221
	v_pk_fma_f32 v[32:33], v[10:11], v[14:15], v[32:33] op_sel_hi:[0,1,1]
	v_pk_fma_f32 v[216:217], v[8:9], v[12:13], v[216:217] op_sel:[1,0,0]
	v_permlane32_swap_b32_e32 v22, v38
	v_pk_fma_f32 v[12:13], v[8:9], v[12:13], v[32:33] op_sel_hi:[0,1,1]
	v_pk_fma_f32 v[14:15], v[8:9], v[14:15], v[216:217] op_sel_hi:[0,1,1]
	v_permlane32_swap_b32_e32 v206, v222
	v_pk_fma_f32 v[34:35], v[10:11], v[14:15], v[34:35] op_sel_hi:[0,1,1]
	v_pk_fma_f32 v[218:219], v[8:9], v[12:13], v[218:219] op_sel:[1,0,0]
	v_permlane32_swap_b32_e32 v23, v39
	v_pk_fma_f32 v[12:13], v[8:9], v[12:13], v[34:35] op_sel_hi:[0,1,1]
	v_pk_fma_f32 v[14:15], v[8:9], v[14:15], v[218:219] op_sel_hi:[0,1,1]
	v_permlane32_swap_b32_e32 v207, v223
	v_pk_fma_f32 v[20:21], v[10:11], v[14:15], v[20:21] op_sel_hi:[0,1,1]
	v_pk_fma_f32 v[204:205], v[8:9], v[12:13], v[204:205] op_sel:[1,0,0]
	v_permlane32_swap_b32_e32 v24, v40
	v_pk_fma_f32 v[12:13], v[8:9], v[12:13], v[20:21] op_sel_hi:[0,1,1]
	v_pk_fma_f32 v[14:15], v[8:9], v[14:15], v[204:205] op_sel_hi:[0,1,1]
	v_permlane32_swap_b32_e32 v208, v224
	v_pk_fma_f32 v[22:23], v[10:11], v[14:15], v[22:23] op_sel_hi:[0,1,1]
	v_pk_fma_f32 v[206:207], v[8:9], v[12:13], v[206:207] op_sel:[1,0,0]
	v_permlane32_swap_b32_e32 v25, v41
	v_pk_fma_f32 v[12:13], v[8:9], v[12:13], v[22:23] op_sel_hi:[0,1,1]
	v_pk_fma_f32 v[14:15], v[8:9], v[14:15], v[206:207] op_sel_hi:[0,1,1]
	v_permlane32_swap_b32_e32 v209, v225
	v_pk_fma_f32 v[36:37], v[10:11], v[14:15], v[36:37] op_sel_hi:[0,1,1]
	v_pk_fma_f32 v[220:221], v[8:9], v[12:13], v[220:221] op_sel:[1,0,0]
	v_permlane32_swap_b32_e32 v26, v42
	v_pk_fma_f32 v[12:13], v[8:9], v[12:13], v[36:37] op_sel_hi:[0,1,1]
	v_pk_fma_f32 v[14:15], v[8:9], v[14:15], v[220:221] op_sel_hi:[0,1,1]
	v_permlane32_swap_b32_e32 v210, v226
	v_pk_fma_f32 v[38:39], v[10:11], v[14:15], v[38:39] op_sel_hi:[0,1,1]
	v_pk_fma_f32 v[222:223], v[8:9], v[12:13], v[222:223] op_sel:[1,0,0]
	v_permlane32_swap_b32_e32 v27, v43
	v_pk_fma_f32 v[12:13], v[8:9], v[12:13], v[38:39] op_sel_hi:[0,1,1]
	v_pk_fma_f32 v[14:15], v[8:9], v[14:15], v[222:223] op_sel_hi:[0,1,1]
	v_permlane32_swap_b32_e32 v211, v227
	v_pk_fma_f32 v[24:25], v[10:11], v[14:15], v[24:25] op_sel_hi:[0,1,1]
	v_pk_fma_f32 v[208:209], v[8:9], v[12:13], v[208:209] op_sel:[1,0,0]
	v_permlane32_swap_b32_e32 v28, v44
	v_pk_fma_f32 v[12:13], v[8:9], v[12:13], v[24:25] op_sel_hi:[0,1,1]
	v_pk_fma_f32 v[14:15], v[8:9], v[14:15], v[208:209] op_sel_hi:[0,1,1]
	v_permlane32_swap_b32_e32 v212, v228
	v_pk_fma_f32 v[26:27], v[10:11], v[14:15], v[26:27] op_sel_hi:[0,1,1]
	v_pk_fma_f32 v[210:211], v[8:9], v[12:13], v[210:211] op_sel:[1,0,0]
	v_permlane32_swap_b32_e32 v29, v45
	v_pk_fma_f32 v[12:13], v[8:9], v[12:13], v[26:27] op_sel_hi:[0,1,1]
	v_pk_fma_f32 v[14:15], v[8:9], v[14:15], v[210:211] op_sel_hi:[0,1,1]
	v_permlane32_swap_b32_e32 v213, v229
	v_pk_fma_f32 v[40:41], v[10:11], v[14:15], v[40:41] op_sel_hi:[0,1,1]
	v_pk_fma_f32 v[224:225], v[8:9], v[12:13], v[224:225] op_sel:[1,0,0]
	v_permlane32_swap_b32_e32 v30, v46
	v_pk_fma_f32 v[12:13], v[8:9], v[12:13], v[40:41] op_sel_hi:[0,1,1]
	v_pk_fma_f32 v[14:15], v[8:9], v[14:15], v[224:225] op_sel_hi:[0,1,1]
	v_permlane32_swap_b32_e32 v214, v230
	v_pk_fma_f32 v[42:43], v[10:11], v[14:15], v[42:43] op_sel_hi:[0,1,1]
	v_pk_fma_f32 v[226:227], v[8:9], v[12:13], v[226:227] op_sel:[1,0,0]
	v_permlane32_swap_b32_e32 v31, v47
	v_pk_fma_f32 v[12:13], v[8:9], v[12:13], v[42:43] op_sel_hi:[0,1,1]
	v_pk_fma_f32 v[14:15], v[8:9], v[14:15], v[226:227] op_sel_hi:[0,1,1]
	v_permlane32_swap_b32_e32 v215, v231
	v_pk_fma_f32 v[28:29], v[10:11], v[14:15], v[28:29] op_sel_hi:[0,1,1]
	v_pk_fma_f32 v[212:213], v[8:9], v[12:13], v[212:213] op_sel:[1,0,0]
	s_nop 0
	v_pk_fma_f32 v[12:13], v[8:9], v[12:13], v[28:29] op_sel_hi:[0,1,1]
	v_pk_fma_f32 v[14:15], v[8:9], v[14:15], v[212:213] op_sel_hi:[0,1,1]
	s_nop 0
	v_pk_fma_f32 v[30:31], v[10:11], v[14:15], v[30:31] op_sel_hi:[0,1,1]
	v_pk_fma_f32 v[214:215], v[8:9], v[12:13], v[214:215] op_sel:[1,0,0]
	s_nop 0
	v_pk_fma_f32 v[12:13], v[8:9], v[12:13], v[30:31] op_sel_hi:[0,1,1]
	v_pk_fma_f32 v[14:15], v[8:9], v[14:15], v[214:215] op_sel_hi:[0,1,1]
	s_nop 0
	v_pk_fma_f32 v[44:45], v[10:11], v[14:15], v[44:45] op_sel_hi:[0,1,1]
	v_pk_fma_f32 v[228:229], v[8:9], v[12:13], v[228:229] op_sel:[1,0,0]
	s_nop 0
	v_pk_fma_f32 v[12:13], v[8:9], v[12:13], v[44:45] op_sel_hi:[0,1,1]
	v_pk_fma_f32 v[14:15], v[8:9], v[14:15], v[228:229] op_sel_hi:[0,1,1]
	s_nop 0
	v_pk_fma_f32 v[46:47], v[10:11], v[14:15], v[46:47] op_sel_hi:[0,1,1]
	v_pk_fma_f32 v[230:231], v[8:9], v[12:13], v[230:231] op_sel:[1,0,0]
	s_nop 0
	v_pk_fma_f32 v[12:13], v[8:9], v[12:13], v[46:47] op_sel_hi:[0,1,1]
	v_pk_fma_f32 v[14:15], v[8:9], v[14:15], v[230:231] op_sel_hi:[0,1,1]
	s_nop 0
	s_nop 0
	v_fma_f32 v181, v180, v14, v13
	v_fma_f32 v182, v179, v12, v15
	v_fma_f32 v12, v178, v12, v181
	v_fma_f32 v14, v178, v14, v182
	v_mov_b32_e32 v13, 0
	v_mov_b32_e32 v15, 0
	v_mov_b32_e32 v182, v12
	v_mov_b32_e32 v183, v14
	global_store_dwordx2 v7, v[182:183], s[48:49]
	s_add_u32 s48, s48, 0x100000
	s_addc_u32 s49, s49, 0
	global_load_dwordx4 v[88:91], v5, s[54:55]
	global_load_dwordx4 v[92:95], v6, s[54:55]
	s_add_u32 s54, s54, 0x400000
	s_addc_u32 s55, s55, 0
	v_mov_b32_e32 v12, 0
	v_mov_b32_e32 v13, 0
	v_mov_b32_e32 v14, 0
	v_mov_b32_e32 v15, 0
	s_waitcnt vmcnt(8)
; #define LAS __attribute__((address_space(3)))
; #define LDS_WAIT() asm volatile("s_waitcnt lgkmcnt(0)" ::: "memory")
; #define MFMA_PIN(a, b) do { __builtin_amdgcn_sched_barrier(0); asm volatile("" :: "v"(a), "v"(b)); } while (0)
; #define MFMA_SETTLE() do { __builtin_amdgcn_sched_barrier(0); asm volatile("s_nop 15"); __builtin_amdgcn_sched_barrier(0); } while (0)
; __device__ __forceinline__ void ssm_bu16(const bf16x8 afr, const bf16x8 (&bf)[8], LAS float* bubuf, int lane) {
;     LAS float* wp = bubuf + (4 * (lane >> 4)) * BUP + (lane & 15);
;     f32x4 d[8];
; #pragma unroll
;     for (int cb = 0; cb < 8; ++cb) { d[cb] = __builtin_amdgcn_mfma_f32_16x16x32_bf16(afr, bf[cb], (f32x4){0.f, 0.f, 0.f, 0.f}, 0, 0, 0); MFMA_PIN(afr, bf[cb]); }
;     MFMA_SETTLE();
; __device__ __forceinline__ void p5_phase(Frame& F) {
;     ...
;     for (int it = F.gw; it < NB * NCH * NGRP; it += F.ngw) {
;         bf16x8 afr[4];
; #pragma unroll
;         for (int sub = 0; sub < 4; ++sub) afr[sub] = nfr[sub];
;         if (it + F.ngw < NB * NCH * NGRP) { const int bc = (it + F.ngw) >> 7, r0 = (bc / NCH) * SEQ + (bc % NCH) * TCH;
; #pragma unroll
;             for (int sub = 0; sub < 4; ++sub) nfr[sub] = ssm_load_afrag(U, r0 + 16 * sub, g, F.lane); }
;         float sr = 0.f, si = 0.f;
; #pragma unroll
;         for (int sub = 0; sub < 4; ++sub) {
;             ssm_bu16(afr[sub], bf, bubuf, F.lane);
; #pragma unroll
;             for (int tt = 0; tt < 16; ++tt) { const float bur = bubuf[tt * BUP + F.lane], bui = bubuf[tt * BUP + 64 + F.lane];
;                 const float nr = fmaf(ab.x, sr, fmaf(-ab.y, si, bur)), ni = fmaf(ab.x, si, fmaf(ab.y, sr, bui)); sr = nr; si = ni; }
;             LDS_WAIT(); asm volatile("" ::: "memory");
;         }
;         ((f32x2*)(F.ws + WS_E))[(size_t)it * NST + F.lane] = (f32x2){sr, si};
	v_mfma_f32_32x32x16_bf16 v[16:31], v[100:103], v[48:51], 0
	v_mfma_f32_32x32x16_bf16 v[32:47], v[100:103], v[52:55], 0
	v_mfma_f32_32x32x16_bf16 v[200:215], v[100:103], v[56:59], 0
	v_mfma_f32_32x32x16_bf16 v[216:231], v[100:103], v[60:63], 0
	v_mfma_f32_32x32x16_bf16 v[16:31], v[100:103], v[64:67], v[16:31]
	v_mfma_f32_32x32x16_bf16 v[32:47], v[100:103], v[68:71], v[32:47]
	v_mfma_f32_32x32x16_bf16 v[200:215], v[100:103], v[72:75], v[200:215]
	v_mfma_f32_32x32x16_bf16 v[216:231], v[100:103], v[76:79], v[216:231]
	s_nop 3
	v_permlane32_swap_b32_e32 v112, v128
	v_permlane32_swap_b32_e32 v144, v160
	v_permlane32_swap_b32_e32 v113, v129
	v_permlane32_swap_b32_e32 v145, v161
	v_permlane32_swap_b32_e32 v114, v130
	v_permlane32_swap_b32_e32 v146, v162
	v_permlane32_swap_b32_e32 v115, v131
	v_permlane32_swap_b32_e32 v147, v163
	v_pk_fma_f32 v[112:113], v[10:11], v[14:15], v[112:113] op_sel_hi:[0,1,1]
	v_pk_fma_f32 v[144:145], v[8:9], v[12:13], v[144:145] op_sel:[1,0,0]
	v_permlane32_swap_b32_e32 v116, v132
	v_pk_fma_f32 v[12:13], v[8:9], v[12:13], v[112:113] op_sel_hi:[0,1,1]
	v_pk_fma_f32 v[14:15], v[8:9], v[14:15], v[144:145] op_sel_hi:[0,1,1]
	v_permlane32_swap_b32_e32 v148, v164
	v_pk_fma_f32 v[114:115], v[10:11], v[14:15], v[114:115] op_sel_hi:[0,1,1]
	v_pk_fma_f32 v[146:147], v[8:9], v[12:13], v[146:147] op_sel:[1,0,0]
	v_permlane32_swap_b32_e32 v117, v133
	v_pk_fma_f32 v[12:13], v[8:9], v[12:13], v[114:115] op_sel_hi:[0,1,1]
	v_pk_fma_f32 v[14:15], v[8:9], v[14:15], v[146:147] op_sel_hi:[0,1,1]
	v_permlane32_swap_b32_e32 v149, v165
	v_pk_fma_f32 v[128:129], v[10:11], v[14:15], v[128:129] op_sel_hi:[0,1,1]
	v_pk_fma_f32 v[160:161], v[8:9], v[12:13], v[160:161] op_sel:[1,0,0]
	v_permlane32_swap_b32_e32 v118, v134
	v_pk_fma_f32 v[12:13], v[8:9], v[12:13], v[128:129] op_sel_hi:[0,1,1]
	v_pk_fma_f32 v[14:15], v[8:9], v[14:15], v[160:161] op_sel_hi:[0,1,1]
	v_permlane32_swap_b32_e32 v150, v166
	v_pk_fma_f32 v[130:131], v[10:11], v[14:15], v[130:131] op_sel_hi:[0,1,1]
	v_pk_fma_f32 v[162:163], v[8:9], v[12:13], v[162:163] op_sel:[1,0,0]
	v_permlane32_swap_b32_e32 v119, v135
	v_pk_fma_f32 v[12:13], v[8:9], v[12:13], v[130:131] op_sel_hi:[0,1,1]
	v_pk_fma_f32 v[14:15], v[8:9], v[14:15], v[162:163] op_sel_hi:[0,1,1]
	v_permlane32_swap_b32_e32 v151, v167
	v_pk_fma_f32 v[116:117], v[10:11], v[14:15], v[116:117] op_sel_hi:[0,1,1]
	v_pk_fma_f32 v[148:149], v[8:9], v[12:13], v[148:149] op_sel:[1,0,0]
	v_permlane32_swap_b32_e32 v120, v136
	v_pk_fma_f32 v[12:13], v[8:9], v[12:13], v[116:117] op_sel_hi:[0,1,1]
	v_pk_fma_f32 v[14:15], v[8:9], v[14:15], v[148:149] op_sel_hi:[0,1,1]
	v_permlane32_swap_b32_e32 v152, v168
	v_pk_fma_f32 v[118:119], v[10:11], v[14:15], v[118:119] op_sel_hi:[0,1,1]
	v_pk_fma_f32 v[150:151], v[8:9], v[12:13], v[150:151] op_sel:[1,0,0]
	v_permlane32_swap_b32_e32 v121, v137
	v_pk_fma_f32 v[12:13], v[8:9], v[12:13], v[118:119] op_sel_hi:[0,1,1]
	v_pk_fma_f32 v[14:15], v[8:9], v[14:15], v[150:151] op_sel_hi:[0,1,1]
	v_permlane32_swap_b32_e32 v153, v169
	v_pk_fma_f32 v[132:133], v[10:11], v[14:15], v[132:133] op_sel_hi:[0,1,1]
	v_pk_fma_f32 v[164:165], v[8:9], v[12:13], v[164:165] op_sel:[1,0,0]
	v_permlane32_swap_b32_e32 v122, v138
	v_pk_fma_f32 v[12:13], v[8:9], v[12:13], v[132:133] op_sel_hi:[0,1,1]
	v_pk_fma_f32 v[14:15], v[8:9], v[14:15], v[164:165] op_sel_hi:[0,1,1]
	v_permlane32_swap_b32_e32 v154, v170
	v_pk_fma_f32 v[134:135], v[10:11], v[14:15], v[134:135] op_sel_hi:[0,1,1]
	v_pk_fma_f32 v[166:167], v[8:9], v[12:13], v[166:167] op_sel:[1,0,0]
	v_permlane32_swap_b32_e32 v123, v139
	v_pk_fma_f32 v[12:13], v[8:9], v[12:13], v[134:135] op_sel_hi:[0,1,1]
	v_pk_fma_f32 v[14:15], v[8:9], v[14:15], v[166:167] op_sel_hi:[0,1,1]
	v_permlane32_swap_b32_e32 v155, v171
	v_pk_fma_f32 v[120:121], v[10:11], v[14:15], v[120:121] op_sel_hi:[0,1,1]
	v_pk_fma_f32 v[152:153], v[8:9], v[12:13], v[152:153] op_sel:[1,0,0]
	v_permlane32_swap_b32_e32 v124, v140
	v_pk_fma_f32 v[12:13], v[8:9], v[12:13], v[120:121] op_sel_hi:[0,1,1]
	v_pk_fma_f32 v[14:15], v[8:9], v[14:15], v[152:153] op_sel_hi:[0,1,1]
	v_permlane32_swap_b32_e32 v156, v172
	v_pk_fma_f32 v[122:123], v[10:11], v[14:15], v[122:123] op_sel_hi:[0,1,1]
	v_pk_fma_f32 v[154:155], v[8:9], v[12:13], v[154:155] op_sel:[1,0,0]
	v_permlane32_swap_b32_e32 v125, v141
	v_pk_fma_f32 v[12:13], v[8:9], v[12:13], v[122:123] op_sel_hi:[0,1,1]
	v_pk_fma_f32 v[14:15], v[8:9], v[14:15], v[154:155] op_sel_hi:[0,1,1]
	v_permlane32_swap_b32_e32 v157, v173
	v_pk_fma_f32 v[136:137], v[10:11], v[14:15], v[136:137] op_sel_hi:[0,1,1]
	v_pk_fma_f32 v[168:169], v[8:9], v[12:13], v[168:169] op_sel:[1,0,0]
	v_permlane32_swap_b32_e32 v126, v142
	v_pk_fma_f32 v[12:13], v[8:9], v[12:13], v[136:137] op_sel_hi:[0,1,1]
	v_pk_fma_f32 v[14:15], v[8:9], v[14:15], v[168:169] op_sel_hi:[0,1,1]
	v_permlane32_swap_b32_e32 v158, v174
	v_pk_fma_f32 v[138:139], v[10:11], v[14:15], v[138:139] op_sel_hi:[0,1,1]
	v_pk_fma_f32 v[170:171], v[8:9], v[12:13], v[170:171] op_sel:[1,0,0]
	v_permlane32_swap_b32_e32 v127, v143
	v_pk_fma_f32 v[12:13], v[8:9], v[12:13], v[138:139] op_sel_hi:[0,1,1]
	v_pk_fma_f32 v[14:15], v[8:9], v[14:15], v[170:171] op_sel_hi:[0,1,1]
	v_permlane32_swap_b32_e32 v159, v175
	v_pk_fma_f32 v[124:125], v[10:11], v[14:15], v[124:125] op_sel_hi:[0,1,1]
	v_pk_fma_f32 v[156:157], v[8:9], v[12:13], v[156:157] op_sel:[1,0,0]
	s_nop 0
	v_pk_fma_f32 v[12:13], v[8:9], v[12:13], v[124:125] op_sel_hi:[0,1,1]
	v_pk_fma_f32 v[14:15], v[8:9], v[14:15], v[156:157] op_sel_hi:[0,1,1]
	s_nop 0
	v_pk_fma_f32 v[126:127], v[10:11], v[14:15], v[126:127] op_sel_hi:[0,1,1]
	v_pk_fma_f32 v[158:159], v[8:9], v[12:13], v[158:159] op_sel:[1,0,0]
	s_nop 0
	v_pk_fma_f32 v[12:13], v[8:9], v[12:13], v[126:127] op_sel_hi:[0,1,1]
	v_pk_fma_f32 v[14:15], v[8:9], v[14:15], v[158:159] op_sel_hi:[0,1,1]
	s_nop 0
	v_pk_fma_f32 v[140:141], v[10:11], v[14:15], v[140:141] op_sel_hi:[0,1,1]
	v_pk_fma_f32 v[172:173], v[8:9], v[12:13], v[172:173] op_sel:[1,0,0]
	s_nop 0
	v_pk_fma_f32 v[12:13], v[8:9], v[12:13], v[140:141] op_sel_hi:[0,1,1]
	v_pk_fma_f32 v[14:15], v[8:9], v[14:15], v[172:173] op_sel_hi:[0,1,1]
	s_nop 0
	v_pk_fma_f32 v[142:143], v[10:11], v[14:15], v[142:143] op_sel_hi:[0,1,1]
	v_pk_fma_f32 v[174:175], v[8:9], v[12:13], v[174:175] op_sel:[1,0,0]
	s_nop 0
	v_pk_fma_f32 v[12:13], v[8:9], v[12:13], v[142:143] op_sel_hi:[0,1,1]
	v_pk_fma_f32 v[14:15], v[8:9], v[14:15], v[174:175] op_sel_hi:[0,1,1]
	s_nop 0
	s_nop 0
	v_fma_f32 v181, v180, v14, v13
	v_fma_f32 v182, v179, v12, v15
	v_fma_f32 v12, v178, v12, v181
	v_fma_f32 v14, v178, v14, v182
	v_mov_b32_e32 v13, 0
	v_mov_b32_e32 v15, 0
	s_waitcnt vmcnt(7)
; #define LAS __attribute__((address_space(3)))
; #define LDS_WAIT() asm volatile("s_waitcnt lgkmcnt(0)" ::: "memory")
; #define MFMA_PIN(a, b) do { __builtin_amdgcn_sched_barrier(0); asm volatile("" :: "v"(a), "v"(b)); } while (0)
; #define MFMA_SETTLE() do { __builtin_amdgcn_sched_barrier(0); asm volatile("s_nop 15"); __builtin_amdgcn_sched_barrier(0); } while (0)
; __device__ __forceinline__ void ssm_bu16(const bf16x8 afr, const bf16x8 (&bf)[8], LAS float* bubuf, int lane) {
;     LAS float* wp = bubuf + (4 * (lane >> 4)) * BUP + (lane & 15);
;     f32x4 d[8];
; #pragma unroll
;     for (int cb = 0; cb < 8; ++cb) { d[cb] = __builtin_amdgcn_mfma_f32_16x16x32_bf16(afr, bf[cb], (f32x4){0.f, 0.f, 0.f, 0.f}, 0, 0, 0); MFMA_PIN(afr, bf[cb]); }
;     MFMA_SETTLE();
; __device__ __forceinline__ void p5_phase(Frame& F) {
;     ...
;     for (int it = F.gw; it < NB * NCH * NGRP; it += F.ngw) {
;         bf16x8 afr[4];
; #pragma unroll
;         for (int sub = 0; sub < 4; ++sub) afr[sub] = nfr[sub];
;         if (it + F.ngw < NB * NCH * NGRP) { const int bc = (it + F.ngw) >> 7, r0 = (bc / NCH) * SEQ + (bc % NCH) * TCH;
; #pragma unroll
;             for (int sub = 0; sub < 4; ++sub) nfr[sub] = ssm_load_afrag(U, r0 + 16 * sub, g, F.lane); }
;         float sr = 0.f, si = 0.f;
; #pragma unroll
;         for (int sub = 0; sub < 4; ++sub) {
;             ssm_bu16(afr[sub], bf, bubuf, F.lane);
; #pragma unroll
;             for (int tt = 0; tt < 16; ++tt) { const float bur = bubuf[tt * BUP + F.lane], bui = bubuf[tt * BUP + 64 + F.lane];
;                 const float nr = fmaf(ab.x, sr, fmaf(-ab.y, si, bur)), ni = fmaf(ab.x, si, fmaf(ab.y, sr, bui)); sr = nr; si = ni; }
;             LDS_WAIT(); asm volatile("" ::: "memory");
;         }
;         ((f32x2*)(F.ws + WS_E))[(size_t)it * NST + F.lane] = (f32x2){sr, si};
	v_mfma_f32_32x32x16_bf16 v[112:127], v[104:107], v[48:51], 0
	v_mfma_f32_32x32x16_bf16 v[128:143], v[104:107], v[52:55], 0
	v_mfma_f32_32x32x16_bf16 v[144:159], v[104:107], v[56:59], 0
	v_mfma_f32_32x32x16_bf16 v[160:175], v[104:107], v[60:63], 0
	v_mfma_f32_32x32x16_bf16 v[112:127], v[104:107], v[64:67], v[112:127]
	v_mfma_f32_32x32x16_bf16 v[128:143], v[104:107], v[68:71], v[128:143]
	v_mfma_f32_32x32x16_bf16 v[144:159], v[104:107], v[72:75], v[144:159]
	v_mfma_f32_32x32x16_bf16 v[160:175], v[104:107], v[76:79], v[160:175]
	s_nop 3
	v_permlane32_swap_b32_e32 v16, v32
	v_permlane32_swap_b32_e32 v200, v216
	v_permlane32_swap_b32_e32 v17, v33
	v_permlane32_swap_b32_e32 v201, v217
	v_permlane32_swap_b32_e32 v18, v34
	v_permlane32_swap_b32_e32 v202, v218
	v_permlane32_swap_b32_e32 v19, v35
	v_permlane32_swap_b32_e32 v203, v219
	v_pk_fma_f32 v[16:17], v[10:11], v[14:15], v[16:17] op_sel_hi:[0,1,1]
	v_pk_fma_f32 v[200:201], v[8:9], v[12:13], v[200:201] op_sel:[1,0,0]
	v_permlane32_swap_b32_e32 v20, v36
	v_pk_fma_f32 v[12:13], v[8:9], v[12:13], v[16:17] op_sel_hi:[0,1,1]
	v_pk_fma_f32 v[14:15], v[8:9], v[14:15], v[200:201] op_sel_hi:[0,1,1]
	v_permlane32_swap_b32_e32 v204, v220
	v_pk_fma_f32 v[18:19], v[10:11], v[14:15], v[18:19] op_sel_hi:[0,1,1]
	v_pk_fma_f32 v[202:203], v[8:9], v[12:13], v[202:203] op_sel:[1,0,0]
	v_permlane32_swap_b32_e32 v21, v37
	v_pk_fma_f32 v[12:13], v[8:9], v[12:13], v[18:19] op_sel_hi:[0,1,1]
	v_pk_fma_f32 v[14:15], v[8:9], v[14:15], v[202:203] op_sel_hi:[0,1,1]
	v_permlane32_swap_b32_e32 v205, v221
	v_pk_fma_f32 v[32:33], v[10:11], v[14:15], v[32:33] op_sel_hi:[0,1,1]
	v_pk_fma_f32 v[216:217], v[8:9], v[12:13], v[216:217] op_sel:[1,0,0]
	v_permlane32_swap_b32_e32 v22, v38
	v_pk_fma_f32 v[12:13], v[8:9], v[12:13], v[32:33] op_sel_hi:[0,1,1]
	v_pk_fma_f32 v[14:15], v[8:9], v[14:15], v[216:217] op_sel_hi:[0,1,1]
	v_permlane32_swap_b32_e32 v206, v222
	v_pk_fma_f32 v[34:35], v[10:11], v[14:15], v[34:35] op_sel_hi:[0,1,1]
	v_pk_fma_f32 v[218:219], v[8:9], v[12:13], v[218:219] op_sel:[1,0,0]
	v_permlane32_swap_b32_e32 v23, v39
	v_pk_fma_f32 v[12:13], v[8:9], v[12:13], v[34:35] op_sel_hi:[0,1,1]
	v_pk_fma_f32 v[14:15], v[8:9], v[14:15], v[218:219] op_sel_hi:[0,1,1]
	v_permlane32_swap_b32_e32 v207, v223
	v_pk_fma_f32 v[20:21], v[10:11], v[14:15], v[20:21] op_sel_hi:[0,1,1]
	v_pk_fma_f32 v[204:205], v[8:9], v[12:13], v[204:205] op_sel:[1,0,0]
	v_permlane32_swap_b32_e32 v24, v40
	v_pk_fma_f32 v[12:13], v[8:9], v[12:13], v[20:21] op_sel_hi:[0,1,1]
	v_pk_fma_f32 v[14:15], v[8:9], v[14:15], v[204:205] op_sel_hi:[0,1,1]
	v_permlane32_swap_b32_e32 v208, v224
	v_pk_fma_f32 v[22:23], v[10:11], v[14:15], v[22:23] op_sel_hi:[0,1,1]
	v_pk_fma_f32 v[206:207], v[8:9], v[12:13], v[206:207] op_sel:[1,0,0]
	v_permlane32_swap_b32_e32 v25, v41
	v_pk_fma_f32 v[12:13], v[8:9], v[12:13], v[22:23] op_sel_hi:[0,1,1]
	v_pk_fma_f32 v[14:15], v[8:9], v[14:15], v[206:207] op_sel_hi:[0,1,1]
	v_permlane32_swap_b32_e32 v209, v225
	v_pk_fma_f32 v[36:37], v[10:11], v[14:15], v[36:37] op_sel_hi:[0,1,1]
	v_pk_fma_f32 v[220:221], v[8:9], v[12:13], v[220:221] op_sel:[1,0,0]
	v_permlane32_swap_b32_e32 v26, v42
	v_pk_fma_f32 v[12:13], v[8:9], v[12:13], v[36:37] op_sel_hi:[0,1,1]
	v_pk_fma_f32 v[14:15], v[8:9], v[14:15], v[220:221] op_sel_hi:[0,1,1]
	v_permlane32_swap_b32_e32 v210, v226
	v_pk_fma_f32 v[38:39], v[10:11], v[14:15], v[38:39] op_sel_hi:[0,1,1]
	v_pk_fma_f32 v[222:223], v[8:9], v[12:13], v[222:223] op_sel:[1,0,0]
	v_permlane32_swap_b32_e32 v27, v43
	v_pk_fma_f32 v[12:13], v[8:9], v[12:13], v[38:39] op_sel_hi:[0,1,1]
	v_pk_fma_f32 v[14:15], v[8:9], v[14:15], v[222:223] op_sel_hi:[0,1,1]
	v_permlane32_swap_b32_e32 v211, v227
	v_pk_fma_f32 v[24:25], v[10:11], v[14:15], v[24:25] op_sel_hi:[0,1,1]
	v_pk_fma_f32 v[208:209], v[8:9], v[12:13], v[208:209] op_sel:[1,0,0]
	v_permlane32_swap_b32_e32 v28, v44
	v_pk_fma_f32 v[12:13], v[8:9], v[12:13], v[24:25] op_sel_hi:[0,1,1]
	v_pk_fma_f32 v[14:15], v[8:9], v[14:15], v[208:209] op_sel_hi:[0,1,1]
	v_permlane32_swap_b32_e32 v212, v228
	v_pk_fma_f32 v[26:27], v[10:11], v[14:15], v[26:27] op_sel_hi:[0,1,1]
	v_pk_fma_f32 v[210:211], v[8:9], v[12:13], v[210:211] op_sel:[1,0,0]
	v_permlane32_swap_b32_e32 v29, v45
	v_pk_fma_f32 v[12:13], v[8:9], v[12:13], v[26:27] op_sel_hi:[0,1,1]
	v_pk_fma_f32 v[14:15], v[8:9], v[14:15], v[210:211] op_sel_hi:[0,1,1]
	v_permlane32_swap_b32_e32 v213, v229
	v_pk_fma_f32 v[40:41], v[10:11], v[14:15], v[40:41] op_sel_hi:[0,1,1]
	v_pk_fma_f32 v[224:225], v[8:9], v[12:13], v[224:225] op_sel:[1,0,0]
	v_permlane32_swap_b32_e32 v30, v46
	v_pk_fma_f32 v[12:13], v[8:9], v[12:13], v[40:41] op_sel_hi:[0,1,1]
	v_pk_fma_f32 v[14:15], v[8:9], v[14:15], v[224:225] op_sel_hi:[0,1,1]
	v_permlane32_swap_b32_e32 v214, v230
	v_pk_fma_f32 v[42:43], v[10:11], v[14:15], v[42:43] op_sel_hi:[0,1,1]
	v_pk_fma_f32 v[226:227], v[8:9], v[12:13], v[226:227] op_sel:[1,0,0]
	v_permlane32_swap_b32_e32 v31, v47
	v_pk_fma_f32 v[12:13], v[8:9], v[12:13], v[42:43] op_sel_hi:[0,1,1]
	v_pk_fma_f32 v[14:15], v[8:9], v[14:15], v[226:227] op_sel_hi:[0,1,1]
	v_permlane32_swap_b32_e32 v215, v231
	v_pk_fma_f32 v[28:29], v[10:11], v[14:15], v[28:29] op_sel_hi:[0,1,1]
	v_pk_fma_f32 v[212:213], v[8:9], v[12:13], v[212:213] op_sel:[1,0,0]
	s_nop 0
	v_pk_fma_f32 v[12:13], v[8:9], v[12:13], v[28:29] op_sel_hi:[0,1,1]
	v_pk_fma_f32 v[14:15], v[8:9], v[14:15], v[212:213] op_sel_hi:[0,1,1]
	s_nop 0
	v_pk_fma_f32 v[30:31], v[10:11], v[14:15], v[30:31] op_sel_hi:[0,1,1]
	v_pk_fma_f32 v[214:215], v[8:9], v[12:13], v[214:215] op_sel:[1,0,0]
	s_nop 0
	v_pk_fma_f32 v[12:13], v[8:9], v[12:13], v[30:31] op_sel_hi:[0,1,1]
	v_pk_fma_f32 v[14:15], v[8:9], v[14:15], v[214:215] op_sel_hi:[0,1,1]
	s_nop 0
	v_pk_fma_f32 v[44:45], v[10:11], v[14:15], v[44:45] op_sel_hi:[0,1,1]
	v_pk_fma_f32 v[228:229], v[8:9], v[12:13], v[228:229] op_sel:[1,0,0]
	s_nop 0
	v_pk_fma_f32 v[12:13], v[8:9], v[12:13], v[44:45] op_sel_hi:[0,1,1]
	v_pk_fma_f32 v[14:15], v[8:9], v[14:15], v[228:229] op_sel_hi:[0,1,1]
	s_nop 0
	v_pk_fma_f32 v[46:47], v[10:11], v[14:15], v[46:47] op_sel_hi:[0,1,1]
	v_pk_fma_f32 v[230:231], v[8:9], v[12:13], v[230:231] op_sel:[1,0,0]
	s_nop 0
	v_pk_fma_f32 v[12:13], v[8:9], v[12:13], v[46:47] op_sel_hi:[0,1,1]
	v_pk_fma_f32 v[14:15], v[8:9], v[14:15], v[230:231] op_sel_hi:[0,1,1]
	s_nop 0
	s_nop 0
	v_fma_f32 v181, v180, v14, v13
	v_fma_f32 v182, v179, v12, v15
	v_fma_f32 v12, v178, v12, v181
	v_fma_f32 v14, v178, v14, v182
	v_mov_b32_e32 v13, 0
	v_mov_b32_e32 v15, 0
	v_mov_b32_e32 v182, v12
	v_mov_b32_e32 v183, v14
	global_store_dwordx2 v7, v[182:183], s[48:49]
	s_add_u32 s48, s48, 0x100000
	s_addc_u32 s49, s49, 0
	global_load_dwordx4 v[96:99], v5, s[54:55]
	global_load_dwordx4 v[100:103], v6, s[54:55]
	s_add_u32 s54, s54, 0x400000
	s_addc_u32 s55, s55, 0
	v_mov_b32_e32 v12, 0
	v_mov_b32_e32 v13, 0
	v_mov_b32_e32 v14, 0
	v_mov_b32_e32 v15, 0
	s_waitcnt vmcnt(9)
; #define LAS __attribute__((address_space(3)))
; #define LDS_WAIT() asm volatile("s_waitcnt lgkmcnt(0)" ::: "memory")
; #define MFMA_PIN(a, b) do { __builtin_amdgcn_sched_barrier(0); asm volatile("" :: "v"(a), "v"(b)); } while (0)
; #define MFMA_SETTLE() do { __builtin_amdgcn_sched_barrier(0); asm volatile("s_nop 15"); __builtin_amdgcn_sched_barrier(0); } while (0)
; __device__ __forceinline__ void ssm_bu16(const bf16x8 afr, const bf16x8 (&bf)[8], LAS float* bubuf, int lane) {
;     LAS float* wp = bubuf + (4 * (lane >> 4)) * BUP + (lane & 15);
;     f32x4 d[8];
; #pragma unroll
;     for (int cb = 0; cb < 8; ++cb) { d[cb] = __builtin_amdgcn_mfma_f32_16x16x32_bf16(afr, bf[cb], (f32x4){0.f, 0.f, 0.f, 0.f}, 0, 0, 0); MFMA_PIN(afr, bf[cb]); }
;     MFMA_SETTLE();
; __device__ __forceinline__ void p5_phase(Frame& F) {
;     ...
;     for (int it = F.gw; it < NB * NCH * NGRP; it += F.ngw) {
;         bf16x8 afr[4];
; #pragma unroll
;         for (int sub = 0; sub < 4; ++sub) afr[sub] = nfr[sub];
;         if (it + F.ngw < NB * NCH * NGRP) { const int bc = (it + F.ngw) >> 7, r0 = (bc / NCH) * SEQ + (bc % NCH) * TCH;
; #pragma unroll
;             for (int sub = 0; sub < 4; ++sub) nfr[sub] = ssm_load_afrag(U, r0 + 16 * sub, g, F.lane); }
;         float sr = 0.f, si = 0.f;
; #pragma unroll
;         for (int sub = 0; sub < 4; ++sub) {
;             ssm_bu16(afr[sub], bf, bubuf, F.lane);
; #pragma unroll
;             for (int tt = 0; tt < 16; ++tt) { const float bur = bubuf[tt * BUP + F.lane], bui = bubuf[tt * BUP + 64 + F.lane];
;                 const float nr = fmaf(ab.x, sr, fmaf(-ab.y, si, bur)), ni = fmaf(ab.x, si, fmaf(ab.y, sr, bui)); sr = nr; si = ni; }
;             LDS_WAIT(); asm volatile("" ::: "memory");
;         }
;         ((f32x2*)(F.ws + WS_E))[(size_t)it * NST + F.lane] = (f32x2){sr, si};
	v_mfma_f32_32x32x16_bf16 v[16:31], v[108:111], v[48:51], 0
	v_mfma_f32_32x32x16_bf16 v[32:47], v[108:111], v[52:55], 0
	v_mfma_f32_32x32x16_bf16 v[200:215], v[108:111], v[56:59], 0
	v_mfma_f32_32x32x16_bf16 v[216:231], v[108:111], v[60:63], 0
	v_mfma_f32_32x32x16_bf16 v[16:31], v[108:111], v[64:67], v[16:31]
	v_mfma_f32_32x32x16_bf16 v[32:47], v[108:111], v[68:71], v[32:47]
	v_mfma_f32_32x32x16_bf16 v[200:215], v[108:111], v[72:75], v[200:215]
	v_mfma_f32_32x32x16_bf16 v[216:231], v[108:111], v[76:79], v[216:231]
	s_nop 3
	v_permlane32_swap_b32_e32 v112, v128
	v_permlane32_swap_b32_e32 v144, v160
	v_permlane32_swap_b32_e32 v113, v129
	v_permlane32_swap_b32_e32 v145, v161
	v_permlane32_swap_b32_e32 v114, v130
	v_permlane32_swap_b32_e32 v146, v162
	v_permlane32_swap_b32_e32 v115, v131
	v_permlane32_swap_b32_e32 v147, v163
	v_pk_fma_f32 v[112:113], v[10:11], v[14:15], v[112:113] op_sel_hi:[0,1,1]
	v_pk_fma_f32 v[144:145], v[8:9], v[12:13], v[144:145] op_sel:[1,0,0]
	v_permlane32_swap_b32_e32 v116, v132
	v_pk_fma_f32 v[12:13], v[8:9], v[12:13], v[112:113] op_sel_hi:[0,1,1]
	v_pk_fma_f32 v[14:15], v[8:9], v[14:15], v[144:145] op_sel_hi:[0,1,1]
	v_permlane32_swap_b32_e32 v148, v164
	v_pk_fma_f32 v[114:115], v[10:11], v[14:15], v[114:115] op_sel_hi:[0,1,1]
	v_pk_fma_f32 v[146:147], v[8:9], v[12:13], v[146:147] op_sel:[1,0,0]
	v_permlane32_swap_b32_e32 v117, v133
	v_pk_fma_f32 v[12:13], v[8:9], v[12:13], v[114:115] op_sel_hi:[0,1,1]
	v_pk_fma_f32 v[14:15], v[8:9], v[14:15], v[146:147] op_sel_hi:[0,1,1]
	v_permlane32_swap_b32_e32 v149, v165
	v_pk_fma_f32 v[128:129], v[10:11], v[14:15], v[128:129] op_sel_hi:[0,1,1]
	v_pk_fma_f32 v[160:161], v[8:9], v[12:13], v[160:161] op_sel:[1,0,0]
	v_permlane32_swap_b32_e32 v118, v134
	v_pk_fma_f32 v[12:13], v[8:9], v[12:13], v[128:129] op_sel_hi:[0,1,1]
	v_pk_fma_f32 v[14:15], v[8:9], v[14:15], v[160:161] op_sel_hi:[0,1,1]
	v_permlane32_swap_b32_e32 v150, v166
	v_pk_fma_f32 v[130:131], v[10:11], v[14:15], v[130:131] op_sel_hi:[0,1,1]
	v_pk_fma_f32 v[162:163], v[8:9], v[12:13], v[162:163] op_sel:[1,0,0]
	v_permlane32_swap_b32_e32 v119, v135
	v_pk_fma_f32 v[12:13], v[8:9], v[12:13], v[130:131] op_sel_hi:[0,1,1]
	v_pk_fma_f32 v[14:15], v[8:9], v[14:15], v[162:163] op_sel_hi:[0,1,1]
	v_permlane32_swap_b32_e32 v151, v167
	v_pk_fma_f32 v[116:117], v[10:11], v[14:15], v[116:117] op_sel_hi:[0,1,1]
	v_pk_fma_f32 v[148:149], v[8:9], v[12:13], v[148:149] op_sel:[1,0,0]
	v_permlane32_swap_b32_e32 v120, v136
	v_pk_fma_f32 v[12:13], v[8:9], v[12:13], v[116:117] op_sel_hi:[0,1,1]
	v_pk_fma_f32 v[14:15], v[8:9], v[14:15], v[148:149] op_sel_hi:[0,1,1]
	v_permlane32_swap_b32_e32 v152, v168
	v_pk_fma_f32 v[118:119], v[10:11], v[14:15], v[118:119] op_sel_hi:[0,1,1]
	v_pk_fma_f32 v[150:151], v[8:9], v[12:13], v[150:151] op_sel:[1,0,0]
	v_permlane32_swap_b32_e32 v121, v137
	v_pk_fma_f32 v[12:13], v[8:9], v[12:13], v[118:119] op_sel_hi:[0,1,1]
	v_pk_fma_f32 v[14:15], v[8:9], v[14:15], v[150:151] op_sel_hi:[0,1,1]
	v_permlane32_swap_b32_e32 v153, v169
	v_pk_fma_f32 v[132:133], v[10:11], v[14:15], v[132:133] op_sel_hi:[0,1,1]
	v_pk_fma_f32 v[164:165], v[8:9], v[12:13], v[164:165] op_sel:[1,0,0]
	v_permlane32_swap_b32_e32 v122, v138
	v_pk_fma_f32 v[12:13], v[8:9], v[12:13], v[132:133] op_sel_hi:[0,1,1]
	v_pk_fma_f32 v[14:15], v[8:9], v[14:15], v[164:165] op_sel_hi:[0,1,1]
	v_permlane32_swap_b32_e32 v154, v170
	v_pk_fma_f32 v[134:135], v[10:11], v[14:15], v[134:135] op_sel_hi:[0,1,1]
	v_pk_fma_f32 v[166:167], v[8:9], v[12:13], v[166:167] op_sel:[1,0,0]
	v_permlane32_swap_b32_e32 v123, v139
	v_pk_fma_f32 v[12:13], v[8:9], v[12:13], v[134:135] op_sel_hi:[0,1,1]
	v_pk_fma_f32 v[14:15], v[8:9], v[14:15], v[166:167] op_sel_hi:[0,1,1]
	v_permlane32_swap_b32_e32 v155, v171
	v_pk_fma_f32 v[120:121], v[10:11], v[14:15], v[120:121] op_sel_hi:[0,1,1]
	v_pk_fma_f32 v[152:153], v[8:9], v[12:13], v[152:153] op_sel:[1,0,0]
	v_permlane32_swap_b32_e32 v124, v140
	v_pk_fma_f32 v[12:13], v[8:9], v[12:13], v[120:121] op_sel_hi:[0,1,1]
	v_pk_fma_f32 v[14:15], v[8:9], v[14:15], v[152:153] op_sel_hi:[0,1,1]
	v_permlane32_swap_b32_e32 v156, v172
	v_pk_fma_f32 v[122:123], v[10:11], v[14:15], v[122:123] op_sel_hi:[0,1,1]
	v_pk_fma_f32 v[154:155], v[8:9], v[12:13], v[154:155] op_sel:[1,0,0]
	v_permlane32_swap_b32_e32 v125, v141
	v_pk_fma_f32 v[12:13], v[8:9], v[12:13], v[122:123] op_sel_hi:[0,1,1]
	v_pk_fma_f32 v[14:15], v[8:9], v[14:15], v[154:155] op_sel_hi:[0,1,1]
	v_permlane32_swap_b32_e32 v157, v173
	v_pk_fma_f32 v[136:137], v[10:11], v[14:15], v[136:137] op_sel_hi:[0,1,1]
	v_pk_fma_f32 v[168:169], v[8:9], v[12:13], v[168:169] op_sel:[1,0,0]
	v_permlane32_swap_b32_e32 v126, v142
	v_pk_fma_f32 v[12:13], v[8:9], v[12:13], v[136:137] op_sel_hi:[0,1,1]
	v_pk_fma_f32 v[14:15], v[8:9], v[14:15], v[168:169] op_sel_hi:[0,1,1]
	v_permlane32_swap_b32_e32 v158, v174
	v_pk_fma_f32 v[138:139], v[10:11], v[14:15], v[138:139] op_sel_hi:[0,1,1]
	v_pk_fma_f32 v[170:171], v[8:9], v[12:13], v[170:171] op_sel:[1,0,0]
	v_permlane32_swap_b32_e32 v127, v143
	v_pk_fma_f32 v[12:13], v[8:9], v[12:13], v[138:139] op_sel_hi:[0,1,1]
	v_pk_fma_f32 v[14:15], v[8:9], v[14:15], v[170:171] op_sel_hi:[0,1,1]
	v_permlane32_swap_b32_e32 v159, v175
	v_pk_fma_f32 v[124:125], v[10:11], v[14:15], v[124:125] op_sel_hi:[0,1,1]
	v_pk_fma_f32 v[156:157], v[8:9], v[12:13], v[156:157] op_sel:[1,0,0]
	s_nop 0
	v_pk_fma_f32 v[12:13], v[8:9], v[12:13], v[124:125] op_sel_hi:[0,1,1]
	v_pk_fma_f32 v[14:15], v[8:9], v[14:15], v[156:157] op_sel_hi:[0,1,1]
	s_nop 0
	v_pk_fma_f32 v[126:127], v[10:11], v[14:15], v[126:127] op_sel_hi:[0,1,1]
	v_pk_fma_f32 v[158:159], v[8:9], v[12:13], v[158:159] op_sel:[1,0,0]
	s_nop 0
	v_pk_fma_f32 v[12:13], v[8:9], v[12:13], v[126:127] op_sel_hi:[0,1,1]
	v_pk_fma_f32 v[14:15], v[8:9], v[14:15], v[158:159] op_sel_hi:[0,1,1]
	s_nop 0
	v_pk_fma_f32 v[140:141], v[10:11], v[14:15], v[140:141] op_sel_hi:[0,1,1]
	v_pk_fma_f32 v[172:173], v[8:9], v[12:13], v[172:173] op_sel:[1,0,0]
	s_nop 0
	v_pk_fma_f32 v[12:13], v[8:9], v[12:13], v[140:141] op_sel_hi:[0,1,1]
	v_pk_fma_f32 v[14:15], v[8:9], v[14:15], v[172:173] op_sel_hi:[0,1,1]
	s_nop 0
	v_pk_fma_f32 v[142:143], v[10:11], v[14:15], v[142:143] op_sel_hi:[0,1,1]
	v_pk_fma_f32 v[174:175], v[8:9], v[12:13], v[174:175] op_sel:[1,0,0]
	s_nop 0
	v_pk_fma_f32 v[12:13], v[8:9], v[12:13], v[142:143] op_sel_hi:[0,1,1]
	v_pk_fma_f32 v[14:15], v[8:9], v[14:15], v[174:175] op_sel_hi:[0,1,1]
	s_nop 0
	s_nop 0
	v_fma_f32 v181, v180, v14, v13
	v_fma_f32 v182, v179, v12, v15
	v_fma_f32 v12, v178, v12, v181
	v_fma_f32 v14, v178, v14, v182
	v_mov_b32_e32 v13, 0
	v_mov_b32_e32 v15, 0
	s_waitcnt vmcnt(7)
; #define LAS __attribute__((address_space(3)))
; #define LDS_WAIT() asm volatile("s_waitcnt lgkmcnt(0)" ::: "memory")
; #define MFMA_PIN(a, b) do { __builtin_amdgcn_sched_barrier(0); asm volatile("" :: "v"(a), "v"(b)); } while (0)
; #define MFMA_SETTLE() do { __builtin_amdgcn_sched_barrier(0); asm volatile("s_nop 15"); __builtin_amdgcn_sched_barrier(0); } while (0)
; __device__ __forceinline__ void ssm_bu16(const bf16x8 afr, const bf16x8 (&bf)[8], LAS float* bubuf, int lane) {
;     LAS float* wp = bubuf + (4 * (lane >> 4)) * BUP + (lane & 15);
;     f32x4 d[8];
; #pragma unroll
;     for (int cb = 0; cb < 8; ++cb) { d[cb] = __builtin_amdgcn_mfma_f32_16x16x32_bf16(afr, bf[cb], (f32x4){0.f, 0.f, 0.f, 0.f}, 0, 0, 0); MFMA_PIN(afr, bf[cb]); }
;     MFMA_SETTLE();
; __device__ __forceinline__ void p5_phase(Frame& F) {
;     ...
;     for (int it = F.gw; it < NB * NCH * NGRP; it += F.ngw) {
;         bf16x8 afr[4];
; #pragma unroll
;         for (int sub = 0; sub < 4; ++sub) afr[sub] = nfr[sub];
;         if (it + F.ngw < NB * NCH * NGRP) { const int bc = (it + F.ngw) >> 7, r0 = (bc / NCH) * SEQ + (bc % NCH) * TCH;
; #pragma unroll
;             for (int sub = 0; sub < 4; ++sub) nfr[sub] = ssm_load_afrag(U, r0 + 16 * sub, g, F.lane); }
;         float sr = 0.f, si = 0.f;
; #pragma unroll
;         for (int sub = 0; sub < 4; ++sub) {
;             ssm_bu16(afr[sub], bf, bubuf, F.lane);
; #pragma unroll
;             for (int tt = 0; tt < 16; ++tt) { const float bur = bubuf[tt * BUP + F.lane], bui = bubuf[tt * BUP + 64 + F.lane];
;                 const float nr = fmaf(ab.x, sr, fmaf(-ab.y, si, bur)), ni = fmaf(ab.x, si, fmaf(ab.y, sr, bui)); sr = nr; si = ni; }
;             LDS_WAIT(); asm volatile("" ::: "memory");
;         }
;         ((f32x2*)(F.ws + WS_E))[(size_t)it * NST + F.lane] = (f32x2){sr, si};
	v_mfma_f32_32x32x16_bf16 v[112:127], v[80:83], v[48:51], 0
	v_mfma_f32_32x32x16_bf16 v[128:143], v[80:83], v[52:55], 0
	v_mfma_f32_32x32x16_bf16 v[144:159], v[80:83], v[56:59], 0
	v_mfma_f32_32x32x16_bf16 v[160:175], v[80:83], v[60:63], 0
	v_mfma_f32_32x32x16_bf16 v[112:127], v[80:83], v[64:67], v[112:127]
	v_mfma_f32_32x32x16_bf16 v[128:143], v[80:83], v[68:71], v[128:143]
	v_mfma_f32_32x32x16_bf16 v[144:159], v[80:83], v[72:75], v[144:159]
	v_mfma_f32_32x32x16_bf16 v[160:175], v[80:83], v[76:79], v[160:175]
	s_nop 3
	v_permlane32_swap_b32_e32 v16, v32
	v_permlane32_swap_b32_e32 v200, v216
	v_permlane32_swap_b32_e32 v17, v33
	v_permlane32_swap_b32_e32 v201, v217
	v_permlane32_swap_b32_e32 v18, v34
	v_permlane32_swap_b32_e32 v202, v218
	v_permlane32_swap_b32_e32 v19, v35
	v_permlane32_swap_b32_e32 v203, v219
	v_pk_fma_f32 v[16:17], v[10:11], v[14:15], v[16:17] op_sel_hi:[0,1,1]
	v_pk_fma_f32 v[200:201], v[8:9], v[12:13], v[200:201] op_sel:[1,0,0]
	v_permlane32_swap_b32_e32 v20, v36
	v_pk_fma_f32 v[12:13], v[8:9], v[12:13], v[16:17] op_sel_hi:[0,1,1]
	v_pk_fma_f32 v[14:15], v[8:9], v[14:15], v[200:201] op_sel_hi:[0,1,1]
	v_permlane32_swap_b32_e32 v204, v220
	v_pk_fma_f32 v[18:19], v[10:11], v[14:15], v[18:19] op_sel_hi:[0,1,1]
	v_pk_fma_f32 v[202:203], v[8:9], v[12:13], v[202:203] op_sel:[1,0,0]
	v_permlane32_swap_b32_e32 v21, v37
	v_pk_fma_f32 v[12:13], v[8:9], v[12:13], v[18:19] op_sel_hi:[0,1,1]
	v_pk_fma_f32 v[14:15], v[8:9], v[14:15], v[202:203] op_sel_hi:[0,1,1]
	v_permlane32_swap_b32_e32 v205, v221
	v_pk_fma_f32 v[32:33], v[10:11], v[14:15], v[32:33] op_sel_hi:[0,1,1]
	v_pk_fma_f32 v[216:217], v[8:9], v[12:13], v[216:217] op_sel:[1,0,0]
	v_permlane32_swap_b32_e32 v22, v38
	v_pk_fma_f32 v[12:13], v[8:9], v[12:13], v[32:33] op_sel_hi:[0,1,1]
	v_pk_fma_f32 v[14:15], v[8:9], v[14:15], v[216:217] op_sel_hi:[0,1,1]
	v_permlane32_swap_b32_e32 v206, v222
	v_pk_fma_f32 v[34:35], v[10:11], v[14:15], v[34:35] op_sel_hi:[0,1,1]
	v_pk_fma_f32 v[218:219], v[8:9], v[12:13], v[218:219] op_sel:[1,0,0]
	v_permlane32_swap_b32_e32 v23, v39
	v_pk_fma_f32 v[12:13], v[8:9], v[12:13], v[34:35] op_sel_hi:[0,1,1]
	v_pk_fma_f32 v[14:15], v[8:9], v[14:15], v[218:219] op_sel_hi:[0,1,1]
	v_permlane32_swap_b32_e32 v207, v223
	v_pk_fma_f32 v[20:21], v[10:11], v[14:15], v[20:21] op_sel_hi:[0,1,1]
	v_pk_fma_f32 v[204:205], v[8:9], v[12:13], v[204:205] op_sel:[1,0,0]
	v_permlane32_swap_b32_e32 v24, v40
	v_pk_fma_f32 v[12:13], v[8:9], v[12:13], v[20:21] op_sel_hi:[0,1,1]
	v_pk_fma_f32 v[14:15], v[8:9], v[14:15], v[204:205] op_sel_hi:[0,1,1]
	v_permlane32_swap_b32_e32 v208, v224
	v_pk_fma_f32 v[22:23], v[10:11], v[14:15], v[22:23] op_sel_hi:[0,1,1]
	v_pk_fma_f32 v[206:207], v[8:9], v[12:13], v[206:207] op_sel:[1,0,0]
	v_permlane32_swap_b32_e32 v25, v41
	v_pk_fma_f32 v[12:13], v[8:9], v[12:13], v[22:23] op_sel_hi:[0,1,1]
	v_pk_fma_f32 v[14:15], v[8:9], v[14:15], v[206:207] op_sel_hi:[0,1,1]
	v_permlane32_swap_b32_e32 v209, v225
	v_pk_fma_f32 v[36:37], v[10:11], v[14:15], v[36:37] op_sel_hi:[0,1,1]
	v_pk_fma_f32 v[220:221], v[8:9], v[12:13], v[220:221] op_sel:[1,0,0]
	v_permlane32_swap_b32_e32 v26, v42
	v_pk_fma_f32 v[12:13], v[8:9], v[12:13], v[36:37] op_sel_hi:[0,1,1]
	v_pk_fma_f32 v[14:15], v[8:9], v[14:15], v[220:221] op_sel_hi:[0,1,1]
	v_permlane32_swap_b32_e32 v210, v226
	v_pk_fma_f32 v[38:39], v[10:11], v[14:15], v[38:39] op_sel_hi:[0,1,1]
	v_pk_fma_f32 v[222:223], v[8:9], v[12:13], v[222:223] op_sel:[1,0,0]
	v_permlane32_swap_b32_e32 v27, v43
	v_pk_fma_f32 v[12:13], v[8:9], v[12:13], v[38:39] op_sel_hi:[0,1,1]
	v_pk_fma_f32 v[14:15], v[8:9], v[14:15], v[222:223] op_sel_hi:[0,1,1]
	v_permlane32_swap_b32_e32 v211, v227
	v_pk_fma_f32 v[24:25], v[10:11], v[14:15], v[24:25] op_sel_hi:[0,1,1]
	v_pk_fma_f32 v[208:209], v[8:9], v[12:13], v[208:209] op_sel:[1,0,0]
	v_permlane32_swap_b32_e32 v28, v44
	v_pk_fma_f32 v[12:13], v[8:9], v[12:13], v[24:25] op_sel_hi:[0,1,1]
	v_pk_fma_f32 v[14:15], v[8:9], v[14:15], v[208:209] op_sel_hi:[0,1,1]
	v_permlane32_swap_b32_e32 v212, v228
	v_pk_fma_f32 v[26:27], v[10:11], v[14:15], v[26:27] op_sel_hi:[0,1,1]
	v_pk_fma_f32 v[210:211], v[8:9], v[12:13], v[210:211] op_sel:[1,0,0]
	v_permlane32_swap_b32_e32 v29, v45
	v_pk_fma_f32 v[12:13], v[8:9], v[12:13], v[26:27] op_sel_hi:[0,1,1]
	v_pk_fma_f32 v[14:15], v[8:9], v[14:15], v[210:211] op_sel_hi:[0,1,1]
	v_permlane32_swap_b32_e32 v213, v229
	v_pk_fma_f32 v[40:41], v[10:11], v[14:15], v[40:41] op_sel_hi:[0,1,1]
	v_pk_fma_f32 v[224:225], v[8:9], v[12:13], v[224:225] op_sel:[1,0,0]
	v_permlane32_swap_b32_e32 v30, v46
	v_pk_fma_f32 v[12:13], v[8:9], v[12:13], v[40:41] op_sel_hi:[0,1,1]
	v_pk_fma_f32 v[14:15], v[8:9], v[14:15], v[224:225] op_sel_hi:[0,1,1]
	v_permlane32_swap_b32_e32 v214, v230
	v_pk_fma_f32 v[42:43], v[10:11], v[14:15], v[42:43] op_sel_hi:[0,1,1]
	v_pk_fma_f32 v[226:227], v[8:9], v[12:13], v[226:227] op_sel:[1,0,0]
	v_permlane32_swap_b32_e32 v31, v47
	v_pk_fma_f32 v[12:13], v[8:9], v[12:13], v[42:43] op_sel_hi:[0,1,1]
	v_pk_fma_f32 v[14:15], v[8:9], v[14:15], v[226:227] op_sel_hi:[0,1,1]
	v_permlane32_swap_b32_e32 v215, v231
	v_pk_fma_f32 v[28:29], v[10:11], v[14:15], v[28:29] op_sel_hi:[0,1,1]
	v_pk_fma_f32 v[212:213], v[8:9], v[12:13], v[212:213] op_sel:[1,0,0]
	s_nop 0
	v_pk_fma_f32 v[12:13], v[8:9], v[12:13], v[28:29] op_sel_hi:[0,1,1]
	v_pk_fma_f32 v[14:15], v[8:9], v[14:15], v[212:213] op_sel_hi:[0,1,1]
	s_nop 0
	v_pk_fma_f32 v[30:31], v[10:11], v[14:15], v[30:31] op_sel_hi:[0,1,1]
	v_pk_fma_f32 v[214:215], v[8:9], v[12:13], v[214:215] op_sel:[1,0,0]
	s_nop 0
	v_pk_fma_f32 v[12:13], v[8:9], v[12:13], v[30:31] op_sel_hi:[0,1,1]
	v_pk_fma_f32 v[14:15], v[8:9], v[14:15], v[214:215] op_sel_hi:[0,1,1]
	s_nop 0
	v_pk_fma_f32 v[44:45], v[10:11], v[14:15], v[44:45] op_sel_hi:[0,1,1]
	v_pk_fma_f32 v[228:229], v[8:9], v[12:13], v[228:229] op_sel:[1,0,0]
	s_nop 0
	v_pk_fma_f32 v[12:13], v[8:9], v[12:13], v[44:45] op_sel_hi:[0,1,1]
	v_pk_fma_f32 v[14:15], v[8:9], v[14:15], v[228:229] op_sel_hi:[0,1,1]
	s_nop 0
	v_pk_fma_f32 v[46:47], v[10:11], v[14:15], v[46:47] op_sel_hi:[0,1,1]
	v_pk_fma_f32 v[230:231], v[8:9], v[12:13], v[230:231] op_sel:[1,0,0]
	s_nop 0
	v_pk_fma_f32 v[12:13], v[8:9], v[12:13], v[46:47] op_sel_hi:[0,1,1]
	v_pk_fma_f32 v[14:15], v[8:9], v[14:15], v[230:231] op_sel_hi:[0,1,1]
	s_nop 0
	s_nop 0
	v_fma_f32 v181, v180, v14, v13
	v_fma_f32 v182, v179, v12, v15
	v_fma_f32 v12, v178, v12, v181
	v_fma_f32 v14, v178, v14, v182
	v_mov_b32_e32 v13, 0
	v_mov_b32_e32 v15, 0
	v_mov_b32_e32 v182, v12
	v_mov_b32_e32 v183, v14
	global_store_dwordx2 v7, v[182:183], s[48:49]
	s_add_u32 s48, s48, 0x100000
	s_addc_u32 s49, s49, 0
	global_load_dwordx4 v[104:107], v5, s[54:55]
	global_load_dwordx4 v[108:111], v6, s[54:55]
	s_add_u32 s54, s54, 0x400000
	s_addc_u32 s55, s55, 0
	v_mov_b32_e32 v12, 0
	v_mov_b32_e32 v13, 0
	v_mov_b32_e32 v14, 0
	v_mov_b32_e32 v15, 0
	s_waitcnt vmcnt(9)
; #define LAS __attribute__((address_space(3)))
; #define LDS_WAIT() asm volatile("s_waitcnt lgkmcnt(0)" ::: "memory")
; #define MFMA_PIN(a, b) do { __builtin_amdgcn_sched_barrier(0); asm volatile("" :: "v"(a), "v"(b)); } while (0)
; #define MFMA_SETTLE() do { __builtin_amdgcn_sched_barrier(0); asm volatile("s_nop 15"); __builtin_amdgcn_sched_barrier(0); } while (0)
; __device__ __forceinline__ void ssm_bu16(const bf16x8 afr, const bf16x8 (&bf)[8], LAS float* bubuf, int lane) {
;     LAS float* wp = bubuf + (4 * (lane >> 4)) * BUP + (lane & 15);
;     f32x4 d[8];
; #pragma unroll
;     for (int cb = 0; cb < 8; ++cb) { d[cb] = __builtin_amdgcn_mfma_f32_16x16x32_bf16(afr, bf[cb], (f32x4){0.f, 0.f, 0.f, 0.f}, 0, 0, 0); MFMA_PIN(afr, bf[cb]); }
;     MFMA_SETTLE();
; __device__ __forceinline__ void p5_phase(Frame& F) {
;     ...
;     for (int it = F.gw; it < NB * NCH * NGRP; it += F.ngw) {
;         bf16x8 afr[4];
; #pragma unroll
;         for (int sub = 0; sub < 4; ++sub) afr[sub] = nfr[sub];
;         if (it + F.ngw < NB * NCH * NGRP) { const int bc = (it + F.ngw) >> 7, r0 = (bc / NCH) * SEQ + (bc % NCH) * TCH;
; #pragma unroll
;             for (int sub = 0; sub < 4; ++sub) nfr[sub] = ssm_load_afrag(U, r0 + 16 * sub, g, F.lane); }
;         float sr = 0.f, si = 0.f;
; #pragma unroll
;         for (int sub = 0; sub < 4; ++sub) {
;             ssm_bu16(afr[sub], bf, bubuf, F.lane);
; #pragma unroll
;             for (int tt = 0; tt < 16; ++tt) { const float bur = bubuf[tt * BUP + F.lane], bui = bubuf[tt * BUP + 64 + F.lane];
;                 const float nr = fmaf(ab.x, sr, fmaf(-ab.y, si, bur)), ni = fmaf(ab.x, si, fmaf(ab.y, sr, bui)); sr = nr; si = ni; }
;             LDS_WAIT(); asm volatile("" ::: "memory");
;         }
;         ((f32x2*)(F.ws + WS_E))[(size_t)it * NST + F.lane] = (f32x2){sr, si};
	v_mfma_f32_32x32x16_bf16 v[16:31], v[84:87], v[48:51], 0
	v_mfma_f32_32x32x16_bf16 v[32:47], v[84:87], v[52:55], 0
	v_mfma_f32_32x32x16_bf16 v[200:215], v[84:87], v[56:59], 0
	v_mfma_f32_32x32x16_bf16 v[216:231], v[84:87], v[60:63], 0
	v_mfma_f32_32x32x16_bf16 v[16:31], v[84:87], v[64:67], v[16:31]
	v_mfma_f32_32x32x16_bf16 v[32:47], v[84:87], v[68:71], v[32:47]
	v_mfma_f32_32x32x16_bf16 v[200:215], v[84:87], v[72:75], v[200:215]
	v_mfma_f32_32x32x16_bf16 v[216:231], v[84:87], v[76:79], v[216:231]
	s_nop 3
	v_permlane32_swap_b32_e32 v112, v128
	v_permlane32_swap_b32_e32 v144, v160
	v_permlane32_swap_b32_e32 v113, v129
	v_permlane32_swap_b32_e32 v145, v161
	v_permlane32_swap_b32_e32 v114, v130
	v_permlane32_swap_b32_e32 v146, v162
	v_permlane32_swap_b32_e32 v115, v131
	v_permlane32_swap_b32_e32 v147, v163
	v_pk_fma_f32 v[112:113], v[10:11], v[14:15], v[112:113] op_sel_hi:[0,1,1]
	v_pk_fma_f32 v[144:145], v[8:9], v[12:13], v[144:145] op_sel:[1,0,0]
	v_permlane32_swap_b32_e32 v116, v132
	v_pk_fma_f32 v[12:13], v[8:9], v[12:13], v[112:113] op_sel_hi:[0,1,1]
	v_pk_fma_f32 v[14:15], v[8:9], v[14:15], v[144:145] op_sel_hi:[0,1,1]
	v_permlane32_swap_b32_e32 v148, v164
	v_pk_fma_f32 v[114:115], v[10:11], v[14:15], v[114:115] op_sel_hi:[0,1,1]
	v_pk_fma_f32 v[146:147], v[8:9], v[12:13], v[146:147] op_sel:[1,0,0]
	v_permlane32_swap_b32_e32 v117, v133
	v_pk_fma_f32 v[12:13], v[8:9], v[12:13], v[114:115] op_sel_hi:[0,1,1]
	v_pk_fma_f32 v[14:15], v[8:9], v[14:15], v[146:147] op_sel_hi:[0,1,1]
	v_permlane32_swap_b32_e32 v149, v165
	v_pk_fma_f32 v[128:129], v[10:11], v[14:15], v[128:129] op_sel_hi:[0,1,1]
	v_pk_fma_f32 v[160:161], v[8:9], v[12:13], v[160:161] op_sel:[1,0,0]
	v_permlane32_swap_b32_e32 v118, v134
	v_pk_fma_f32 v[12:13], v[8:9], v[12:13], v[128:129] op_sel_hi:[0,1,1]
	v_pk_fma_f32 v[14:15], v[8:9], v[14:15], v[160:161] op_sel_hi:[0,1,1]
	v_permlane32_swap_b32_e32 v150, v166
	v_pk_fma_f32 v[130:131], v[10:11], v[14:15], v[130:131] op_sel_hi:[0,1,1]
	v_pk_fma_f32 v[162:163], v[8:9], v[12:13], v[162:163] op_sel:[1,0,0]
	v_permlane32_swap_b32_e32 v119, v135
	v_pk_fma_f32 v[12:13], v[8:9], v[12:13], v[130:131] op_sel_hi:[0,1,1]
	v_pk_fma_f32 v[14:15], v[8:9], v[14:15], v[162:163] op_sel_hi:[0,1,1]
	v_permlane32_swap_b32_e32 v151, v167
	v_pk_fma_f32 v[116:117], v[10:11], v[14:15], v[116:117] op_sel_hi:[0,1,1]
	v_pk_fma_f32 v[148:149], v[8:9], v[12:13], v[148:149] op_sel:[1,0,0]
	v_permlane32_swap_b32_e32 v120, v136
	v_pk_fma_f32 v[12:13], v[8:9], v[12:13], v[116:117] op_sel_hi:[0,1,1]
	v_pk_fma_f32 v[14:15], v[8:9], v[14:15], v[148:149] op_sel_hi:[0,1,1]
	v_permlane32_swap_b32_e32 v152, v168
	v_pk_fma_f32 v[118:119], v[10:11], v[14:15], v[118:119] op_sel_hi:[0,1,1]
	v_pk_fma_f32 v[150:151], v[8:9], v[12:13], v[150:151] op_sel:[1,0,0]
	v_permlane32_swap_b32_e32 v121, v137
	v_pk_fma_f32 v[12:13], v[8:9], v[12:13], v[118:119] op_sel_hi:[0,1,1]
	v_pk_fma_f32 v[14:15], v[8:9], v[14:15], v[150:151] op_sel_hi:[0,1,1]
	v_permlane32_swap_b32_e32 v153, v169
	v_pk_fma_f32 v[132:133], v[10:11], v[14:15], v[132:133] op_sel_hi:[0,1,1]
	v_pk_fma_f32 v[164:165], v[8:9], v[12:13], v[164:165] op_sel:[1,0,0]
	v_permlane32_swap_b32_e32 v122, v138
	v_pk_fma_f32 v[12:13], v[8:9], v[12:13], v[132:133] op_sel_hi:[0,1,1]
	v_pk_fma_f32 v[14:15], v[8:9], v[14:15], v[164:165] op_sel_hi:[0,1,1]
	v_permlane32_swap_b32_e32 v154, v170
	v_pk_fma_f32 v[134:135], v[10:11], v[14:15], v[134:135] op_sel_hi:[0,1,1]
	v_pk_fma_f32 v[166:167], v[8:9], v[12:13], v[166:167] op_sel:[1,0,0]
	v_permlane32_swap_b32_e32 v123, v139
	v_pk_fma_f32 v[12:13], v[8:9], v[12:13], v[134:135] op_sel_hi:[0,1,1]
	v_pk_fma_f32 v[14:15], v[8:9], v[14:15], v[166:167] op_sel_hi:[0,1,1]
	v_permlane32_swap_b32_e32 v155, v171
	v_pk_fma_f32 v[120:121], v[10:11], v[14:15], v[120:121] op_sel_hi:[0,1,1]
	v_pk_fma_f32 v[152:153], v[8:9], v[12:13], v[152:153] op_sel:[1,0,0]
	v_permlane32_swap_b32_e32 v124, v140
	v_pk_fma_f32 v[12:13], v[8:9], v[12:13], v[120:121] op_sel_hi:[0,1,1]
	v_pk_fma_f32 v[14:15], v[8:9], v[14:15], v[152:153] op_sel_hi:[0,1,1]
	v_permlane32_swap_b32_e32 v156, v172
	v_pk_fma_f32 v[122:123], v[10:11], v[14:15], v[122:123] op_sel_hi:[0,1,1]
	v_pk_fma_f32 v[154:155], v[8:9], v[12:13], v[154:155] op_sel:[1,0,0]
	v_permlane32_swap_b32_e32 v125, v141
	v_pk_fma_f32 v[12:13], v[8:9], v[12:13], v[122:123] op_sel_hi:[0,1,1]
	v_pk_fma_f32 v[14:15], v[8:9], v[14:15], v[154:155] op_sel_hi:[0,1,1]
	v_permlane32_swap_b32_e32 v157, v173
	v_pk_fma_f32 v[136:137], v[10:11], v[14:15], v[136:137] op_sel_hi:[0,1,1]
	v_pk_fma_f32 v[168:169], v[8:9], v[12:13], v[168:169] op_sel:[1,0,0]
	v_permlane32_swap_b32_e32 v126, v142
	v_pk_fma_f32 v[12:13], v[8:9], v[12:13], v[136:137] op_sel_hi:[0,1,1]
	v_pk_fma_f32 v[14:15], v[8:9], v[14:15], v[168:169] op_sel_hi:[0,1,1]
	v_permlane32_swap_b32_e32 v158, v174
	v_pk_fma_f32 v[138:139], v[10:11], v[14:15], v[138:139] op_sel_hi:[0,1,1]
	v_pk_fma_f32 v[170:171], v[8:9], v[12:13], v[170:171] op_sel:[1,0,0]
	v_permlane32_swap_b32_e32 v127, v143
	v_pk_fma_f32 v[12:13], v[8:9], v[12:13], v[138:139] op_sel_hi:[0,1,1]
	v_pk_fma_f32 v[14:15], v[8:9], v[14:15], v[170:171] op_sel_hi:[0,1,1]
	v_permlane32_swap_b32_e32 v159, v175
	v_pk_fma_f32 v[124:125], v[10:11], v[14:15], v[124:125] op_sel_hi:[0,1,1]
	v_pk_fma_f32 v[156:157], v[8:9], v[12:13], v[156:157] op_sel:[1,0,0]
	s_nop 0
	v_pk_fma_f32 v[12:13], v[8:9], v[12:13], v[124:125] op_sel_hi:[0,1,1]
	v_pk_fma_f32 v[14:15], v[8:9], v[14:15], v[156:157] op_sel_hi:[0,1,1]
	s_nop 0
	v_pk_fma_f32 v[126:127], v[10:11], v[14:15], v[126:127] op_sel_hi:[0,1,1]
	v_pk_fma_f32 v[158:159], v[8:9], v[12:13], v[158:159] op_sel:[1,0,0]
	s_nop 0
	v_pk_fma_f32 v[12:13], v[8:9], v[12:13], v[126:127] op_sel_hi:[0,1,1]
	v_pk_fma_f32 v[14:15], v[8:9], v[14:15], v[158:159] op_sel_hi:[0,1,1]
	s_nop 0
	v_pk_fma_f32 v[140:141], v[10:11], v[14:15], v[140:141] op_sel_hi:[0,1,1]
	v_pk_fma_f32 v[172:173], v[8:9], v[12:13], v[172:173] op_sel:[1,0,0]
	s_nop 0
	v_pk_fma_f32 v[12:13], v[8:9], v[12:13], v[140:141] op_sel_hi:[0,1,1]
	v_pk_fma_f32 v[14:15], v[8:9], v[14:15], v[172:173] op_sel_hi:[0,1,1]
	s_nop 0
	v_pk_fma_f32 v[142:143], v[10:11], v[14:15], v[142:143] op_sel_hi:[0,1,1]
	v_pk_fma_f32 v[174:175], v[8:9], v[12:13], v[174:175] op_sel:[1,0,0]
	s_nop 0
	v_pk_fma_f32 v[12:13], v[8:9], v[12:13], v[142:143] op_sel_hi:[0,1,1]
	v_pk_fma_f32 v[14:15], v[8:9], v[14:15], v[174:175] op_sel_hi:[0,1,1]
	s_nop 0
	s_nop 0
	v_fma_f32 v181, v180, v14, v13
	v_fma_f32 v182, v179, v12, v15
	v_fma_f32 v12, v178, v12, v181
	v_fma_f32 v14, v178, v14, v182
	v_mov_b32_e32 v13, 0
	v_mov_b32_e32 v15, 0
	s_waitcnt vmcnt(7)
; #define LAS __attribute__((address_space(3)))
; #define LDS_WAIT() asm volatile("s_waitcnt lgkmcnt(0)" ::: "memory")
; #define MFMA_PIN(a, b) do { __builtin_amdgcn_sched_barrier(0); asm volatile("" :: "v"(a), "v"(b)); } while (0)
; #define MFMA_SETTLE() do { __builtin_amdgcn_sched_barrier(0); asm volatile("s_nop 15"); __builtin_amdgcn_sched_barrier(0); } while (0)
; __device__ __forceinline__ void ssm_bu16(const bf16x8 afr, const bf16x8 (&bf)[8], LAS float* bubuf, int lane) {
;     LAS float* wp = bubuf + (4 * (lane >> 4)) * BUP + (lane & 15);
;     f32x4 d[8];
; #pragma unroll
;     for (int cb = 0; cb < 8; ++cb) { d[cb] = __builtin_amdgcn_mfma_f32_16x16x32_bf16(afr, bf[cb], (f32x4){0.f, 0.f, 0.f, 0.f}, 0, 0, 0); MFMA_PIN(afr, bf[cb]); }
;     MFMA_SETTLE();
; __device__ __forceinline__ void p5_phase(Frame& F) {
;     ...
;     for (int it = F.gw; it < NB * NCH * NGRP; it += F.ngw) {
;         bf16x8 afr[4];
; #pragma unroll
;         for (int sub = 0; sub < 4; ++sub) afr[sub] = nfr[sub];
;         if (it + F.ngw < NB * NCH * NGRP) { const int bc = (it + F.ngw) >> 7, r0 = (bc / NCH) * SEQ + (bc % NCH) * TCH;
; #pragma unroll
;             for (int sub = 0; sub < 4; ++sub) nfr[sub] = ssm_load_afrag(U, r0 + 16 * sub, g, F.lane); }
;         float sr = 0.f, si = 0.f;
; #pragma unroll
;         for (int sub = 0; sub < 4; ++sub) {
;             ssm_bu16(afr[sub], bf, bubuf, F.lane);
; #pragma unroll
;             for (int tt = 0; tt < 16; ++tt) { const float bur = bubuf[tt * BUP + F.lane], bui = bubuf[tt * BUP + 64 + F.lane];
;                 const float nr = fmaf(ab.x, sr, fmaf(-ab.y, si, bur)), ni = fmaf(ab.x, si, fmaf(ab.y, sr, bui)); sr = nr; si = ni; }
;             LDS_WAIT(); asm volatile("" ::: "memory");
;         }
;         ((f32x2*)(F.ws + WS_E))[(size_t)it * NST + F.lane] = (f32x2){sr, si};
	v_mfma_f32_32x32x16_bf16 v[112:127], v[88:91], v[48:51], 0
	v_mfma_f32_32x32x16_bf16 v[128:143], v[88:91], v[52:55], 0
	v_mfma_f32_32x32x16_bf16 v[144:159], v[88:91], v[56:59], 0
	v_mfma_f32_32x32x16_bf16 v[160:175], v[88:91], v[60:63], 0
	v_mfma_f32_32x32x16_bf16 v[112:127], v[88:91], v[64:67], v[112:127]
	v_mfma_f32_32x32x16_bf16 v[128:143], v[88:91], v[68:71], v[128:143]
	v_mfma_f32_32x32x16_bf16 v[144:159], v[88:91], v[72:75], v[144:159]
	v_mfma_f32_32x32x16_bf16 v[160:175], v[88:91], v[76:79], v[160:175]
	s_nop 3
	v_permlane32_swap_b32_e32 v16, v32
	v_permlane32_swap_b32_e32 v200, v216
	v_permlane32_swap_b32_e32 v17, v33
	v_permlane32_swap_b32_e32 v201, v217
	v_permlane32_swap_b32_e32 v18, v34
	v_permlane32_swap_b32_e32 v202, v218
	v_permlane32_swap_b32_e32 v19, v35
	v_permlane32_swap_b32_e32 v203, v219
	v_pk_fma_f32 v[16:17], v[10:11], v[14:15], v[16:17] op_sel_hi:[0,1,1]
	v_pk_fma_f32 v[200:201], v[8:9], v[12:13], v[200:201] op_sel:[1,0,0]
	v_permlane32_swap_b32_e32 v20, v36
	v_pk_fma_f32 v[12:13], v[8:9], v[12:13], v[16:17] op_sel_hi:[0,1,1]
	v_pk_fma_f32 v[14:15], v[8:9], v[14:15], v[200:201] op_sel_hi:[0,1,1]
	v_permlane32_swap_b32_e32 v204, v220
	v_pk_fma_f32 v[18:19], v[10:11], v[14:15], v[18:19] op_sel_hi:[0,1,1]
	v_pk_fma_f32 v[202:203], v[8:9], v[12:13], v[202:203] op_sel:[1,0,0]
	v_permlane32_swap_b32_e32 v21, v37
	v_pk_fma_f32 v[12:13], v[8:9], v[12:13], v[18:19] op_sel_hi:[0,1,1]
	v_pk_fma_f32 v[14:15], v[8:9], v[14:15], v[202:203] op_sel_hi:[0,1,1]
	v_permlane32_swap_b32_e32 v205, v221
	v_pk_fma_f32 v[32:33], v[10:11], v[14:15], v[32:33] op_sel_hi:[0,1,1]
	v_pk_fma_f32 v[216:217], v[8:9], v[12:13], v[216:217] op_sel:[1,0,0]
	v_permlane32_swap_b32_e32 v22, v38
	v_pk_fma_f32 v[12:13], v[8:9], v[12:13], v[32:33] op_sel_hi:[0,1,1]
	v_pk_fma_f32 v[14:15], v[8:9], v[14:15], v[216:217] op_sel_hi:[0,1,1]
	v_permlane32_swap_b32_e32 v206, v222
	v_pk_fma_f32 v[34:35], v[10:11], v[14:15], v[34:35] op_sel_hi:[0,1,1]
	v_pk_fma_f32 v[218:219], v[8:9], v[12:13], v[218:219] op_sel:[1,0,0]
	v_permlane32_swap_b32_e32 v23, v39
	v_pk_fma_f32 v[12:13], v[8:9], v[12:13], v[34:35] op_sel_hi:[0,1,1]
	v_pk_fma_f32 v[14:15], v[8:9], v[14:15], v[218:219] op_sel_hi:[0,1,1]
	v_permlane32_swap_b32_e32 v207, v223
	v_pk_fma_f32 v[20:21], v[10:11], v[14:15], v[20:21] op_sel_hi:[0,1,1]
	v_pk_fma_f32 v[204:205], v[8:9], v[12:13], v[204:205] op_sel:[1,0,0]
	v_permlane32_swap_b32_e32 v24, v40
	v_pk_fma_f32 v[12:13], v[8:9], v[12:13], v[20:21] op_sel_hi:[0,1,1]
	v_pk_fma_f32 v[14:15], v[8:9], v[14:15], v[204:205] op_sel_hi:[0,1,1]
	v_permlane32_swap_b32_e32 v208, v224
	v_pk_fma_f32 v[22:23], v[10:11], v[14:15], v[22:23] op_sel_hi:[0,1,1]
	v_pk_fma_f32 v[206:207], v[8:9], v[12:13], v[206:207] op_sel:[1,0,0]
	v_permlane32_swap_b32_e32 v25, v41
	v_pk_fma_f32 v[12:13], v[8:9], v[12:13], v[22:23] op_sel_hi:[0,1,1]
	v_pk_fma_f32 v[14:15], v[8:9], v[14:15], v[206:207] op_sel_hi:[0,1,1]
	v_permlane32_swap_b32_e32 v209, v225
	v_pk_fma_f32 v[36:37], v[10:11], v[14:15], v[36:37] op_sel_hi:[0,1,1]
	v_pk_fma_f32 v[220:221], v[8:9], v[12:13], v[220:221] op_sel:[1,0,0]
	v_permlane32_swap_b32_e32 v26, v42
	v_pk_fma_f32 v[12:13], v[8:9], v[12:13], v[36:37] op_sel_hi:[0,1,1]
	v_pk_fma_f32 v[14:15], v[8:9], v[14:15], v[220:221] op_sel_hi:[0,1,1]
	v_permlane32_swap_b32_e32 v210, v226
	v_pk_fma_f32 v[38:39], v[10:11], v[14:15], v[38:39] op_sel_hi:[0,1,1]
	v_pk_fma_f32 v[222:223], v[8:9], v[12:13], v[222:223] op_sel:[1,0,0]
	v_permlane32_swap_b32_e32 v27, v43
	v_pk_fma_f32 v[12:13], v[8:9], v[12:13], v[38:39] op_sel_hi:[0,1,1]
	v_pk_fma_f32 v[14:15], v[8:9], v[14:15], v[222:223] op_sel_hi:[0,1,1]
	v_permlane32_swap_b32_e32 v211, v227
	v_pk_fma_f32 v[24:25], v[10:11], v[14:15], v[24:25] op_sel_hi:[0,1,1]
	v_pk_fma_f32 v[208:209], v[8:9], v[12:13], v[208:209] op_sel:[1,0,0]
	v_permlane32_swap_b32_e32 v28, v44
	v_pk_fma_f32 v[12:13], v[8:9], v[12:13], v[24:25] op_sel_hi:[0,1,1]
	v_pk_fma_f32 v[14:15], v[8:9], v[14:15], v[208:209] op_sel_hi:[0,1,1]
	v_permlane32_swap_b32_e32 v212, v228
	v_pk_fma_f32 v[26:27], v[10:11], v[14:15], v[26:27] op_sel_hi:[0,1,1]
	v_pk_fma_f32 v[210:211], v[8:9], v[12:13], v[210:211] op_sel:[1,0,0]
	v_permlane32_swap_b32_e32 v29, v45
	v_pk_fma_f32 v[12:13], v[8:9], v[12:13], v[26:27] op_sel_hi:[0,1,1]
	v_pk_fma_f32 v[14:15], v[8:9], v[14:15], v[210:211] op_sel_hi:[0,1,1]
	v_permlane32_swap_b32_e32 v213, v229
	v_pk_fma_f32 v[40:41], v[10:11], v[14:15], v[40:41] op_sel_hi:[0,1,1]
	v_pk_fma_f32 v[224:225], v[8:9], v[12:13], v[224:225] op_sel:[1,0,0]
	v_permlane32_swap_b32_e32 v30, v46
	v_pk_fma_f32 v[12:13], v[8:9], v[12:13], v[40:41] op_sel_hi:[0,1,1]
	v_pk_fma_f32 v[14:15], v[8:9], v[14:15], v[224:225] op_sel_hi:[0,1,1]
	v_permlane32_swap_b32_e32 v214, v230
	v_pk_fma_f32 v[42:43], v[10:11], v[14:15], v[42:43] op_sel_hi:[0,1,1]
	v_pk_fma_f32 v[226:227], v[8:9], v[12:13], v[226:227] op_sel:[1,0,0]
	v_permlane32_swap_b32_e32 v31, v47
	v_pk_fma_f32 v[12:13], v[8:9], v[12:13], v[42:43] op_sel_hi:[0,1,1]
	v_pk_fma_f32 v[14:15], v[8:9], v[14:15], v[226:227] op_sel_hi:[0,1,1]
	v_permlane32_swap_b32_e32 v215, v231
	v_pk_fma_f32 v[28:29], v[10:11], v[14:15], v[28:29] op_sel_hi:[0,1,1]
	v_pk_fma_f32 v[212:213], v[8:9], v[12:13], v[212:213] op_sel:[1,0,0]
	s_nop 0
	v_pk_fma_f32 v[12:13], v[8:9], v[12:13], v[28:29] op_sel_hi:[0,1,1]
	v_pk_fma_f32 v[14:15], v[8:9], v[14:15], v[212:213] op_sel_hi:[0,1,1]
	s_nop 0
	v_pk_fma_f32 v[30:31], v[10:11], v[14:15], v[30:31] op_sel_hi:[0,1,1]
	v_pk_fma_f32 v[214:215], v[8:9], v[12:13], v[214:215] op_sel:[1,0,0]
	s_nop 0
	v_pk_fma_f32 v[12:13], v[8:9], v[12:13], v[30:31] op_sel_hi:[0,1,1]
	v_pk_fma_f32 v[14:15], v[8:9], v[14:15], v[214:215] op_sel_hi:[0,1,1]
	s_nop 0
	v_pk_fma_f32 v[44:45], v[10:11], v[14:15], v[44:45] op_sel_hi:[0,1,1]
	v_pk_fma_f32 v[228:229], v[8:9], v[12:13], v[228:229] op_sel:[1,0,0]
	s_nop 0
	v_pk_fma_f32 v[12:13], v[8:9], v[12:13], v[44:45] op_sel_hi:[0,1,1]
	v_pk_fma_f32 v[14:15], v[8:9], v[14:15], v[228:229] op_sel_hi:[0,1,1]
	s_nop 0
	v_pk_fma_f32 v[46:47], v[10:11], v[14:15], v[46:47] op_sel_hi:[0,1,1]
	v_pk_fma_f32 v[230:231], v[8:9], v[12:13], v[230:231] op_sel:[1,0,0]
	s_nop 0
	v_pk_fma_f32 v[12:13], v[8:9], v[12:13], v[46:47] op_sel_hi:[0,1,1]
	v_pk_fma_f32 v[14:15], v[8:9], v[14:15], v[230:231] op_sel_hi:[0,1,1]
	s_nop 0
	s_nop 0
	v_fma_f32 v181, v180, v14, v13
	v_fma_f32 v182, v179, v12, v15
	v_fma_f32 v12, v178, v12, v181
	v_fma_f32 v14, v178, v14, v182
	v_mov_b32_e32 v13, 0
	v_mov_b32_e32 v15, 0
	v_mov_b32_e32 v182, v12
	v_mov_b32_e32 v183, v14
	global_store_dwordx2 v7, v[182:183], s[48:49]
	s_add_u32 s48, s48, 0x100000
	s_addc_u32 s49, s49, 0
	v_mov_b32_e32 v12, 0
	v_mov_b32_e32 v13, 0
	v_mov_b32_e32 v14, 0
	v_mov_b32_e32 v15, 0
	s_waitcnt vmcnt(7)
; #define LAS __attribute__((address_space(3)))
; #define LDS_WAIT() asm volatile("s_waitcnt lgkmcnt(0)" ::: "memory")
; #define MFMA_PIN(a, b) do { __builtin_amdgcn_sched_barrier(0); asm volatile("" :: "v"(a), "v"(b)); } while (0)
; #define MFMA_SETTLE() do { __builtin_amdgcn_sched_barrier(0); asm volatile("s_nop 15"); __builtin_amdgcn_sched_barrier(0); } while (0)
; __device__ __forceinline__ void ssm_bu16(const bf16x8 afr, const bf16x8 (&bf)[8], LAS float* bubuf, int lane) {
;     LAS float* wp = bubuf + (4 * (lane >> 4)) * BUP + (lane & 15);
;     f32x4 d[8];
; #pragma unroll
;     for (int cb = 0; cb < 8; ++cb) { d[cb] = __builtin_amdgcn_mfma_f32_16x16x32_bf16(afr, bf[cb], (f32x4){0.f, 0.f, 0.f, 0.f}, 0, 0, 0); MFMA_PIN(afr, bf[cb]); }
;     MFMA_SETTLE();
; __device__ __forceinline__ void p5_phase(Frame& F) {
;     ...
;     for (int it = F.gw; it < NB * NCH * NGRP; it += F.ngw) {
;         bf16x8 afr[4];
; #pragma unroll
;         for (int sub = 0; sub < 4; ++sub) afr[sub] = nfr[sub];
;         if (it + F.ngw < NB * NCH * NGRP) { const int bc = (it + F.ngw) >> 7, r0 = (bc / NCH) * SEQ + (bc % NCH) * TCH;
; #pragma unroll
;             for (int sub = 0; sub < 4; ++sub) nfr[sub] = ssm_load_afrag(U, r0 + 16 * sub, g, F.lane); }
;         float sr = 0.f, si = 0.f;
; #pragma unroll
;         for (int sub = 0; sub < 4; ++sub) {
;             ssm_bu16(afr[sub], bf, bubuf, F.lane);
; #pragma unroll
;             for (int tt = 0; tt < 16; ++tt) { const float bur = bubuf[tt * BUP + F.lane], bui = bubuf[tt * BUP + 64 + F.lane];
;                 const float nr = fmaf(ab.x, sr, fmaf(-ab.y, si, bur)), ni = fmaf(ab.x, si, fmaf(ab.y, sr, bui)); sr = nr; si = ni; }
;             LDS_WAIT(); asm volatile("" ::: "memory");
;         }
;         ((f32x2*)(F.ws + WS_E))[(size_t)it * NST + F.lane] = (f32x2){sr, si};
	v_mfma_f32_32x32x16_bf16 v[16:31], v[92:95], v[48:51], 0
	v_mfma_f32_32x32x16_bf16 v[32:47], v[92:95], v[52:55], 0
	v_mfma_f32_32x32x16_bf16 v[200:215], v[92:95], v[56:59], 0
	v_mfma_f32_32x32x16_bf16 v[216:231], v[92:95], v[60:63], 0
	v_mfma_f32_32x32x16_bf16 v[16:31], v[92:95], v[64:67], v[16:31]
	v_mfma_f32_32x32x16_bf16 v[32:47], v[92:95], v[68:71], v[32:47]
	v_mfma_f32_32x32x16_bf16 v[200:215], v[92:95], v[72:75], v[200:215]
	v_mfma_f32_32x32x16_bf16 v[216:231], v[92:95], v[76:79], v[216:231]
	s_nop 3
	v_permlane32_swap_b32_e32 v112, v128
	v_permlane32_swap_b32_e32 v144, v160
	v_permlane32_swap_b32_e32 v113, v129
	v_permlane32_swap_b32_e32 v145, v161
	v_permlane32_swap_b32_e32 v114, v130
	v_permlane32_swap_b32_e32 v146, v162
	v_permlane32_swap_b32_e32 v115, v131
	v_permlane32_swap_b32_e32 v147, v163
	v_pk_fma_f32 v[112:113], v[10:11], v[14:15], v[112:113] op_sel_hi:[0,1,1]
	v_pk_fma_f32 v[144:145], v[8:9], v[12:13], v[144:145] op_sel:[1,0,0]
	v_permlane32_swap_b32_e32 v116, v132
	v_pk_fma_f32 v[12:13], v[8:9], v[12:13], v[112:113] op_sel_hi:[0,1,1]
	v_pk_fma_f32 v[14:15], v[8:9], v[14:15], v[144:145] op_sel_hi:[0,1,1]
	v_permlane32_swap_b32_e32 v148, v164
	v_pk_fma_f32 v[114:115], v[10:11], v[14:15], v[114:115] op_sel_hi:[0,1,1]
	v_pk_fma_f32 v[146:147], v[8:9], v[12:13], v[146:147] op_sel:[1,0,0]
	v_permlane32_swap_b32_e32 v117, v133
	v_pk_fma_f32 v[12:13], v[8:9], v[12:13], v[114:115] op_sel_hi:[0,1,1]
	v_pk_fma_f32 v[14:15], v[8:9], v[14:15], v[146:147] op_sel_hi:[0,1,1]
	v_permlane32_swap_b32_e32 v149, v165
	v_pk_fma_f32 v[128:129], v[10:11], v[14:15], v[128:129] op_sel_hi:[0,1,1]
	v_pk_fma_f32 v[160:161], v[8:9], v[12:13], v[160:161] op_sel:[1,0,0]
	v_permlane32_swap_b32_e32 v118, v134
	v_pk_fma_f32 v[12:13], v[8:9], v[12:13], v[128:129] op_sel_hi:[0,1,1]
	v_pk_fma_f32 v[14:15], v[8:9], v[14:15], v[160:161] op_sel_hi:[0,1,1]
	v_permlane32_swap_b32_e32 v150, v166
	v_pk_fma_f32 v[130:131], v[10:11], v[14:15], v[130:131] op_sel_hi:[0,1,1]
	v_pk_fma_f32 v[162:163], v[8:9], v[12:13], v[162:163] op_sel:[1,0,0]
	v_permlane32_swap_b32_e32 v119, v135
	v_pk_fma_f32 v[12:13], v[8:9], v[12:13], v[130:131] op_sel_hi:[0,1,1]
	v_pk_fma_f32 v[14:15], v[8:9], v[14:15], v[162:163] op_sel_hi:[0,1,1]
	v_permlane32_swap_b32_e32 v151, v167
	v_pk_fma_f32 v[116:117], v[10:11], v[14:15], v[116:117] op_sel_hi:[0,1,1]
	v_pk_fma_f32 v[148:149], v[8:9], v[12:13], v[148:149] op_sel:[1,0,0]
	v_permlane32_swap_b32_e32 v120, v136
	v_pk_fma_f32 v[12:13], v[8:9], v[12:13], v[116:117] op_sel_hi:[0,1,1]
	v_pk_fma_f32 v[14:15], v[8:9], v[14:15], v[148:149] op_sel_hi:[0,1,1]
	v_permlane32_swap_b32_e32 v152, v168
	v_pk_fma_f32 v[118:119], v[10:11], v[14:15], v[118:119] op_sel_hi:[0,1,1]
	v_pk_fma_f32 v[150:151], v[8:9], v[12:13], v[150:151] op_sel:[1,0,0]
	v_permlane32_swap_b32_e32 v121, v137
	v_pk_fma_f32 v[12:13], v[8:9], v[12:13], v[118:119] op_sel_hi:[0,1,1]
	v_pk_fma_f32 v[14:15], v[8:9], v[14:15], v[150:151] op_sel_hi:[0,1,1]
	v_permlane32_swap_b32_e32 v153, v169
	v_pk_fma_f32 v[132:133], v[10:11], v[14:15], v[132:133] op_sel_hi:[0,1,1]
	v_pk_fma_f32 v[164:165], v[8:9], v[12:13], v[164:165] op_sel:[1,0,0]
	v_permlane32_swap_b32_e32 v122, v138
	v_pk_fma_f32 v[12:13], v[8:9], v[12:13], v[132:133] op_sel_hi:[0,1,1]
	v_pk_fma_f32 v[14:15], v[8:9], v[14:15], v[164:165] op_sel_hi:[0,1,1]
	v_permlane32_swap_b32_e32 v154, v170
	v_pk_fma_f32 v[134:135], v[10:11], v[14:15], v[134:135] op_sel_hi:[0,1,1]
	v_pk_fma_f32 v[166:167], v[8:9], v[12:13], v[166:167] op_sel:[1,0,0]
	v_permlane32_swap_b32_e32 v123, v139
	v_pk_fma_f32 v[12:13], v[8:9], v[12:13], v[134:135] op_sel_hi:[0,1,1]
	v_pk_fma_f32 v[14:15], v[8:9], v[14:15], v[166:167] op_sel_hi:[0,1,1]
	v_permlane32_swap_b32_e32 v155, v171
	v_pk_fma_f32 v[120:121], v[10:11], v[14:15], v[120:121] op_sel_hi:[0,1,1]
	v_pk_fma_f32 v[152:153], v[8:9], v[12:13], v[152:153] op_sel:[1,0,0]
	v_permlane32_swap_b32_e32 v124, v140
	v_pk_fma_f32 v[12:13], v[8:9], v[12:13], v[120:121] op_sel_hi:[0,1,1]
	v_pk_fma_f32 v[14:15], v[8:9], v[14:15], v[152:153] op_sel_hi:[0,1,1]
	v_permlane32_swap_b32_e32 v156, v172
	v_pk_fma_f32 v[122:123], v[10:11], v[14:15], v[122:123] op_sel_hi:[0,1,1]
	v_pk_fma_f32 v[154:155], v[8:9], v[12:13], v[154:155] op_sel:[1,0,0]
	v_permlane32_swap_b32_e32 v125, v141
	v_pk_fma_f32 v[12:13], v[8:9], v[12:13], v[122:123] op_sel_hi:[0,1,1]
	v_pk_fma_f32 v[14:15], v[8:9], v[14:15], v[154:155] op_sel_hi:[0,1,1]
	v_permlane32_swap_b32_e32 v157, v173
	v_pk_fma_f32 v[136:137], v[10:11], v[14:15], v[136:137] op_sel_hi:[0,1,1]
	v_pk_fma_f32 v[168:169], v[8:9], v[12:13], v[168:169] op_sel:[1,0,0]
	v_permlane32_swap_b32_e32 v126, v142
	v_pk_fma_f32 v[12:13], v[8:9], v[12:13], v[136:137] op_sel_hi:[0,1,1]
	v_pk_fma_f32 v[14:15], v[8:9], v[14:15], v[168:169] op_sel_hi:[0,1,1]
	v_permlane32_swap_b32_e32 v158, v174
	v_pk_fma_f32 v[138:139], v[10:11], v[14:15], v[138:139] op_sel_hi:[0,1,1]
	v_pk_fma_f32 v[170:171], v[8:9], v[12:13], v[170:171] op_sel:[1,0,0]
	v_permlane32_swap_b32_e32 v127, v143
	v_pk_fma_f32 v[12:13], v[8:9], v[12:13], v[138:139] op_sel_hi:[0,1,1]
	v_pk_fma_f32 v[14:15], v[8:9], v[14:15], v[170:171] op_sel_hi:[0,1,1]
	v_permlane32_swap_b32_e32 v159, v175
	v_pk_fma_f32 v[124:125], v[10:11], v[14:15], v[124:125] op_sel_hi:[0,1,1]
	v_pk_fma_f32 v[156:157], v[8:9], v[12:13], v[156:157] op_sel:[1,0,0]
	s_nop 0
	v_pk_fma_f32 v[12:13], v[8:9], v[12:13], v[124:125] op_sel_hi:[0,1,1]
	v_pk_fma_f32 v[14:15], v[8:9], v[14:15], v[156:157] op_sel_hi:[0,1,1]
	s_nop 0
	v_pk_fma_f32 v[126:127], v[10:11], v[14:15], v[126:127] op_sel_hi:[0,1,1]
	v_pk_fma_f32 v[158:159], v[8:9], v[12:13], v[158:159] op_sel:[1,0,0]
	s_nop 0
	v_pk_fma_f32 v[12:13], v[8:9], v[12:13], v[126:127] op_sel_hi:[0,1,1]
	v_pk_fma_f32 v[14:15], v[8:9], v[14:15], v[158:159] op_sel_hi:[0,1,1]
	s_nop 0
	v_pk_fma_f32 v[140:141], v[10:11], v[14:15], v[140:141] op_sel_hi:[0,1,1]
	v_pk_fma_f32 v[172:173], v[8:9], v[12:13], v[172:173] op_sel:[1,0,0]
	s_nop 0
	v_pk_fma_f32 v[12:13], v[8:9], v[12:13], v[140:141] op_sel_hi:[0,1,1]
	v_pk_fma_f32 v[14:15], v[8:9], v[14:15], v[172:173] op_sel_hi:[0,1,1]
	s_nop 0
	v_pk_fma_f32 v[142:143], v[10:11], v[14:15], v[142:143] op_sel_hi:[0,1,1]
	v_pk_fma_f32 v[174:175], v[8:9], v[12:13], v[174:175] op_sel:[1,0,0]
	s_nop 0
	v_pk_fma_f32 v[12:13], v[8:9], v[12:13], v[142:143] op_sel_hi:[0,1,1]
	v_pk_fma_f32 v[14:15], v[8:9], v[14:15], v[174:175] op_sel_hi:[0,1,1]
	s_nop 0
	s_nop 0
	v_fma_f32 v181, v180, v14, v13
	v_fma_f32 v182, v179, v12, v15
	v_fma_f32 v12, v178, v12, v181
	v_fma_f32 v14, v178, v14, v182
	v_mov_b32_e32 v13, 0
	v_mov_b32_e32 v15, 0
	s_waitcnt vmcnt(5)
; #define LAS __attribute__((address_space(3)))
; #define LDS_WAIT() asm volatile("s_waitcnt lgkmcnt(0)" ::: "memory")
; #define MFMA_PIN(a, b) do { __builtin_amdgcn_sched_barrier(0); asm volatile("" :: "v"(a), "v"(b)); } while (0)
; #define MFMA_SETTLE() do { __builtin_amdgcn_sched_barrier(0); asm volatile("s_nop 15"); __builtin_amdgcn_sched_barrier(0); } while (0)
; __device__ __forceinline__ void ssm_bu16(const bf16x8 afr, const bf16x8 (&bf)[8], LAS float* bubuf, int lane) {
;     LAS float* wp = bubuf + (4 * (lane >> 4)) * BUP + (lane & 15);
;     f32x4 d[8];
; #pragma unroll
;     for (int cb = 0; cb < 8; ++cb) { d[cb] = __builtin_amdgcn_mfma_f32_16x16x32_bf16(afr, bf[cb], (f32x4){0.f, 0.f, 0.f, 0.f}, 0, 0, 0); MFMA_PIN(afr, bf[cb]); }
;     MFMA_SETTLE();
; __device__ __forceinline__ void p5_phase(Frame& F) {
;     ...
;     for (int it = F.gw; it < NB * NCH * NGRP; it += F.ngw) {
;         bf16x8 afr[4];
; #pragma unroll
;         for (int sub = 0; sub < 4; ++sub) afr[sub] = nfr[sub];
;         if (it + F.ngw < NB * NCH * NGRP) { const int bc = (it + F.ngw) >> 7, r0 = (bc / NCH) * SEQ + (bc % NCH) * TCH;
; #pragma unroll
;             for (int sub = 0; sub < 4; ++sub) nfr[sub] = ssm_load_afrag(U, r0 + 16 * sub, g, F.lane); }
;         float sr = 0.f, si = 0.f;
; #pragma unroll
;         for (int sub = 0; sub < 4; ++sub) {
;             ssm_bu16(afr[sub], bf, bubuf, F.lane);
; #pragma unroll
;             for (int tt = 0; tt < 16; ++tt) { const float bur = bubuf[tt * BUP + F.lane], bui = bubuf[tt * BUP + 64 + F.lane];
;                 const float nr = fmaf(ab.x, sr, fmaf(-ab.y, si, bur)), ni = fmaf(ab.x, si, fmaf(ab.y, sr, bui)); sr = nr; si = ni; }
;             LDS_WAIT(); asm volatile("" ::: "memory");
;         }
;         ((f32x2*)(F.ws + WS_E))[(size_t)it * NST + F.lane] = (f32x2){sr, si};
	v_mfma_f32_32x32x16_bf16 v[112:127], v[96:99], v[48:51], 0
	v_mfma_f32_32x32x16_bf16 v[128:143], v[96:99], v[52:55], 0
	v_mfma_f32_32x32x16_bf16 v[144:159], v[96:99], v[56:59], 0
	v_mfma_f32_32x32x16_bf16 v[160:175], v[96:99], v[60:63], 0
	v_mfma_f32_32x32x16_bf16 v[112:127], v[96:99], v[64:67], v[112:127]
	v_mfma_f32_32x32x16_bf16 v[128:143], v[96:99], v[68:71], v[128:143]
	v_mfma_f32_32x32x16_bf16 v[144:159], v[96:99], v[72:75], v[144:159]
	v_mfma_f32_32x32x16_bf16 v[160:175], v[96:99], v[76:79], v[160:175]
	s_nop 3
	v_permlane32_swap_b32_e32 v16, v32
	v_permlane32_swap_b32_e32 v200, v216
	v_permlane32_swap_b32_e32 v17, v33
	v_permlane32_swap_b32_e32 v201, v217
	v_permlane32_swap_b32_e32 v18, v34
	v_permlane32_swap_b32_e32 v202, v218
	v_permlane32_swap_b32_e32 v19, v35
	v_permlane32_swap_b32_e32 v203, v219
	v_pk_fma_f32 v[16:17], v[10:11], v[14:15], v[16:17] op_sel_hi:[0,1,1]
	v_pk_fma_f32 v[200:201], v[8:9], v[12:13], v[200:201] op_sel:[1,0,0]
	v_permlane32_swap_b32_e32 v20, v36
	v_pk_fma_f32 v[12:13], v[8:9], v[12:13], v[16:17] op_sel_hi:[0,1,1]
	v_pk_fma_f32 v[14:15], v[8:9], v[14:15], v[200:201] op_sel_hi:[0,1,1]
	v_permlane32_swap_b32_e32 v204, v220
	v_pk_fma_f32 v[18:19], v[10:11], v[14:15], v[18:19] op_sel_hi:[0,1,1]
	v_pk_fma_f32 v[202:203], v[8:9], v[12:13], v[202:203] op_sel:[1,0,0]
	v_permlane32_swap_b32_e32 v21, v37
	v_pk_fma_f32 v[12:13], v[8:9], v[12:13], v[18:19] op_sel_hi:[0,1,1]
	v_pk_fma_f32 v[14:15], v[8:9], v[14:15], v[202:203] op_sel_hi:[0,1,1]
	v_permlane32_swap_b32_e32 v205, v221
	v_pk_fma_f32 v[32:33], v[10:11], v[14:15], v[32:33] op_sel_hi:[0,1,1]
	v_pk_fma_f32 v[216:217], v[8:9], v[12:13], v[216:217] op_sel:[1,0,0]
	v_permlane32_swap_b32_e32 v22, v38
	v_pk_fma_f32 v[12:13], v[8:9], v[12:13], v[32:33] op_sel_hi:[0,1,1]
	v_pk_fma_f32 v[14:15], v[8:9], v[14:15], v[216:217] op_sel_hi:[0,1,1]
	v_permlane32_swap_b32_e32 v206, v222
	v_pk_fma_f32 v[34:35], v[10:11], v[14:15], v[34:35] op_sel_hi:[0,1,1]
	v_pk_fma_f32 v[218:219], v[8:9], v[12:13], v[218:219] op_sel:[1,0,0]
	v_permlane32_swap_b32_e32 v23, v39
	v_pk_fma_f32 v[12:13], v[8:9], v[12:13], v[34:35] op_sel_hi:[0,1,1]
	v_pk_fma_f32 v[14:15], v[8:9], v[14:15], v[218:219] op_sel_hi:[0,1,1]
	v_permlane32_swap_b32_e32 v207, v223
	v_pk_fma_f32 v[20:21], v[10:11], v[14:15], v[20:21] op_sel_hi:[0,1,1]
	v_pk_fma_f32 v[204:205], v[8:9], v[12:13], v[204:205] op_sel:[1,0,0]
	v_permlane32_swap_b32_e32 v24, v40
	v_pk_fma_f32 v[12:13], v[8:9], v[12:13], v[20:21] op_sel_hi:[0,1,1]
	v_pk_fma_f32 v[14:15], v[8:9], v[14:15], v[204:205] op_sel_hi:[0,1,1]
	v_permlane32_swap_b32_e32 v208, v224
	v_pk_fma_f32 v[22:23], v[10:11], v[14:15], v[22:23] op_sel_hi:[0,1,1]
	v_pk_fma_f32 v[206:207], v[8:9], v[12:13], v[206:207] op_sel:[1,0,0]
	v_permlane32_swap_b32_e32 v25, v41
	v_pk_fma_f32 v[12:13], v[8:9], v[12:13], v[22:23] op_sel_hi:[0,1,1]
	v_pk_fma_f32 v[14:15], v[8:9], v[14:15], v[206:207] op_sel_hi:[0,1,1]
	v_permlane32_swap_b32_e32 v209, v225
	v_pk_fma_f32 v[36:37], v[10:11], v[14:15], v[36:37] op_sel_hi:[0,1,1]
	v_pk_fma_f32 v[220:221], v[8:9], v[12:13], v[220:221] op_sel:[1,0,0]
	v_permlane32_swap_b32_e32 v26, v42
	v_pk_fma_f32 v[12:13], v[8:9], v[12:13], v[36:37] op_sel_hi:[0,1,1]
	v_pk_fma_f32 v[14:15], v[8:9], v[14:15], v[220:221] op_sel_hi:[0,1,1]
	v_permlane32_swap_b32_e32 v210, v226
	v_pk_fma_f32 v[38:39], v[10:11], v[14:15], v[38:39] op_sel_hi:[0,1,1]
	v_pk_fma_f32 v[222:223], v[8:9], v[12:13], v[222:223] op_sel:[1,0,0]
	v_permlane32_swap_b32_e32 v27, v43
	v_pk_fma_f32 v[12:13], v[8:9], v[12:13], v[38:39] op_sel_hi:[0,1,1]
	v_pk_fma_f32 v[14:15], v[8:9], v[14:15], v[222:223] op_sel_hi:[0,1,1]
	v_permlane32_swap_b32_e32 v211, v227
	v_pk_fma_f32 v[24:25], v[10:11], v[14:15], v[24:25] op_sel_hi:[0,1,1]
	v_pk_fma_f32 v[208:209], v[8:9], v[12:13], v[208:209] op_sel:[1,0,0]
	v_permlane32_swap_b32_e32 v28, v44
	v_pk_fma_f32 v[12:13], v[8:9], v[12:13], v[24:25] op_sel_hi:[0,1,1]
	v_pk_fma_f32 v[14:15], v[8:9], v[14:15], v[208:209] op_sel_hi:[0,1,1]
	v_permlane32_swap_b32_e32 v212, v228
	v_pk_fma_f32 v[26:27], v[10:11], v[14:15], v[26:27] op_sel_hi:[0,1,1]
	v_pk_fma_f32 v[210:211], v[8:9], v[12:13], v[210:211] op_sel:[1,0,0]
	v_permlane32_swap_b32_e32 v29, v45
	v_pk_fma_f32 v[12:13], v[8:9], v[12:13], v[26:27] op_sel_hi:[0,1,1]
	v_pk_fma_f32 v[14:15], v[8:9], v[14:15], v[210:211] op_sel_hi:[0,1,1]
	v_permlane32_swap_b32_e32 v213, v229
	v_pk_fma_f32 v[40:41], v[10:11], v[14:15], v[40:41] op_sel_hi:[0,1,1]
	v_pk_fma_f32 v[224:225], v[8:9], v[12:13], v[224:225] op_sel:[1,0,0]
	v_permlane32_swap_b32_e32 v30, v46
	v_pk_fma_f32 v[12:13], v[8:9], v[12:13], v[40:41] op_sel_hi:[0,1,1]
	v_pk_fma_f32 v[14:15], v[8:9], v[14:15], v[224:225] op_sel_hi:[0,1,1]
	v_permlane32_swap_b32_e32 v214, v230
	v_pk_fma_f32 v[42:43], v[10:11], v[14:15], v[42:43] op_sel_hi:[0,1,1]
	v_pk_fma_f32 v[226:227], v[8:9], v[12:13], v[226:227] op_sel:[1,0,0]
	v_permlane32_swap_b32_e32 v31, v47
	v_pk_fma_f32 v[12:13], v[8:9], v[12:13], v[42:43] op_sel_hi:[0,1,1]
	v_pk_fma_f32 v[14:15], v[8:9], v[14:15], v[226:227] op_sel_hi:[0,1,1]
	v_permlane32_swap_b32_e32 v215, v231
	v_pk_fma_f32 v[28:29], v[10:11], v[14:15], v[28:29] op_sel_hi:[0,1,1]
	v_pk_fma_f32 v[212:213], v[8:9], v[12:13], v[212:213] op_sel:[1,0,0]
	s_nop 0
	v_pk_fma_f32 v[12:13], v[8:9], v[12:13], v[28:29] op_sel_hi:[0,1,1]
	v_pk_fma_f32 v[14:15], v[8:9], v[14:15], v[212:213] op_sel_hi:[0,1,1]
	s_nop 0
	v_pk_fma_f32 v[30:31], v[10:11], v[14:15], v[30:31] op_sel_hi:[0,1,1]
	v_pk_fma_f32 v[214:215], v[8:9], v[12:13], v[214:215] op_sel:[1,0,0]
	s_nop 0
	v_pk_fma_f32 v[12:13], v[8:9], v[12:13], v[30:31] op_sel_hi:[0,1,1]
	v_pk_fma_f32 v[14:15], v[8:9], v[14:15], v[214:215] op_sel_hi:[0,1,1]
	s_nop 0
	v_pk_fma_f32 v[44:45], v[10:11], v[14:15], v[44:45] op_sel_hi:[0,1,1]
	v_pk_fma_f32 v[228:229], v[8:9], v[12:13], v[228:229] op_sel:[1,0,0]
	s_nop 0
	v_pk_fma_f32 v[12:13], v[8:9], v[12:13], v[44:45] op_sel_hi:[0,1,1]
	v_pk_fma_f32 v[14:15], v[8:9], v[14:15], v[228:229] op_sel_hi:[0,1,1]
	s_nop 0
	v_pk_fma_f32 v[46:47], v[10:11], v[14:15], v[46:47] op_sel_hi:[0,1,1]
	v_pk_fma_f32 v[230:231], v[8:9], v[12:13], v[230:231] op_sel:[1,0,0]
	s_nop 0
	v_pk_fma_f32 v[12:13], v[8:9], v[12:13], v[46:47] op_sel_hi:[0,1,1]
	v_pk_fma_f32 v[14:15], v[8:9], v[14:15], v[230:231] op_sel_hi:[0,1,1]
	s_nop 0
	s_nop 0
	v_fma_f32 v181, v180, v14, v13
	v_fma_f32 v182, v179, v12, v15
	v_fma_f32 v12, v178, v12, v181
	v_fma_f32 v14, v178, v14, v182
	v_mov_b32_e32 v13, 0
	v_mov_b32_e32 v15, 0
	v_mov_b32_e32 v182, v12
	v_mov_b32_e32 v183, v14
	global_store_dwordx2 v7, v[182:183], s[48:49]
	s_add_u32 s48, s48, 0x100000
	s_addc_u32 s49, s49, 0
	v_mov_b32_e32 v12, 0
	v_mov_b32_e32 v13, 0
	v_mov_b32_e32 v14, 0
	v_mov_b32_e32 v15, 0
	s_waitcnt vmcnt(5)
; #define LAS __attribute__((address_space(3)))
; #define LDS_WAIT() asm volatile("s_waitcnt lgkmcnt(0)" ::: "memory")
; #define MFMA_PIN(a, b) do { __builtin_amdgcn_sched_barrier(0); asm volatile("" :: "v"(a), "v"(b)); } while (0)
; #define MFMA_SETTLE() do { __builtin_amdgcn_sched_barrier(0); asm volatile("s_nop 15"); __builtin_amdgcn_sched_barrier(0); } while (0)
; __device__ __forceinline__ void ssm_bu16(const bf16x8 afr, const bf16x8 (&bf)[8], LAS float* bubuf, int lane) {
;     LAS float* wp = bubuf + (4 * (lane >> 4)) * BUP + (lane & 15);
;     f32x4 d[8];
; #pragma unroll
;     for (int cb = 0; cb < 8; ++cb) { d[cb] = __builtin_amdgcn_mfma_f32_16x16x32_bf16(afr, bf[cb], (f32x4){0.f, 0.f, 0.f, 0.f}, 0, 0, 0); MFMA_PIN(afr, bf[cb]); }
;     MFMA_SETTLE();
; __device__ __forceinline__ void p5_phase(Frame& F) {
;     ...
;     for (int it = F.gw; it < NB * NCH * NGRP; it += F.ngw) {
;         bf16x8 afr[4];
; #pragma unroll
;         for (int sub = 0; sub < 4; ++sub) afr[sub] = nfr[sub];
;         if (it + F.ngw < NB * NCH * NGRP) { const int bc = (it + F.ngw) >> 7, r0 = (bc / NCH) * SEQ + (bc % NCH) * TCH;
; #pragma unroll
;             for (int sub = 0; sub < 4; ++sub) nfr[sub] = ssm_load_afrag(U, r0 + 16 * sub, g, F.lane); }
;         float sr = 0.f, si = 0.f;
; #pragma unroll
;         for (int sub = 0; sub < 4; ++sub) {
;             ssm_bu16(afr[sub], bf, bubuf, F.lane);
; #pragma unroll
;             for (int tt = 0; tt < 16; ++tt) { const float bur = bubuf[tt * BUP + F.lane], bui = bubuf[tt * BUP + 64 + F.lane];
;                 const float nr = fmaf(ab.x, sr, fmaf(-ab.y, si, bur)), ni = fmaf(ab.x, si, fmaf(ab.y, sr, bui)); sr = nr; si = ni; }
;             LDS_WAIT(); asm volatile("" ::: "memory");
;         }
;         ((f32x2*)(F.ws + WS_E))[(size_t)it * NST + F.lane] = (f32x2){sr, si};
	v_mfma_f32_32x32x16_bf16 v[16:31], v[100:103], v[48:51], 0
	v_mfma_f32_32x32x16_bf16 v[32:47], v[100:103], v[52:55], 0
	v_mfma_f32_32x32x16_bf16 v[200:215], v[100:103], v[56:59], 0
	v_mfma_f32_32x32x16_bf16 v[216:231], v[100:103], v[60:63], 0
	v_mfma_f32_32x32x16_bf16 v[16:31], v[100:103], v[64:67], v[16:31]
	v_mfma_f32_32x32x16_bf16 v[32:47], v[100:103], v[68:71], v[32:47]
	v_mfma_f32_32x32x16_bf16 v[200:215], v[100:103], v[72:75], v[200:215]
	v_mfma_f32_32x32x16_bf16 v[216:231], v[100:103], v[76:79], v[216:231]
	s_nop 3
	v_permlane32_swap_b32_e32 v112, v128
	v_permlane32_swap_b32_e32 v144, v160
	v_permlane32_swap_b32_e32 v113, v129
	v_permlane32_swap_b32_e32 v145, v161
	v_permlane32_swap_b32_e32 v114, v130
	v_permlane32_swap_b32_e32 v146, v162
	v_permlane32_swap_b32_e32 v115, v131
	v_permlane32_swap_b32_e32 v147, v163
	v_pk_fma_f32 v[112:113], v[10:11], v[14:15], v[112:113] op_sel_hi:[0,1,1]
	v_pk_fma_f32 v[144:145], v[8:9], v[12:13], v[144:145] op_sel:[1,0,0]
	v_permlane32_swap_b32_e32 v116, v132
	v_pk_fma_f32 v[12:13], v[8:9], v[12:13], v[112:113] op_sel_hi:[0,1,1]
	v_pk_fma_f32 v[14:15], v[8:9], v[14:15], v[144:145] op_sel_hi:[0,1,1]
	v_permlane32_swap_b32_e32 v148, v164
	v_pk_fma_f32 v[114:115], v[10:11], v[14:15], v[114:115] op_sel_hi:[0,1,1]
	v_pk_fma_f32 v[146:147], v[8:9], v[12:13], v[146:147] op_sel:[1,0,0]
	v_permlane32_swap_b32_e32 v117, v133
	v_pk_fma_f32 v[12:13], v[8:9], v[12:13], v[114:115] op_sel_hi:[0,1,1]
	v_pk_fma_f32 v[14:15], v[8:9], v[14:15], v[146:147] op_sel_hi:[0,1,1]
	v_permlane32_swap_b32_e32 v149, v165
	v_pk_fma_f32 v[128:129], v[10:11], v[14:15], v[128:129] op_sel_hi:[0,1,1]
	v_pk_fma_f32 v[160:161], v[8:9], v[12:13], v[160:161] op_sel:[1,0,0]
	v_permlane32_swap_b32_e32 v118, v134
	v_pk_fma_f32 v[12:13], v[8:9], v[12:13], v[128:129] op_sel_hi:[0,1,1]
	v_pk_fma_f32 v[14:15], v[8:9], v[14:15], v[160:161] op_sel_hi:[0,1,1]
	v_permlane32_swap_b32_e32 v150, v166
	v_pk_fma_f32 v[130:131], v[10:11], v[14:15], v[130:131] op_sel_hi:[0,1,1]
	v_pk_fma_f32 v[162:163], v[8:9], v[12:13], v[162:163] op_sel:[1,0,0]
	v_permlane32_swap_b32_e32 v119, v135
	v_pk_fma_f32 v[12:13], v[8:9], v[12:13], v[130:131] op_sel_hi:[0,1,1]
	v_pk_fma_f32 v[14:15], v[8:9], v[14:15], v[162:163] op_sel_hi:[0,1,1]
	v_permlane32_swap_b32_e32 v151, v167
	v_pk_fma_f32 v[116:117], v[10:11], v[14:15], v[116:117] op_sel_hi:[0,1,1]
	v_pk_fma_f32 v[148:149], v[8:9], v[12:13], v[148:149] op_sel:[1,0,0]
	v_permlane32_swap_b32_e32 v120, v136
	v_pk_fma_f32 v[12:13], v[8:9], v[12:13], v[116:117] op_sel_hi:[0,1,1]
	v_pk_fma_f32 v[14:15], v[8:9], v[14:15], v[148:149] op_sel_hi:[0,1,1]
	v_permlane32_swap_b32_e32 v152, v168
	v_pk_fma_f32 v[118:119], v[10:11], v[14:15], v[118:119] op_sel_hi:[0,1,1]
	v_pk_fma_f32 v[150:151], v[8:9], v[12:13], v[150:151] op_sel:[1,0,0]
	v_permlane32_swap_b32_e32 v121, v137
	v_pk_fma_f32 v[12:13], v[8:9], v[12:13], v[118:119] op_sel_hi:[0,1,1]
	v_pk_fma_f32 v[14:15], v[8:9], v[14:15], v[150:151] op_sel_hi:[0,1,1]
	v_permlane32_swap_b32_e32 v153, v169
	v_pk_fma_f32 v[132:133], v[10:11], v[14:15], v[132:133] op_sel_hi:[0,1,1]
	v_pk_fma_f32 v[164:165], v[8:9], v[12:13], v[164:165] op_sel:[1,0,0]
	v_permlane32_swap_b32_e32 v122, v138
	v_pk_fma_f32 v[12:13], v[8:9], v[12:13], v[132:133] op_sel_hi:[0,1,1]
	v_pk_fma_f32 v[14:15], v[8:9], v[14:15], v[164:165] op_sel_hi:[0,1,1]
	v_permlane32_swap_b32_e32 v154, v170
	v_pk_fma_f32 v[134:135], v[10:11], v[14:15], v[134:135] op_sel_hi:[0,1,1]
	v_pk_fma_f32 v[166:167], v[8:9], v[12:13], v[166:167] op_sel:[1,0,0]
	v_permlane32_swap_b32_e32 v123, v139
	v_pk_fma_f32 v[12:13], v[8:9], v[12:13], v[134:135] op_sel_hi:[0,1,1]
	v_pk_fma_f32 v[14:15], v[8:9], v[14:15], v[166:167] op_sel_hi:[0,1,1]
	v_permlane32_swap_b32_e32 v155, v171
	v_pk_fma_f32 v[120:121], v[10:11], v[14:15], v[120:121] op_sel_hi:[0,1,1]
	v_pk_fma_f32 v[152:153], v[8:9], v[12:13], v[152:153] op_sel:[1,0,0]
	v_permlane32_swap_b32_e32 v124, v140
	v_pk_fma_f32 v[12:13], v[8:9], v[12:13], v[120:121] op_sel_hi:[0,1,1]
	v_pk_fma_f32 v[14:15], v[8:9], v[14:15], v[152:153] op_sel_hi:[0,1,1]
	v_permlane32_swap_b32_e32 v156, v172
	v_pk_fma_f32 v[122:123], v[10:11], v[14:15], v[122:123] op_sel_hi:[0,1,1]
	v_pk_fma_f32 v[154:155], v[8:9], v[12:13], v[154:155] op_sel:[1,0,0]
	v_permlane32_swap_b32_e32 v125, v141
	v_pk_fma_f32 v[12:13], v[8:9], v[12:13], v[122:123] op_sel_hi:[0,1,1]
	v_pk_fma_f32 v[14:15], v[8:9], v[14:15], v[154:155] op_sel_hi:[0,1,1]
	v_permlane32_swap_b32_e32 v157, v173
	v_pk_fma_f32 v[136:137], v[10:11], v[14:15], v[136:137] op_sel_hi:[0,1,1]
	v_pk_fma_f32 v[168:169], v[8:9], v[12:13], v[168:169] op_sel:[1,0,0]
	v_permlane32_swap_b32_e32 v126, v142
	v_pk_fma_f32 v[12:13], v[8:9], v[12:13], v[136:137] op_sel_hi:[0,1,1]
	v_pk_fma_f32 v[14:15], v[8:9], v[14:15], v[168:169] op_sel_hi:[0,1,1]
	v_permlane32_swap_b32_e32 v158, v174
	v_pk_fma_f32 v[138:139], v[10:11], v[14:15], v[138:139] op_sel_hi:[0,1,1]
	v_pk_fma_f32 v[170:171], v[8:9], v[12:13], v[170:171] op_sel:[1,0,0]
	v_permlane32_swap_b32_e32 v127, v143
	v_pk_fma_f32 v[12:13], v[8:9], v[12:13], v[138:139] op_sel_hi:[0,1,1]
	v_pk_fma_f32 v[14:15], v[8:9], v[14:15], v[170:171] op_sel_hi:[0,1,1]
	v_permlane32_swap_b32_e32 v159, v175
	v_pk_fma_f32 v[124:125], v[10:11], v[14:15], v[124:125] op_sel_hi:[0,1,1]
	v_pk_fma_f32 v[156:157], v[8:9], v[12:13], v[156:157] op_sel:[1,0,0]
	s_nop 0
	v_pk_fma_f32 v[12:13], v[8:9], v[12:13], v[124:125] op_sel_hi:[0,1,1]
	v_pk_fma_f32 v[14:15], v[8:9], v[14:15], v[156:157] op_sel_hi:[0,1,1]
	s_nop 0
	v_pk_fma_f32 v[126:127], v[10:11], v[14:15], v[126:127] op_sel_hi:[0,1,1]
	v_pk_fma_f32 v[158:159], v[8:9], v[12:13], v[158:159] op_sel:[1,0,0]
	s_nop 0
	v_pk_fma_f32 v[12:13], v[8:9], v[12:13], v[126:127] op_sel_hi:[0,1,1]
	v_pk_fma_f32 v[14:15], v[8:9], v[14:15], v[158:159] op_sel_hi:[0,1,1]
	s_nop 0
	v_pk_fma_f32 v[140:141], v[10:11], v[14:15], v[140:141] op_sel_hi:[0,1,1]
	v_pk_fma_f32 v[172:173], v[8:9], v[12:13], v[172:173] op_sel:[1,0,0]
	s_nop 0
	v_pk_fma_f32 v[12:13], v[8:9], v[12:13], v[140:141] op_sel_hi:[0,1,1]
	v_pk_fma_f32 v[14:15], v[8:9], v[14:15], v[172:173] op_sel_hi:[0,1,1]
	s_nop 0
	v_pk_fma_f32 v[142:143], v[10:11], v[14:15], v[142:143] op_sel_hi:[0,1,1]
	v_pk_fma_f32 v[174:175], v[8:9], v[12:13], v[174:175] op_sel:[1,0,0]
	s_nop 0
	v_pk_fma_f32 v[12:13], v[8:9], v[12:13], v[142:143] op_sel_hi:[0,1,1]
	v_pk_fma_f32 v[14:15], v[8:9], v[14:15], v[174:175] op_sel_hi:[0,1,1]
	s_nop 0
	s_nop 0
	v_fma_f32 v181, v180, v14, v13
	v_fma_f32 v182, v179, v12, v15
	v_fma_f32 v12, v178, v12, v181
	v_fma_f32 v14, v178, v14, v182
	v_mov_b32_e32 v13, 0
	v_mov_b32_e32 v15, 0
	s_waitcnt vmcnt(3)
; #define LAS __attribute__((address_space(3)))
; #define LDS_WAIT() asm volatile("s_waitcnt lgkmcnt(0)" ::: "memory")
; #define MFMA_PIN(a, b) do { __builtin_amdgcn_sched_barrier(0); asm volatile("" :: "v"(a), "v"(b)); } while (0)
; #define MFMA_SETTLE() do { __builtin_amdgcn_sched_barrier(0); asm volatile("s_nop 15"); __builtin_amdgcn_sched_barrier(0); } while (0)
; __device__ __forceinline__ void ssm_bu16(const bf16x8 afr, const bf16x8 (&bf)[8], LAS float* bubuf, int lane) {
;     LAS float* wp = bubuf + (4 * (lane >> 4)) * BUP + (lane & 15);
;     f32x4 d[8];
; #pragma unroll
;     for (int cb = 0; cb < 8; ++cb) { d[cb] = __builtin_amdgcn_mfma_f32_16x16x32_bf16(afr, bf[cb], (f32x4){0.f, 0.f, 0.f, 0.f}, 0, 0, 0); MFMA_PIN(afr, bf[cb]); }
;     MFMA_SETTLE();
; __device__ __forceinline__ void p5_phase(Frame& F) {
;     ...
;     for (int it = F.gw; it < NB * NCH * NGRP; it += F.ngw) {
;         bf16x8 afr[4];
; #pragma unroll
;         for (int sub = 0; sub < 4; ++sub) afr[sub] = nfr[sub];
;         if (it + F.ngw < NB * NCH * NGRP) { const int bc = (it + F.ngw) >> 7, r0 = (bc / NCH) * SEQ + (bc % NCH) * TCH;
; #pragma unroll
;             for (int sub = 0; sub < 4; ++sub) nfr[sub] = ssm_load_afrag(U, r0 + 16 * sub, g, F.lane); }
;         float sr = 0.f, si = 0.f;
; #pragma unroll
;         for (int sub = 0; sub < 4; ++sub) {
;             ssm_bu16(afr[sub], bf, bubuf, F.lane);
; #pragma unroll
;             for (int tt = 0; tt < 16; ++tt) { const float bur = bubuf[tt * BUP + F.lane], bui = bubuf[tt * BUP + 64 + F.lane];
;                 const float nr = fmaf(ab.x, sr, fmaf(-ab.y, si, bur)), ni = fmaf(ab.x, si, fmaf(ab.y, sr, bui)); sr = nr; si = ni; }
;             LDS_WAIT(); asm volatile("" ::: "memory");
;         }
;         ((f32x2*)(F.ws + WS_E))[(size_t)it * NST + F.lane] = (f32x2){sr, si};
	v_mfma_f32_32x32x16_bf16 v[112:127], v[104:107], v[48:51], 0
	v_mfma_f32_32x32x16_bf16 v[128:143], v[104:107], v[52:55], 0
	v_mfma_f32_32x32x16_bf16 v[144:159], v[104:107], v[56:59], 0
	v_mfma_f32_32x32x16_bf16 v[160:175], v[104:107], v[60:63], 0
	v_mfma_f32_32x32x16_bf16 v[112:127], v[104:107], v[64:67], v[112:127]
	v_mfma_f32_32x32x16_bf16 v[128:143], v[104:107], v[68:71], v[128:143]
	v_mfma_f32_32x32x16_bf16 v[144:159], v[104:107], v[72:75], v[144:159]
	v_mfma_f32_32x32x16_bf16 v[160:175], v[104:107], v[76:79], v[160:175]
	s_nop 3
	v_permlane32_swap_b32_e32 v16, v32
	v_permlane32_swap_b32_e32 v200, v216
	v_permlane32_swap_b32_e32 v17, v33
	v_permlane32_swap_b32_e32 v201, v217
	v_permlane32_swap_b32_e32 v18, v34
	v_permlane32_swap_b32_e32 v202, v218
	v_permlane32_swap_b32_e32 v19, v35
	v_permlane32_swap_b32_e32 v203, v219
	v_pk_fma_f32 v[16:17], v[10:11], v[14:15], v[16:17] op_sel_hi:[0,1,1]
	v_pk_fma_f32 v[200:201], v[8:9], v[12:13], v[200:201] op_sel:[1,0,0]
	v_permlane32_swap_b32_e32 v20, v36
	v_pk_fma_f32 v[12:13], v[8:9], v[12:13], v[16:17] op_sel_hi:[0,1,1]
	v_pk_fma_f32 v[14:15], v[8:9], v[14:15], v[200:201] op_sel_hi:[0,1,1]
	v_permlane32_swap_b32_e32 v204, v220
	v_pk_fma_f32 v[18:19], v[10:11], v[14:15], v[18:19] op_sel_hi:[0,1,1]
	v_pk_fma_f32 v[202:203], v[8:9], v[12:13], v[202:203] op_sel:[1,0,0]
	v_permlane32_swap_b32_e32 v21, v37
	v_pk_fma_f32 v[12:13], v[8:9], v[12:13], v[18:19] op_sel_hi:[0,1,1]
	v_pk_fma_f32 v[14:15], v[8:9], v[14:15], v[202:203] op_sel_hi:[0,1,1]
	v_permlane32_swap_b32_e32 v205, v221
	v_pk_fma_f32 v[32:33], v[10:11], v[14:15], v[32:33] op_sel_hi:[0,1,1]
	v_pk_fma_f32 v[216:217], v[8:9], v[12:13], v[216:217] op_sel:[1,0,0]
	v_permlane32_swap_b32_e32 v22, v38
	v_pk_fma_f32 v[12:13], v[8:9], v[12:13], v[32:33] op_sel_hi:[0,1,1]
	v_pk_fma_f32 v[14:15], v[8:9], v[14:15], v[216:217] op_sel_hi:[0,1,1]
	v_permlane32_swap_b32_e32 v206, v222
	v_pk_fma_f32 v[34:35], v[10:11], v[14:15], v[34:35] op_sel_hi:[0,1,1]
	v_pk_fma_f32 v[218:219], v[8:9], v[12:13], v[218:219] op_sel:[1,0,0]
	v_permlane32_swap_b32_e32 v23, v39
	v_pk_fma_f32 v[12:13], v[8:9], v[12:13], v[34:35] op_sel_hi:[0,1,1]
	v_pk_fma_f32 v[14:15], v[8:9], v[14:15], v[218:219] op_sel_hi:[0,1,1]
	v_permlane32_swap_b32_e32 v207, v223
	v_pk_fma_f32 v[20:21], v[10:11], v[14:15], v[20:21] op_sel_hi:[0,1,1]
	v_pk_fma_f32 v[204:205], v[8:9], v[12:13], v[204:205] op_sel:[1,0,0]
	v_permlane32_swap_b32_e32 v24, v40
	v_pk_fma_f32 v[12:13], v[8:9], v[12:13], v[20:21] op_sel_hi:[0,1,1]
	v_pk_fma_f32 v[14:15], v[8:9], v[14:15], v[204:205] op_sel_hi:[0,1,1]
	v_permlane32_swap_b32_e32 v208, v224
	v_pk_fma_f32 v[22:23], v[10:11], v[14:15], v[22:23] op_sel_hi:[0,1,1]
	v_pk_fma_f32 v[206:207], v[8:9], v[12:13], v[206:207] op_sel:[1,0,0]
	v_permlane32_swap_b32_e32 v25, v41
	v_pk_fma_f32 v[12:13], v[8:9], v[12:13], v[22:23] op_sel_hi:[0,1,1]
	v_pk_fma_f32 v[14:15], v[8:9], v[14:15], v[206:207] op_sel_hi:[0,1,1]
	v_permlane32_swap_b32_e32 v209, v225
	v_pk_fma_f32 v[36:37], v[10:11], v[14:15], v[36:37] op_sel_hi:[0,1,1]
	v_pk_fma_f32 v[220:221], v[8:9], v[12:13], v[220:221] op_sel:[1,0,0]
	v_permlane32_swap_b32_e32 v26, v42
	v_pk_fma_f32 v[12:13], v[8:9], v[12:13], v[36:37] op_sel_hi:[0,1,1]
	v_pk_fma_f32 v[14:15], v[8:9], v[14:15], v[220:221] op_sel_hi:[0,1,1]
	v_permlane32_swap_b32_e32 v210, v226
	v_pk_fma_f32 v[38:39], v[10:11], v[14:15], v[38:39] op_sel_hi:[0,1,1]
	v_pk_fma_f32 v[222:223], v[8:9], v[12:13], v[222:223] op_sel:[1,0,0]
	v_permlane32_swap_b32_e32 v27, v43
	v_pk_fma_f32 v[12:13], v[8:9], v[12:13], v[38:39] op_sel_hi:[0,1,1]
	v_pk_fma_f32 v[14:15], v[8:9], v[14:15], v[222:223] op_sel_hi:[0,1,1]
	v_permlane32_swap_b32_e32 v211, v227
	v_pk_fma_f32 v[24:25], v[10:11], v[14:15], v[24:25] op_sel_hi:[0,1,1]
	v_pk_fma_f32 v[208:209], v[8:9], v[12:13], v[208:209] op_sel:[1,0,0]
	v_permlane32_swap_b32_e32 v28, v44
	v_pk_fma_f32 v[12:13], v[8:9], v[12:13], v[24:25] op_sel_hi:[0,1,1]
	v_pk_fma_f32 v[14:15], v[8:9], v[14:15], v[208:209] op_sel_hi:[0,1,1]
	v_permlane32_swap_b32_e32 v212, v228
	v_pk_fma_f32 v[26:27], v[10:11], v[14:15], v[26:27] op_sel_hi:[0,1,1]
	v_pk_fma_f32 v[210:211], v[8:9], v[12:13], v[210:211] op_sel:[1,0,0]
	v_permlane32_swap_b32_e32 v29, v45
	v_pk_fma_f32 v[12:13], v[8:9], v[12:13], v[26:27] op_sel_hi:[0,1,1]
	v_pk_fma_f32 v[14:15], v[8:9], v[14:15], v[210:211] op_sel_hi:[0,1,1]
	v_permlane32_swap_b32_e32 v213, v229
	v_pk_fma_f32 v[40:41], v[10:11], v[14:15], v[40:41] op_sel_hi:[0,1,1]
	v_pk_fma_f32 v[224:225], v[8:9], v[12:13], v[224:225] op_sel:[1,0,0]
	v_permlane32_swap_b32_e32 v30, v46
	v_pk_fma_f32 v[12:13], v[8:9], v[12:13], v[40:41] op_sel_hi:[0,1,1]
	v_pk_fma_f32 v[14:15], v[8:9], v[14:15], v[224:225] op_sel_hi:[0,1,1]
	v_permlane32_swap_b32_e32 v214, v230
	v_pk_fma_f32 v[42:43], v[10:11], v[14:15], v[42:43] op_sel_hi:[0,1,1]
	v_pk_fma_f32 v[226:227], v[8:9], v[12:13], v[226:227] op_sel:[1,0,0]
	v_permlane32_swap_b32_e32 v31, v47
	v_pk_fma_f32 v[12:13], v[8:9], v[12:13], v[42:43] op_sel_hi:[0,1,1]
	v_pk_fma_f32 v[14:15], v[8:9], v[14:15], v[226:227] op_sel_hi:[0,1,1]
	v_permlane32_swap_b32_e32 v215, v231
	v_pk_fma_f32 v[28:29], v[10:11], v[14:15], v[28:29] op_sel_hi:[0,1,1]
	v_pk_fma_f32 v[212:213], v[8:9], v[12:13], v[212:213] op_sel:[1,0,0]
	s_nop 0
	v_pk_fma_f32 v[12:13], v[8:9], v[12:13], v[28:29] op_sel_hi:[0,1,1]
	v_pk_fma_f32 v[14:15], v[8:9], v[14:15], v[212:213] op_sel_hi:[0,1,1]
	s_nop 0
	v_pk_fma_f32 v[30:31], v[10:11], v[14:15], v[30:31] op_sel_hi:[0,1,1]
	v_pk_fma_f32 v[214:215], v[8:9], v[12:13], v[214:215] op_sel:[1,0,0]
	s_nop 0
	v_pk_fma_f32 v[12:13], v[8:9], v[12:13], v[30:31] op_sel_hi:[0,1,1]
	v_pk_fma_f32 v[14:15], v[8:9], v[14:15], v[214:215] op_sel_hi:[0,1,1]
	s_nop 0
	v_pk_fma_f32 v[44:45], v[10:11], v[14:15], v[44:45] op_sel_hi:[0,1,1]
	v_pk_fma_f32 v[228:229], v[8:9], v[12:13], v[228:229] op_sel:[1,0,0]
	s_nop 0
	v_pk_fma_f32 v[12:13], v[8:9], v[12:13], v[44:45] op_sel_hi:[0,1,1]
	v_pk_fma_f32 v[14:15], v[8:9], v[14:15], v[228:229] op_sel_hi:[0,1,1]
	s_nop 0
	v_pk_fma_f32 v[46:47], v[10:11], v[14:15], v[46:47] op_sel_hi:[0,1,1]
	v_pk_fma_f32 v[230:231], v[8:9], v[12:13], v[230:231] op_sel:[1,0,0]
	s_nop 0
	v_pk_fma_f32 v[12:13], v[8:9], v[12:13], v[46:47] op_sel_hi:[0,1,1]
	v_pk_fma_f32 v[14:15], v[8:9], v[14:15], v[230:231] op_sel_hi:[0,1,1]
	s_nop 0
	s_nop 0
	v_fma_f32 v181, v180, v14, v13
	v_fma_f32 v182, v179, v12, v15
	v_fma_f32 v12, v178, v12, v181
	v_fma_f32 v14, v178, v14, v182
	v_mov_b32_e32 v13, 0
	v_mov_b32_e32 v15, 0
	v_mov_b32_e32 v182, v12
	v_mov_b32_e32 v183, v14
	global_store_dwordx2 v7, v[182:183], s[48:49]
	s_add_u32 s48, s48, 0x100000
	s_addc_u32 s49, s49, 0
	v_mov_b32_e32 v12, 0
	v_mov_b32_e32 v13, 0
	v_mov_b32_e32 v14, 0
	v_mov_b32_e32 v15, 0
	s_waitcnt vmcnt(3)
; #define LDS_WAIT() asm volatile("s_waitcnt lgkmcnt(0)" ::: "memory")
; #define MFMA_PIN(a, b) do { __builtin_amdgcn_sched_barrier(0); asm volatile("" :: "v"(a), "v"(b)); } while (0)
; #define MFMA_SETTLE() do { __builtin_amdgcn_sched_barrier(0); asm volatile("s_nop 15"); __builtin_amdgcn_sched_barrier(0); } while (0)
; __device__ __forceinline__ void ssm_bu16(const bf16x8 afr, const bf16x8 (&bf)[8], LAS float* bubuf, int lane) {
;     ...
;     for (int cb = 0; cb < 8; ++cb) { d[cb] = __builtin_amdgcn_mfma_f32_16x16x32_bf16(afr, bf[cb], (f32x4){0.f, 0.f, 0.f, 0.f}, 0, 0, 0); MFMA_PIN(afr, bf[cb]); }
;     MFMA_SETTLE();
; __device__ __forceinline__ void p5_phase(Frame& F) {
;     ...
;         for (int sub = 0; sub < 4; ++sub) {
;             ssm_bu16(afr[sub], bf, bubuf, F.lane);
; #pragma unroll
;             for (int tt = 0; tt < 16; ++tt) { const float bur = bubuf[tt * BUP + F.lane], bui = bubuf[tt * BUP + 64 + F.lane];
;                 const float nr = fmaf(ab.x, sr, fmaf(-ab.y, si, bur)), ni = fmaf(ab.x, si, fmaf(ab.y, sr, bui)); sr = nr; si = ni; }
;             LDS_WAIT(); asm volatile("" ::: "memory");
;         }
	v_mfma_f32_32x32x16_bf16 v[16:31], v[108:111], v[48:51], 0
	v_mfma_f32_32x32x16_bf16 v[32:47], v[108:111], v[52:55], 0
	v_mfma_f32_32x32x16_bf16 v[200:215], v[108:111], v[56:59], 0
	v_mfma_f32_32x32x16_bf16 v[216:231], v[108:111], v[60:63], 0
	v_mfma_f32_32x32x16_bf16 v[16:31], v[108:111], v[64:67], v[16:31]
	v_mfma_f32_32x32x16_bf16 v[32:47], v[108:111], v[68:71], v[32:47]
	v_mfma_f32_32x32x16_bf16 v[200:215], v[108:111], v[72:75], v[200:215]
	v_mfma_f32_32x32x16_bf16 v[216:231], v[108:111], v[76:79], v[216:231]
	s_nop 3
	v_permlane32_swap_b32_e32 v112, v128
	v_permlane32_swap_b32_e32 v144, v160
	v_permlane32_swap_b32_e32 v113, v129
	v_permlane32_swap_b32_e32 v145, v161
	v_permlane32_swap_b32_e32 v114, v130
	v_permlane32_swap_b32_e32 v146, v162
	v_permlane32_swap_b32_e32 v115, v131
	v_permlane32_swap_b32_e32 v147, v163
	v_pk_fma_f32 v[112:113], v[10:11], v[14:15], v[112:113] op_sel_hi:[0,1,1]
	v_pk_fma_f32 v[144:145], v[8:9], v[12:13], v[144:145] op_sel:[1,0,0]
	v_permlane32_swap_b32_e32 v116, v132
	v_pk_fma_f32 v[12:13], v[8:9], v[12:13], v[112:113] op_sel_hi:[0,1,1]
	v_pk_fma_f32 v[14:15], v[8:9], v[14:15], v[144:145] op_sel_hi:[0,1,1]
	v_permlane32_swap_b32_e32 v148, v164
	v_pk_fma_f32 v[114:115], v[10:11], v[14:15], v[114:115] op_sel_hi:[0,1,1]
	v_pk_fma_f32 v[146:147], v[8:9], v[12:13], v[146:147] op_sel:[1,0,0]
	v_permlane32_swap_b32_e32 v117, v133
	v_pk_fma_f32 v[12:13], v[8:9], v[12:13], v[114:115] op_sel_hi:[0,1,1]
	v_pk_fma_f32 v[14:15], v[8:9], v[14:15], v[146:147] op_sel_hi:[0,1,1]
	v_permlane32_swap_b32_e32 v149, v165
	v_pk_fma_f32 v[128:129], v[10:11], v[14:15], v[128:129] op_sel_hi:[0,1,1]
	v_pk_fma_f32 v[160:161], v[8:9], v[12:13], v[160:161] op_sel:[1,0,0]
	v_permlane32_swap_b32_e32 v118, v134
	v_pk_fma_f32 v[12:13], v[8:9], v[12:13], v[128:129] op_sel_hi:[0,1,1]
	v_pk_fma_f32 v[14:15], v[8:9], v[14:15], v[160:161] op_sel_hi:[0,1,1]
	v_permlane32_swap_b32_e32 v150, v166
	v_pk_fma_f32 v[130:131], v[10:11], v[14:15], v[130:131] op_sel_hi:[0,1,1]
	v_pk_fma_f32 v[162:163], v[8:9], v[12:13], v[162:163] op_sel:[1,0,0]
	v_permlane32_swap_b32_e32 v119, v135
	v_pk_fma_f32 v[12:13], v[8:9], v[12:13], v[130:131] op_sel_hi:[0,1,1]
	v_pk_fma_f32 v[14:15], v[8:9], v[14:15], v[162:163] op_sel_hi:[0,1,1]
	v_permlane32_swap_b32_e32 v151, v167
	v_pk_fma_f32 v[116:117], v[10:11], v[14:15], v[116:117] op_sel_hi:[0,1,1]
	v_pk_fma_f32 v[148:149], v[8:9], v[12:13], v[148:149] op_sel:[1,0,0]
	v_permlane32_swap_b32_e32 v120, v136
	v_pk_fma_f32 v[12:13], v[8:9], v[12:13], v[116:117] op_sel_hi:[0,1,1]
	v_pk_fma_f32 v[14:15], v[8:9], v[14:15], v[148:149] op_sel_hi:[0,1,1]
	v_permlane32_swap_b32_e32 v152, v168
	v_pk_fma_f32 v[118:119], v[10:11], v[14:15], v[118:119] op_sel_hi:[0,1,1]
	v_pk_fma_f32 v[150:151], v[8:9], v[12:13], v[150:151] op_sel:[1,0,0]
	v_permlane32_swap_b32_e32 v121, v137
	v_pk_fma_f32 v[12:13], v[8:9], v[12:13], v[118:119] op_sel_hi:[0,1,1]
	v_pk_fma_f32 v[14:15], v[8:9], v[14:15], v[150:151] op_sel_hi:[0,1,1]
	v_permlane32_swap_b32_e32 v153, v169
	v_pk_fma_f32 v[132:133], v[10:11], v[14:15], v[132:133] op_sel_hi:[0,1,1]
	v_pk_fma_f32 v[164:165], v[8:9], v[12:13], v[164:165] op_sel:[1,0,0]
	v_permlane32_swap_b32_e32 v122, v138
	v_pk_fma_f32 v[12:13], v[8:9], v[12:13], v[132:133] op_sel_hi:[0,1,1]
	v_pk_fma_f32 v[14:15], v[8:9], v[14:15], v[164:165] op_sel_hi:[0,1,1]
	v_permlane32_swap_b32_e32 v154, v170
	v_pk_fma_f32 v[134:135], v[10:11], v[14:15], v[134:135] op_sel_hi:[0,1,1]
	v_pk_fma_f32 v[166:167], v[8:9], v[12:13], v[166:167] op_sel:[1,0,0]
	v_permlane32_swap_b32_e32 v123, v139
	v_pk_fma_f32 v[12:13], v[8:9], v[12:13], v[134:135] op_sel_hi:[0,1,1]
	v_pk_fma_f32 v[14:15], v[8:9], v[14:15], v[166:167] op_sel_hi:[0,1,1]
	v_permlane32_swap_b32_e32 v155, v171
	v_pk_fma_f32 v[120:121], v[10:11], v[14:15], v[120:121] op_sel_hi:[0,1,1]
	v_pk_fma_f32 v[152:153], v[8:9], v[12:13], v[152:153] op_sel:[1,0,0]
	v_permlane32_swap_b32_e32 v124, v140
	v_pk_fma_f32 v[12:13], v[8:9], v[12:13], v[120:121] op_sel_hi:[0,1,1]
	v_pk_fma_f32 v[14:15], v[8:9], v[14:15], v[152:153] op_sel_hi:[0,1,1]
	v_permlane32_swap_b32_e32 v156, v172
	v_pk_fma_f32 v[122:123], v[10:11], v[14:15], v[122:123] op_sel_hi:[0,1,1]
	v_pk_fma_f32 v[154:155], v[8:9], v[12:13], v[154:155] op_sel:[1,0,0]
	v_permlane32_swap_b32_e32 v125, v141
	v_pk_fma_f32 v[12:13], v[8:9], v[12:13], v[122:123] op_sel_hi:[0,1,1]
	v_pk_fma_f32 v[14:15], v[8:9], v[14:15], v[154:155] op_sel_hi:[0,1,1]
	v_permlane32_swap_b32_e32 v157, v173
	v_pk_fma_f32 v[136:137], v[10:11], v[14:15], v[136:137] op_sel_hi:[0,1,1]
	v_pk_fma_f32 v[168:169], v[8:9], v[12:13], v[168:169] op_sel:[1,0,0]
	v_permlane32_swap_b32_e32 v126, v142
	v_pk_fma_f32 v[12:13], v[8:9], v[12:13], v[136:137] op_sel_hi:[0,1,1]
	v_pk_fma_f32 v[14:15], v[8:9], v[14:15], v[168:169] op_sel_hi:[0,1,1]
	v_permlane32_swap_b32_e32 v158, v174
	v_pk_fma_f32 v[138:139], v[10:11], v[14:15], v[138:139] op_sel_hi:[0,1,1]
	v_pk_fma_f32 v[170:171], v[8:9], v[12:13], v[170:171] op_sel:[1,0,0]
	v_permlane32_swap_b32_e32 v127, v143
	v_pk_fma_f32 v[12:13], v[8:9], v[12:13], v[138:139] op_sel_hi:[0,1,1]
	v_pk_fma_f32 v[14:15], v[8:9], v[14:15], v[170:171] op_sel_hi:[0,1,1]
	v_permlane32_swap_b32_e32 v159, v175
	v_pk_fma_f32 v[124:125], v[10:11], v[14:15], v[124:125] op_sel_hi:[0,1,1]
	v_pk_fma_f32 v[156:157], v[8:9], v[12:13], v[156:157] op_sel:[1,0,0]
	s_nop 0
	v_pk_fma_f32 v[12:13], v[8:9], v[12:13], v[124:125] op_sel_hi:[0,1,1]
	v_pk_fma_f32 v[14:15], v[8:9], v[14:15], v[156:157] op_sel_hi:[0,1,1]
	s_nop 0
	v_pk_fma_f32 v[126:127], v[10:11], v[14:15], v[126:127] op_sel_hi:[0,1,1]
	v_pk_fma_f32 v[158:159], v[8:9], v[12:13], v[158:159] op_sel:[1,0,0]
; #define LDS_WAIT() asm volatile("s_waitcnt lgkmcnt(0)" ::: "memory")
; __device__ __forceinline__ void p5_phase(Frame& F) {
;     ...
;         for (int sub = 0; sub < 4; ++sub) {
;             ssm_bu16(afr[sub], bf, bubuf, F.lane);
; #pragma unroll
;             for (int tt = 0; tt < 16; ++tt) { const float bur = bubuf[tt * BUP + F.lane], bui = bubuf[tt * BUP + 64 + F.lane];
;                 const float nr = fmaf(ab.x, sr, fmaf(-ab.y, si, bur)), ni = fmaf(ab.x, si, fmaf(ab.y, sr, bui)); sr = nr; si = ni; }
;             LDS_WAIT(); asm volatile("" ::: "memory");
;         }
	s_nop 0
	v_pk_fma_f32 v[12:13], v[8:9], v[12:13], v[126:127] op_sel_hi:[0,1,1]
	v_pk_fma_f32 v[14:15], v[8:9], v[14:15], v[158:159] op_sel_hi:[0,1,1]
	s_nop 0
	v_pk_fma_f32 v[140:141], v[10:11], v[14:15], v[140:141] op_sel_hi:[0,1,1]
	v_pk_fma_f32 v[172:173], v[8:9], v[12:13], v[172:173] op_sel:[1,0,0]
	s_nop 0
	v_pk_fma_f32 v[12:13], v[8:9], v[12:13], v[140:141] op_sel_hi:[0,1,1]
	v_pk_fma_f32 v[14:15], v[8:9], v[14:15], v[172:173] op_sel_hi:[0,1,1]
	s_nop 0
	v_pk_fma_f32 v[142:143], v[10:11], v[14:15], v[142:143] op_sel_hi:[0,1,1]
	v_pk_fma_f32 v[174:175], v[8:9], v[12:13], v[174:175] op_sel:[1,0,0]
	s_nop 0
	v_pk_fma_f32 v[12:13], v[8:9], v[12:13], v[142:143] op_sel_hi:[0,1,1]
	v_pk_fma_f32 v[14:15], v[8:9], v[14:15], v[174:175] op_sel_hi:[0,1,1]
	s_nop 0
	s_nop 0
	v_fma_f32 v181, v180, v14, v13
	v_fma_f32 v182, v179, v12, v15
	v_fma_f32 v12, v178, v12, v181
	v_fma_f32 v14, v178, v14, v182
	v_mov_b32_e32 v13, 0
	v_mov_b32_e32 v15, 0
	s_nop 15
	s_nop 15
	s_nop 3
	v_permlane32_swap_b32_e32 v16, v32
	v_permlane32_swap_b32_e32 v200, v216
	v_permlane32_swap_b32_e32 v17, v33
	v_permlane32_swap_b32_e32 v201, v217
	v_permlane32_swap_b32_e32 v18, v34
	v_permlane32_swap_b32_e32 v202, v218
	v_permlane32_swap_b32_e32 v19, v35
	v_permlane32_swap_b32_e32 v203, v219
	v_pk_fma_f32 v[16:17], v[10:11], v[14:15], v[16:17] op_sel_hi:[0,1,1]
	v_pk_fma_f32 v[200:201], v[8:9], v[12:13], v[200:201] op_sel:[1,0,0]
	v_permlane32_swap_b32_e32 v20, v36
	v_pk_fma_f32 v[12:13], v[8:9], v[12:13], v[16:17] op_sel_hi:[0,1,1]
	v_pk_fma_f32 v[14:15], v[8:9], v[14:15], v[200:201] op_sel_hi:[0,1,1]
	v_permlane32_swap_b32_e32 v204, v220
	v_pk_fma_f32 v[18:19], v[10:11], v[14:15], v[18:19] op_sel_hi:[0,1,1]
	v_pk_fma_f32 v[202:203], v[8:9], v[12:13], v[202:203] op_sel:[1,0,0]
	v_permlane32_swap_b32_e32 v21, v37
	v_pk_fma_f32 v[12:13], v[8:9], v[12:13], v[18:19] op_sel_hi:[0,1,1]
	v_pk_fma_f32 v[14:15], v[8:9], v[14:15], v[202:203] op_sel_hi:[0,1,1]
	v_permlane32_swap_b32_e32 v205, v221
	v_pk_fma_f32 v[32:33], v[10:11], v[14:15], v[32:33] op_sel_hi:[0,1,1]
	v_pk_fma_f32 v[216:217], v[8:9], v[12:13], v[216:217] op_sel:[1,0,0]
	v_permlane32_swap_b32_e32 v22, v38
	v_pk_fma_f32 v[12:13], v[8:9], v[12:13], v[32:33] op_sel_hi:[0,1,1]
	v_pk_fma_f32 v[14:15], v[8:9], v[14:15], v[216:217] op_sel_hi:[0,1,1]
	v_permlane32_swap_b32_e32 v206, v222
	v_pk_fma_f32 v[34:35], v[10:11], v[14:15], v[34:35] op_sel_hi:[0,1,1]
	v_pk_fma_f32 v[218:219], v[8:9], v[12:13], v[218:219] op_sel:[1,0,0]
	v_permlane32_swap_b32_e32 v23, v39
	v_pk_fma_f32 v[12:13], v[8:9], v[12:13], v[34:35] op_sel_hi:[0,1,1]
	v_pk_fma_f32 v[14:15], v[8:9], v[14:15], v[218:219] op_sel_hi:[0,1,1]
	v_permlane32_swap_b32_e32 v207, v223
	v_pk_fma_f32 v[20:21], v[10:11], v[14:15], v[20:21] op_sel_hi:[0,1,1]
	v_pk_fma_f32 v[204:205], v[8:9], v[12:13], v[204:205] op_sel:[1,0,0]
	v_permlane32_swap_b32_e32 v24, v40
	v_pk_fma_f32 v[12:13], v[8:9], v[12:13], v[20:21] op_sel_hi:[0,1,1]
	v_pk_fma_f32 v[14:15], v[8:9], v[14:15], v[204:205] op_sel_hi:[0,1,1]
	v_permlane32_swap_b32_e32 v208, v224
	v_pk_fma_f32 v[22:23], v[10:11], v[14:15], v[22:23] op_sel_hi:[0,1,1]
	v_pk_fma_f32 v[206:207], v[8:9], v[12:13], v[206:207] op_sel:[1,0,0]
	v_permlane32_swap_b32_e32 v25, v41
	v_pk_fma_f32 v[12:13], v[8:9], v[12:13], v[22:23] op_sel_hi:[0,1,1]
	v_pk_fma_f32 v[14:15], v[8:9], v[14:15], v[206:207] op_sel_hi:[0,1,1]
	v_permlane32_swap_b32_e32 v209, v225
	v_pk_fma_f32 v[36:37], v[10:11], v[14:15], v[36:37] op_sel_hi:[0,1,1]
	v_pk_fma_f32 v[220:221], v[8:9], v[12:13], v[220:221] op_sel:[1,0,0]
; #define LDS_WAIT() asm volatile("s_waitcnt lgkmcnt(0)" ::: "memory")
; __device__ __forceinline__ void p5_phase(Frame& F) {
;     ...
;         for (int sub = 0; sub < 4; ++sub) {
;             ssm_bu16(afr[sub], bf, bubuf, F.lane);
; #pragma unroll
;             for (int tt = 0; tt < 16; ++tt) { const float bur = bubuf[tt * BUP + F.lane], bui = bubuf[tt * BUP + 64 + F.lane];
;                 const float nr = fmaf(ab.x, sr, fmaf(-ab.y, si, bur)), ni = fmaf(ab.x, si, fmaf(ab.y, sr, bui)); sr = nr; si = ni; }
;             LDS_WAIT(); asm volatile("" ::: "memory");
;         }
;         ((f32x2*)(F.ws + WS_E))[(size_t)it * NST + F.lane] = (f32x2){sr, si};
	v_permlane32_swap_b32_e32 v26, v42
	v_pk_fma_f32 v[12:13], v[8:9], v[12:13], v[36:37] op_sel_hi:[0,1,1]
	v_pk_fma_f32 v[14:15], v[8:9], v[14:15], v[220:221] op_sel_hi:[0,1,1]
	v_permlane32_swap_b32_e32 v210, v226
	v_pk_fma_f32 v[38:39], v[10:11], v[14:15], v[38:39] op_sel_hi:[0,1,1]
	v_pk_fma_f32 v[222:223], v[8:9], v[12:13], v[222:223] op_sel:[1,0,0]
	v_permlane32_swap_b32_e32 v27, v43
	v_pk_fma_f32 v[12:13], v[8:9], v[12:13], v[38:39] op_sel_hi:[0,1,1]
	v_pk_fma_f32 v[14:15], v[8:9], v[14:15], v[222:223] op_sel_hi:[0,1,1]
	v_permlane32_swap_b32_e32 v211, v227
	v_pk_fma_f32 v[24:25], v[10:11], v[14:15], v[24:25] op_sel_hi:[0,1,1]
	v_pk_fma_f32 v[208:209], v[8:9], v[12:13], v[208:209] op_sel:[1,0,0]
	v_permlane32_swap_b32_e32 v28, v44
	v_pk_fma_f32 v[12:13], v[8:9], v[12:13], v[24:25] op_sel_hi:[0,1,1]
	v_pk_fma_f32 v[14:15], v[8:9], v[14:15], v[208:209] op_sel_hi:[0,1,1]
	v_permlane32_swap_b32_e32 v212, v228
	v_pk_fma_f32 v[26:27], v[10:11], v[14:15], v[26:27] op_sel_hi:[0,1,1]
	v_pk_fma_f32 v[210:211], v[8:9], v[12:13], v[210:211] op_sel:[1,0,0]
	v_permlane32_swap_b32_e32 v29, v45
	v_pk_fma_f32 v[12:13], v[8:9], v[12:13], v[26:27] op_sel_hi:[0,1,1]
	v_pk_fma_f32 v[14:15], v[8:9], v[14:15], v[210:211] op_sel_hi:[0,1,1]
	v_permlane32_swap_b32_e32 v213, v229
	v_pk_fma_f32 v[40:41], v[10:11], v[14:15], v[40:41] op_sel_hi:[0,1,1]
	v_pk_fma_f32 v[224:225], v[8:9], v[12:13], v[224:225] op_sel:[1,0,0]
	v_permlane32_swap_b32_e32 v30, v46
	v_pk_fma_f32 v[12:13], v[8:9], v[12:13], v[40:41] op_sel_hi:[0,1,1]
	v_pk_fma_f32 v[14:15], v[8:9], v[14:15], v[224:225] op_sel_hi:[0,1,1]
	v_permlane32_swap_b32_e32 v214, v230
	v_pk_fma_f32 v[42:43], v[10:11], v[14:15], v[42:43] op_sel_hi:[0,1,1]
	v_pk_fma_f32 v[226:227], v[8:9], v[12:13], v[226:227] op_sel:[1,0,0]
	v_permlane32_swap_b32_e32 v31, v47
	v_pk_fma_f32 v[12:13], v[8:9], v[12:13], v[42:43] op_sel_hi:[0,1,1]
	v_pk_fma_f32 v[14:15], v[8:9], v[14:15], v[226:227] op_sel_hi:[0,1,1]
	v_permlane32_swap_b32_e32 v215, v231
	v_pk_fma_f32 v[28:29], v[10:11], v[14:15], v[28:29] op_sel_hi:[0,1,1]
	v_pk_fma_f32 v[212:213], v[8:9], v[12:13], v[212:213] op_sel:[1,0,0]
	s_nop 0
	v_pk_fma_f32 v[12:13], v[8:9], v[12:13], v[28:29] op_sel_hi:[0,1,1]
	v_pk_fma_f32 v[14:15], v[8:9], v[14:15], v[212:213] op_sel_hi:[0,1,1]
	s_nop 0
	v_pk_fma_f32 v[30:31], v[10:11], v[14:15], v[30:31] op_sel_hi:[0,1,1]
	v_pk_fma_f32 v[214:215], v[8:9], v[12:13], v[214:215] op_sel:[1,0,0]
	s_nop 0
	v_pk_fma_f32 v[12:13], v[8:9], v[12:13], v[30:31] op_sel_hi:[0,1,1]
	v_pk_fma_f32 v[14:15], v[8:9], v[14:15], v[214:215] op_sel_hi:[0,1,1]
	s_nop 0
	v_pk_fma_f32 v[44:45], v[10:11], v[14:15], v[44:45] op_sel_hi:[0,1,1]
	v_pk_fma_f32 v[228:229], v[8:9], v[12:13], v[228:229] op_sel:[1,0,0]
	s_nop 0
	v_pk_fma_f32 v[12:13], v[8:9], v[12:13], v[44:45] op_sel_hi:[0,1,1]
	v_pk_fma_f32 v[14:15], v[8:9], v[14:15], v[228:229] op_sel_hi:[0,1,1]
	s_nop 0
	v_pk_fma_f32 v[46:47], v[10:11], v[14:15], v[46:47] op_sel_hi:[0,1,1]
	v_pk_fma_f32 v[230:231], v[8:9], v[12:13], v[230:231] op_sel:[1,0,0]
	s_nop 0
	v_pk_fma_f32 v[12:13], v[8:9], v[12:13], v[46:47] op_sel_hi:[0,1,1]
	v_pk_fma_f32 v[14:15], v[8:9], v[14:15], v[230:231] op_sel_hi:[0,1,1]
	s_nop 0
	s_nop 0
	v_fma_f32 v181, v180, v14, v13
	v_fma_f32 v182, v179, v12, v15
	v_fma_f32 v12, v178, v12, v181
	v_fma_f32 v14, v178, v14, v182
	v_mov_b32_e32 v13, 0
	v_mov_b32_e32 v15, 0
	v_mov_b32_e32 v182, v12
	v_mov_b32_e32 v183, v14
	global_store_dwordx2 v7, v[182:183], s[48:49]
	s_add_u32 s48, s48, 0x100000
	s_addc_u32 s49, s49, 0
